# K-loops without the per-segment s_setprio flips (A/B against the previous version)
# speedup vs baseline: 1.0140x; 1.0038x over previous
.LBB0_122:
	v_mov_b64_e32 v[0:1], 0x180
	s_ashr_i32 s15, s14, 31
	v_cmp_lt_i64_e32 vcc, s[16:17], v[0:1]
	s_lshl_b64 s[16:17], s[14:15], 19
	s_add_u32 s16, s30, s16
	s_addc_u32 s17, s31, s17
	s_and_b64 s[18:19], vcc, exec
	s_cselect_b32 s7, s17, s21
	s_cselect_b32 s9, s16, s20
	s_ashr_i32 s13, s12, 31
	s_lshl_b64 s[18:19], s[12:13], 19
	s_add_u32 s18, s34, s18
	s_addc_u32 s19, s35, s19
	s_and_b64 s[22:23], vcc, exec
	s_cselect_b32 s13, s19, s3
	s_cselect_b32 s15, s18, s2
	s_add_u32 s20, s20, 0x40080
	s_addc_u32 s21, s21, 0
	s_add_u32 s50, s2, 0x100
	s_addc_u32 s51, s3, 0
	s_mov_b32 s52, -2
	s_add_u32 s2, s20, 0xfffc0080
	s_addc_u32 s3, s21, -1
	s_add_i32 s53, 0, 0x10000
	v_add_u32_e32 v36, s53, v164
	ds_read_b128 v[24:27], v36
	ds_read_b128 v[28:31], v36 offset:1024
	ds_read_b128 v[32:35], v36 offset:2048
	ds_read_b128 v[36:39], v36 offset:3072
	s_cmp_eq_u32 s52, 12
	s_cselect_b32 s23, s7, s3
	s_cselect_b32 s22, s9, s2
	s_cselect_b32 s3, s13, s51
	s_cselect_b32 s2, s15, s50
	v_lshl_add_u64 v[166:167], s[20:21], 0, v[150:151]
	s_add_i32 m0, s37, 0xc000
	ds_read_b128 v[154:157], v165
	ds_read_b128 v[158:161], v165 offset:1024
	ds_read_b128 v[180:183], v165 offset:2048
	ds_read_b128 v[184:187], v165 offset:3072
	ds_read_b128 v[188:191], v165 offset:4096
	ds_read_b128 v[192:195], v165 offset:5120
	ds_read_b128 v[196:199], v165 offset:6144
	ds_read_b128 v[200:203], v165 offset:7168
	global_load_lds_dwordx4 v[166:167], off
	s_add_i32 m0, s37, 0xe000
	v_lshl_add_u64 v[166:167], s[20:21], 0, v[152:153]
	global_load_lds_dwordx4 v[166:167], off
	s_waitcnt lgkmcnt(8)
	s_barrier
	s_waitcnt lgkmcnt(0)
	v_mfma_f32_16x16x32_bf16 v[140:143], v[24:27], v[154:157], 0
	v_mfma_f32_16x16x32_bf16 v[136:139], v[32:35], v[154:157], 0
	v_mfma_f32_16x16x32_bf16 v[124:127], v[24:27], v[180:183], 0
	v_mfma_f32_16x16x32_bf16 v[120:123], v[32:35], v[180:183], 0
	v_mfma_f32_16x16x32_bf16 v[108:111], v[24:27], v[188:191], 0
	v_mfma_f32_16x16x32_bf16 v[104:107], v[32:35], v[188:191], 0
	v_mfma_f32_16x16x32_bf16 v[92:95], v[24:27], v[196:199], 0
	v_mfma_f32_16x16x32_bf16 v[88:91], v[32:35], v[196:199], 0
	v_mfma_f32_16x16x32_bf16 v[140:143], v[28:31], v[158:161], v[140:143]
	v_mfma_f32_16x16x32_bf16 v[136:139], v[36:39], v[158:161], v[136:139]
	v_mfma_f32_16x16x32_bf16 v[124:127], v[28:31], v[184:187], v[124:127]
	v_mfma_f32_16x16x32_bf16 v[120:123], v[36:39], v[184:187], v[120:123]
	v_mfma_f32_16x16x32_bf16 v[108:111], v[28:31], v[192:195], v[108:111]
	v_mfma_f32_16x16x32_bf16 v[104:107], v[36:39], v[192:195], v[104:107]
	v_mfma_f32_16x16x32_bf16 v[92:95], v[28:31], v[200:203], v[92:95]
	v_mfma_f32_16x16x32_bf16 v[88:91], v[36:39], v[200:203], v[88:91]
	s_barrier
	s_add_i32 s56, 0, 0x14000
	v_add_u32_e32 v166, s56, v164
	s_add_i32 s53, s53, s36
	ds_read_b128 v[204:207], v166
	ds_read_b128 v[208:211], v166 offset:1024
	ds_read_b128 v[212:215], v166 offset:2048
	ds_read_b128 v[216:219], v166 offset:3072
	v_lshl_add_u64 v[166:167], s[2:3], 0, v[168:169]
	s_mov_b32 m0, s53
	v_lshl_add_u64 v[220:221], s[2:3], 0, v[148:149]
	global_load_lds_dwordx4 v[166:167], off
	s_add_i32 m0, s53, 0x2000
	s_nop 0
	global_load_lds_dwordx4 v[220:221], off
	s_barrier
	s_waitcnt lgkmcnt(0)
	v_mfma_f32_16x16x32_bf16 v[132:135], v[204:207], v[154:157], 0
	v_mfma_f32_16x16x32_bf16 v[128:131], v[212:215], v[154:157], 0
	v_mfma_f32_16x16x32_bf16 v[116:119], v[204:207], v[180:183], 0
	v_mfma_f32_16x16x32_bf16 v[112:115], v[212:215], v[180:183], 0
	v_mfma_f32_16x16x32_bf16 v[100:103], v[204:207], v[188:191], 0
	v_mfma_f32_16x16x32_bf16 v[96:99], v[212:215], v[188:191], 0
	v_mfma_f32_16x16x32_bf16 v[84:87], v[204:207], v[196:199], 0
	v_mfma_f32_16x16x32_bf16 v[80:83], v[212:215], v[196:199], 0
	v_mfma_f32_16x16x32_bf16 v[132:135], v[208:211], v[158:161], v[132:135]
	v_mfma_f32_16x16x32_bf16 v[128:131], v[216:219], v[158:161], v[128:131]
	v_mfma_f32_16x16x32_bf16 v[116:119], v[208:211], v[184:187], v[116:119]
	v_mfma_f32_16x16x32_bf16 v[112:115], v[216:219], v[184:187], v[112:115]
	v_mfma_f32_16x16x32_bf16 v[100:103], v[208:211], v[192:195], v[100:103]
	v_mfma_f32_16x16x32_bf16 v[96:99], v[216:219], v[192:195], v[96:99]
	v_mfma_f32_16x16x32_bf16 v[84:87], v[208:211], v[200:203], v[84:87]
	v_mfma_f32_16x16x32_bf16 v[80:83], v[216:219], v[200:203], v[80:83]
	s_mov_b32 m0, s37
	v_lshl_add_u64 v[222:223], s[22:23], 0, v[144:145]
	s_barrier
	ds_read_b128 v[154:157], v165 offset:16384
	ds_read_b128 v[158:161], v165 offset:17408
	ds_read_b128 v[180:183], v165 offset:18432
	ds_read_b128 v[184:187], v165 offset:19456
	ds_read_b128 v[188:191], v165 offset:20480
	ds_read_b128 v[192:195], v165 offset:21504
	ds_read_b128 v[196:199], v165 offset:22528
	ds_read_b128 v[200:203], v165 offset:23552
	global_load_lds_dwordx4 v[222:223], off
	s_mov_b32 m0, s38
	v_lshl_add_u64 v[236:237], s[22:23], 0, v[146:147]
	global_load_lds_dwordx4 v[236:237], off
	s_barrier
	s_waitcnt lgkmcnt(0)
	v_mfma_f32_16x16x32_bf16 v[76:79], v[24:27], v[154:157], 0
	v_mfma_f32_16x16x32_bf16 v[72:75], v[32:35], v[154:157], 0
	v_mfma_f32_16x16x32_bf16 v[60:63], v[24:27], v[180:183], 0
	v_mfma_f32_16x16x32_bf16 v[56:59], v[32:35], v[180:183], 0
	v_mfma_f32_16x16x32_bf16 v[44:47], v[24:27], v[188:191], 0
	v_mfma_f32_16x16x32_bf16 v[40:43], v[32:35], v[188:191], 0
	v_mfma_f32_16x16x32_bf16 v[12:15], v[24:27], v[196:199], 0
	v_mfma_f32_16x16x32_bf16 v[8:11], v[32:35], v[196:199], 0
	v_mfma_f32_16x16x32_bf16 v[76:79], v[28:31], v[158:161], v[76:79]
	v_mfma_f32_16x16x32_bf16 v[72:75], v[36:39], v[158:161], v[72:75]
	v_mfma_f32_16x16x32_bf16 v[60:63], v[28:31], v[184:187], v[60:63]
	v_mfma_f32_16x16x32_bf16 v[56:59], v[36:39], v[184:187], v[56:59]
	v_mfma_f32_16x16x32_bf16 v[44:47], v[28:31], v[192:195], v[44:47]
	v_mfma_f32_16x16x32_bf16 v[40:43], v[36:39], v[192:195], v[40:43]
	v_mfma_f32_16x16x32_bf16 v[12:15], v[28:31], v[200:203], v[12:15]
	v_mfma_f32_16x16x32_bf16 v[8:11], v[36:39], v[200:203], v[8:11]
	s_barrier
	s_add_u32 s54, s2, 0x40000
	s_addc_u32 s55, s3, 0
	s_add_i32 s53, s56, s36
	s_mov_b32 m0, s53
	v_lshl_add_u64 v[24:25], s[54:55], 0, v[168:169]
	global_load_lds_dwordx4 v[24:25], off
	s_add_i32 m0, s53, 0x2000
	v_lshl_add_u64 v[24:25], s[54:55], 0, v[148:149]
	global_load_lds_dwordx4 v[24:25], off
	s_waitcnt vmcnt(6)
	s_barrier
	v_mfma_f32_16x16x32_bf16 v[20:23], v[204:207], v[188:191], 0
	v_mfma_f32_16x16x32_bf16 v[16:19], v[212:215], v[188:191], 0
	v_mfma_f32_16x16x32_bf16 v[4:7], v[204:207], v[196:199], 0
	v_mfma_f32_16x16x32_bf16 v[0:3], v[212:215], v[196:199], 0
	v_mfma_f32_16x16x32_bf16 v[24:27], v[204:207], v[154:157], 0
	v_mfma_f32_16x16x32_bf16 v[28:31], v[212:215], v[154:157], 0
	v_mfma_f32_16x16x32_bf16 v[32:35], v[204:207], v[180:183], 0
	v_mfma_f32_16x16x32_bf16 v[36:39], v[212:215], v[180:183], 0
	v_mfma_f32_16x16x32_bf16 v[20:23], v[208:211], v[192:195], v[20:23]
	v_mfma_f32_16x16x32_bf16 v[16:19], v[216:219], v[192:195], v[16:19]
	v_mfma_f32_16x16x32_bf16 v[4:7], v[208:211], v[200:203], v[4:7]
	v_mfma_f32_16x16x32_bf16 v[0:3], v[216:219], v[200:203], v[0:3]
	v_mfma_f32_16x16x32_bf16 v[24:27], v[208:211], v[158:161], v[24:27]
	v_mfma_f32_16x16x32_bf16 v[28:31], v[216:219], v[158:161], v[28:31]
	v_mfma_f32_16x16x32_bf16 v[32:35], v[208:211], v[184:187], v[32:35]
	v_mfma_f32_16x16x32_bf16 v[36:39], v[216:219], v[184:187], v[36:39]
	s_add_i32 s53, 0, 0x18000
	v_add_u32_e32 v68, s53, v164
	s_barrier
	ds_read_b128 v[48:51], v68
	ds_read_b128 v[52:55], v68 offset:1024
	ds_read_b128 v[64:67], v68 offset:2048
	ds_read_b128 v[68:71], v68 offset:3072
	s_add_u32 s22, s22, 0x40000
	s_addc_u32 s23, s23, 0
	s_mov_b32 m0, s39
	v_lshl_add_u64 v[204:205], s[22:23], 0, v[144:145]
	ds_read_b128 v[154:157], v165 offset:32768
	ds_read_b128 v[158:161], v165 offset:33792
	ds_read_b128 v[180:183], v165 offset:34816
	ds_read_b128 v[184:187], v165 offset:35840
	ds_read_b128 v[188:191], v165 offset:36864
	ds_read_b128 v[192:195], v165 offset:37888
	ds_read_b128 v[196:199], v165 offset:38912
	ds_read_b128 v[200:203], v165 offset:39936
	global_load_lds_dwordx4 v[204:205], off
	s_mov_b32 m0, s40
	v_lshl_add_u64 v[204:205], s[22:23], 0, v[146:147]
	global_load_lds_dwordx4 v[204:205], off
	s_waitcnt lgkmcnt(8)
	s_barrier
	s_waitcnt lgkmcnt(0)
	v_mfma_f32_16x16x32_bf16 v[140:143], v[48:51], v[154:157], v[140:143]
	v_mfma_f32_16x16x32_bf16 v[136:139], v[64:67], v[154:157], v[136:139]
	v_mfma_f32_16x16x32_bf16 v[124:127], v[48:51], v[180:183], v[124:127]
	v_mfma_f32_16x16x32_bf16 v[120:123], v[64:67], v[180:183], v[120:123]
	v_mfma_f32_16x16x32_bf16 v[108:111], v[48:51], v[188:191], v[108:111]
	v_mfma_f32_16x16x32_bf16 v[104:107], v[64:67], v[188:191], v[104:107]
	v_mfma_f32_16x16x32_bf16 v[92:95], v[48:51], v[196:199], v[92:95]
	v_mfma_f32_16x16x32_bf16 v[88:91], v[64:67], v[196:199], v[88:91]
	v_mfma_f32_16x16x32_bf16 v[140:143], v[52:55], v[158:161], v[140:143]
	v_mfma_f32_16x16x32_bf16 v[136:139], v[68:71], v[158:161], v[136:139]
	v_mfma_f32_16x16x32_bf16 v[124:127], v[52:55], v[184:187], v[124:127]
	v_mfma_f32_16x16x32_bf16 v[120:123], v[68:71], v[184:187], v[120:123]
	v_mfma_f32_16x16x32_bf16 v[108:111], v[52:55], v[192:195], v[108:111]
	v_mfma_f32_16x16x32_bf16 v[104:107], v[68:71], v[192:195], v[104:107]
	v_mfma_f32_16x16x32_bf16 v[92:95], v[52:55], v[200:203], v[92:95]
	v_mfma_f32_16x16x32_bf16 v[88:91], v[68:71], v[200:203], v[88:91]
	s_barrier
	s_add_i32 s22, 0, 0x1c000
	s_add_i32 s23, s53, s36
	v_add_u32_e32 v216, s22, v164
	v_lshl_add_u64 v[166:167], v[166:167], 0, s[78:79]
	s_mov_b32 m0, s23
	ds_read_b128 v[204:207], v216
	ds_read_b128 v[208:211], v216 offset:1024
	ds_read_b128 v[212:215], v216 offset:2048
	ds_read_b128 v[216:219], v216 offset:3072
	global_load_lds_dwordx4 v[166:167], off
	s_add_i32 m0, s23, 0x2000
	v_lshl_add_u64 v[166:167], v[220:221], 0, s[78:79]
	global_load_lds_dwordx4 v[166:167], off
	s_barrier
	s_waitcnt lgkmcnt(0)
	v_mfma_f32_16x16x32_bf16 v[132:135], v[204:207], v[154:157], v[132:135]
	v_mfma_f32_16x16x32_bf16 v[128:131], v[212:215], v[154:157], v[128:131]
	v_mfma_f32_16x16x32_bf16 v[116:119], v[204:207], v[180:183], v[116:119]
	v_mfma_f32_16x16x32_bf16 v[112:115], v[212:215], v[180:183], v[112:115]
	v_mfma_f32_16x16x32_bf16 v[100:103], v[204:207], v[188:191], v[100:103]
	v_mfma_f32_16x16x32_bf16 v[96:99], v[212:215], v[188:191], v[96:99]
	v_mfma_f32_16x16x32_bf16 v[84:87], v[204:207], v[196:199], v[84:87]
	v_mfma_f32_16x16x32_bf16 v[80:83], v[212:215], v[196:199], v[80:83]
	v_mfma_f32_16x16x32_bf16 v[132:135], v[208:211], v[158:161], v[132:135]
	v_mfma_f32_16x16x32_bf16 v[128:131], v[216:219], v[158:161], v[128:131]
	v_mfma_f32_16x16x32_bf16 v[116:119], v[208:211], v[184:187], v[116:119]
	v_mfma_f32_16x16x32_bf16 v[112:115], v[216:219], v[184:187], v[112:115]
	v_mfma_f32_16x16x32_bf16 v[100:103], v[208:211], v[192:195], v[100:103]
	v_mfma_f32_16x16x32_bf16 v[96:99], v[216:219], v[192:195], v[96:99]
	v_mfma_f32_16x16x32_bf16 v[84:87], v[208:211], v[200:203], v[84:87]
	v_mfma_f32_16x16x32_bf16 v[80:83], v[216:219], v[200:203], v[80:83]
	s_mov_b32 m0, s45
	v_lshl_add_u64 v[166:167], v[222:223], 0, s[78:79]
	s_barrier
	ds_read_b128 v[154:157], v165 offset:49152
	ds_read_b128 v[158:161], v165 offset:50176
	ds_read_b128 v[180:183], v165 offset:51200
	ds_read_b128 v[184:187], v165 offset:52224
	ds_read_b128 v[188:191], v165 offset:53248
	ds_read_b128 v[192:195], v165 offset:54272
	ds_read_b128 v[196:199], v165 offset:55296
	ds_read_b128 v[200:203], v165 offset:56320
	global_load_lds_dwordx4 v[166:167], off
	s_mov_b32 m0, s46
	v_lshl_add_u64 v[166:167], v[236:237], 0, s[78:79]
	global_load_lds_dwordx4 v[166:167], off
	s_barrier
	s_waitcnt lgkmcnt(0)
	v_mfma_f32_16x16x32_bf16 v[76:79], v[48:51], v[154:157], v[76:79]
	v_mfma_f32_16x16x32_bf16 v[72:75], v[64:67], v[154:157], v[72:75]
	v_mfma_f32_16x16x32_bf16 v[60:63], v[48:51], v[180:183], v[60:63]
	v_mfma_f32_16x16x32_bf16 v[56:59], v[64:67], v[180:183], v[56:59]
	v_mfma_f32_16x16x32_bf16 v[44:47], v[48:51], v[188:191], v[44:47]
	v_mfma_f32_16x16x32_bf16 v[40:43], v[64:67], v[188:191], v[40:43]
	v_mfma_f32_16x16x32_bf16 v[12:15], v[48:51], v[196:199], v[12:15]
	v_mfma_f32_16x16x32_bf16 v[8:11], v[64:67], v[196:199], v[8:11]
	v_mfma_f32_16x16x32_bf16 v[76:79], v[52:55], v[158:161], v[76:79]
	v_mfma_f32_16x16x32_bf16 v[72:75], v[68:71], v[158:161], v[72:75]
	v_mfma_f32_16x16x32_bf16 v[60:63], v[52:55], v[184:187], v[60:63]
	v_mfma_f32_16x16x32_bf16 v[56:59], v[68:71], v[184:187], v[56:59]
	v_mfma_f32_16x16x32_bf16 v[44:47], v[52:55], v[192:195], v[44:47]
	v_mfma_f32_16x16x32_bf16 v[40:43], v[68:71], v[192:195], v[40:43]
	v_mfma_f32_16x16x32_bf16 v[12:15], v[52:55], v[200:203], v[12:15]
	v_mfma_f32_16x16x32_bf16 v[8:11], v[68:71], v[200:203], v[8:11]
	s_barrier
	s_add_u32 s2, s2, 0x40080
	s_addc_u32 s3, s3, 0
	s_add_i32 s22, s22, s36
	s_mov_b32 m0, s22
	v_lshl_add_u64 v[48:49], s[2:3], 0, v[168:169]
	global_load_lds_dwordx4 v[48:49], off
	s_add_i32 m0, s22, 0x2000
	v_lshl_add_u64 v[48:49], s[2:3], 0, v[148:149]
	global_load_lds_dwordx4 v[48:49], off
	s_waitcnt vmcnt(6)
	s_barrier
	v_mfma_f32_16x16x32_bf16 v[24:27], v[204:207], v[154:157], v[24:27]
	v_mfma_f32_16x16x32_bf16 v[68:71], v[208:211], v[158:161], v[24:27]
	v_mfma_f32_16x16x32_bf16 v[24:27], v[212:215], v[154:157], v[28:31]
	v_mfma_f32_16x16x32_bf16 v[64:67], v[216:219], v[158:161], v[24:27]
	v_mfma_f32_16x16x32_bf16 v[24:27], v[204:207], v[180:183], v[32:35]
	v_mfma_f32_16x16x32_bf16 v[52:55], v[208:211], v[184:187], v[24:27]
	v_mfma_f32_16x16x32_bf16 v[24:27], v[212:215], v[180:183], v[36:39]
	v_mfma_f32_16x16x32_bf16 v[20:23], v[204:207], v[188:191], v[20:23]
	v_mfma_f32_16x16x32_bf16 v[16:19], v[212:215], v[188:191], v[16:19]
	v_mfma_f32_16x16x32_bf16 v[4:7], v[204:207], v[196:199], v[4:7]
	v_mfma_f32_16x16x32_bf16 v[0:3], v[212:215], v[196:199], v[0:3]
	v_mfma_f32_16x16x32_bf16 v[48:51], v[216:219], v[184:187], v[24:27]
	v_mfma_f32_16x16x32_bf16 v[20:23], v[208:211], v[192:195], v[20:23]
	v_mfma_f32_16x16x32_bf16 v[16:19], v[216:219], v[192:195], v[16:19]
	v_mfma_f32_16x16x32_bf16 v[4:7], v[208:211], v[200:203], v[4:7]
	v_mfma_f32_16x16x32_bf16 v[0:3], v[216:219], v[200:203], v[0:3]
	s_add_i32 s52, s52, 2
	s_add_u32 s20, s20, 0x100
	s_addc_u32 s21, s21, 0
	s_add_u32 s50, s50, 0x100
	s_addc_u32 s51, s51, 0
	s_cmp_gt_u32 s52, 13
	s_barrier
.LBB0_123:
	s_add_u32 s2, s20, 0xfffc0080
	s_addc_u32 s3, s21, -1
	s_add_i32 s53, 0, 0x10000
	v_add_u32_e32 v36, s53, v164
	ds_read_b128 v[24:27], v36
	ds_read_b128 v[28:31], v36 offset:1024
	ds_read_b128 v[32:35], v36 offset:2048
	ds_read_b128 v[36:39], v36 offset:3072
	s_cmp_eq_u32 s52, 12
	s_cselect_b32 s23, s7, s3
	s_cselect_b32 s22, s9, s2
	s_cselect_b32 s3, s13, s51
	s_cselect_b32 s2, s15, s50
	v_lshl_add_u64 v[166:167], s[20:21], 0, v[150:151]
	s_add_i32 m0, s37, 0xc000
	ds_read_b128 v[154:157], v165
	ds_read_b128 v[158:161], v165 offset:1024
	ds_read_b128 v[180:183], v165 offset:2048
	ds_read_b128 v[184:187], v165 offset:3072
	ds_read_b128 v[188:191], v165 offset:4096
	ds_read_b128 v[192:195], v165 offset:5120
	ds_read_b128 v[196:199], v165 offset:6144
	ds_read_b128 v[200:203], v165 offset:7168
	global_load_lds_dwordx4 v[166:167], off
	s_add_i32 m0, s37, 0xe000
	v_lshl_add_u64 v[166:167], s[20:21], 0, v[152:153]
	global_load_lds_dwordx4 v[166:167], off
	s_waitcnt lgkmcnt(8)
	s_barrier
	s_waitcnt lgkmcnt(0)
	v_mfma_f32_16x16x32_bf16 v[140:143], v[24:27], v[154:157], v[140:143]
	v_mfma_f32_16x16x32_bf16 v[136:139], v[32:35], v[154:157], v[136:139]
	v_mfma_f32_16x16x32_bf16 v[124:127], v[24:27], v[180:183], v[124:127]
	v_mfma_f32_16x16x32_bf16 v[120:123], v[32:35], v[180:183], v[120:123]
	v_mfma_f32_16x16x32_bf16 v[108:111], v[24:27], v[188:191], v[108:111]
	v_mfma_f32_16x16x32_bf16 v[104:107], v[32:35], v[188:191], v[104:107]
	v_mfma_f32_16x16x32_bf16 v[92:95], v[24:27], v[196:199], v[92:95]
	v_mfma_f32_16x16x32_bf16 v[88:91], v[32:35], v[196:199], v[88:91]
	v_mfma_f32_16x16x32_bf16 v[140:143], v[28:31], v[158:161], v[140:143]
	v_mfma_f32_16x16x32_bf16 v[136:139], v[36:39], v[158:161], v[136:139]
	v_mfma_f32_16x16x32_bf16 v[124:127], v[28:31], v[184:187], v[124:127]
	v_mfma_f32_16x16x32_bf16 v[120:123], v[36:39], v[184:187], v[120:123]
	v_mfma_f32_16x16x32_bf16 v[108:111], v[28:31], v[192:195], v[108:111]
	v_mfma_f32_16x16x32_bf16 v[104:107], v[36:39], v[192:195], v[104:107]
	v_mfma_f32_16x16x32_bf16 v[92:95], v[28:31], v[200:203], v[92:95]
	v_mfma_f32_16x16x32_bf16 v[88:91], v[36:39], v[200:203], v[88:91]
	s_barrier
	s_add_i32 s56, 0, 0x14000
	v_add_u32_e32 v166, s56, v164
	s_add_i32 s53, s53, s36
	ds_read_b128 v[204:207], v166
	ds_read_b128 v[208:211], v166 offset:1024
	ds_read_b128 v[212:215], v166 offset:2048
	ds_read_b128 v[216:219], v166 offset:3072
	v_lshl_add_u64 v[166:167], s[2:3], 0, v[168:169]
	s_mov_b32 m0, s53
	v_lshl_add_u64 v[220:221], s[2:3], 0, v[148:149]
	global_load_lds_dwordx4 v[166:167], off
	s_add_i32 m0, s53, 0x2000
	s_nop 0
	global_load_lds_dwordx4 v[220:221], off
	s_barrier
	s_waitcnt lgkmcnt(0)
	v_mfma_f32_16x16x32_bf16 v[132:135], v[204:207], v[154:157], v[132:135]
	v_mfma_f32_16x16x32_bf16 v[128:131], v[212:215], v[154:157], v[128:131]
	v_mfma_f32_16x16x32_bf16 v[116:119], v[204:207], v[180:183], v[116:119]
	v_mfma_f32_16x16x32_bf16 v[112:115], v[212:215], v[180:183], v[112:115]
	v_mfma_f32_16x16x32_bf16 v[100:103], v[204:207], v[188:191], v[100:103]
	v_mfma_f32_16x16x32_bf16 v[96:99], v[212:215], v[188:191], v[96:99]
	v_mfma_f32_16x16x32_bf16 v[84:87], v[204:207], v[196:199], v[84:87]
	v_mfma_f32_16x16x32_bf16 v[80:83], v[212:215], v[196:199], v[80:83]
	v_mfma_f32_16x16x32_bf16 v[132:135], v[208:211], v[158:161], v[132:135]
	v_mfma_f32_16x16x32_bf16 v[128:131], v[216:219], v[158:161], v[128:131]
	v_mfma_f32_16x16x32_bf16 v[116:119], v[208:211], v[184:187], v[116:119]
	v_mfma_f32_16x16x32_bf16 v[112:115], v[216:219], v[184:187], v[112:115]
	v_mfma_f32_16x16x32_bf16 v[100:103], v[208:211], v[192:195], v[100:103]
	v_mfma_f32_16x16x32_bf16 v[96:99], v[216:219], v[192:195], v[96:99]
	v_mfma_f32_16x16x32_bf16 v[84:87], v[208:211], v[200:203], v[84:87]
	v_mfma_f32_16x16x32_bf16 v[80:83], v[216:219], v[200:203], v[80:83]
	s_mov_b32 m0, s37
	v_lshl_add_u64 v[222:223], s[22:23], 0, v[144:145]
	s_barrier
	ds_read_b128 v[154:157], v165 offset:16384
	ds_read_b128 v[158:161], v165 offset:17408
	ds_read_b128 v[180:183], v165 offset:18432
	ds_read_b128 v[184:187], v165 offset:19456
	ds_read_b128 v[188:191], v165 offset:20480
	ds_read_b128 v[192:195], v165 offset:21504
	ds_read_b128 v[196:199], v165 offset:22528
	ds_read_b128 v[200:203], v165 offset:23552
	global_load_lds_dwordx4 v[222:223], off
	s_mov_b32 m0, s38
	v_lshl_add_u64 v[236:237], s[22:23], 0, v[146:147]
	global_load_lds_dwordx4 v[236:237], off
	s_barrier
	s_waitcnt lgkmcnt(0)
	v_mfma_f32_16x16x32_bf16 v[76:79], v[24:27], v[154:157], v[76:79]
	v_mfma_f32_16x16x32_bf16 v[72:75], v[32:35], v[154:157], v[72:75]
	v_mfma_f32_16x16x32_bf16 v[60:63], v[24:27], v[180:183], v[60:63]
	v_mfma_f32_16x16x32_bf16 v[56:59], v[32:35], v[180:183], v[56:59]
	v_mfma_f32_16x16x32_bf16 v[44:47], v[24:27], v[188:191], v[44:47]
	v_mfma_f32_16x16x32_bf16 v[40:43], v[32:35], v[188:191], v[40:43]
	v_mfma_f32_16x16x32_bf16 v[12:15], v[24:27], v[196:199], v[12:15]
	v_mfma_f32_16x16x32_bf16 v[8:11], v[32:35], v[196:199], v[8:11]
	v_mfma_f32_16x16x32_bf16 v[76:79], v[28:31], v[158:161], v[76:79]
	v_mfma_f32_16x16x32_bf16 v[72:75], v[36:39], v[158:161], v[72:75]
	v_mfma_f32_16x16x32_bf16 v[60:63], v[28:31], v[184:187], v[60:63]
	v_mfma_f32_16x16x32_bf16 v[56:59], v[36:39], v[184:187], v[56:59]
	v_mfma_f32_16x16x32_bf16 v[44:47], v[28:31], v[192:195], v[44:47]
	v_mfma_f32_16x16x32_bf16 v[40:43], v[36:39], v[192:195], v[40:43]
	v_mfma_f32_16x16x32_bf16 v[12:15], v[28:31], v[200:203], v[12:15]
	v_mfma_f32_16x16x32_bf16 v[8:11], v[36:39], v[200:203], v[8:11]
	s_barrier
	s_add_u32 s54, s2, 0x40000
	s_addc_u32 s55, s3, 0
	s_add_i32 s53, s56, s36
	s_mov_b32 m0, s53
	v_lshl_add_u64 v[24:25], s[54:55], 0, v[168:169]
	global_load_lds_dwordx4 v[24:25], off
	s_add_i32 m0, s53, 0x2000
	v_lshl_add_u64 v[24:25], s[54:55], 0, v[148:149]
	global_load_lds_dwordx4 v[24:25], off
	s_waitcnt vmcnt(6)
	s_barrier
	v_mfma_f32_16x16x32_bf16 v[20:23], v[204:207], v[188:191], v[20:23]
	v_mfma_f32_16x16x32_bf16 v[16:19], v[212:215], v[188:191], v[16:19]
	v_mfma_f32_16x16x32_bf16 v[4:7], v[204:207], v[196:199], v[4:7]
	v_mfma_f32_16x16x32_bf16 v[0:3], v[212:215], v[196:199], v[0:3]
	v_mfma_f32_16x16x32_bf16 v[24:27], v[204:207], v[154:157], v[68:71]
	v_mfma_f32_16x16x32_bf16 v[28:31], v[212:215], v[154:157], v[64:67]
	v_mfma_f32_16x16x32_bf16 v[32:35], v[204:207], v[180:183], v[52:55]
	v_mfma_f32_16x16x32_bf16 v[36:39], v[212:215], v[180:183], v[48:51]
	v_mfma_f32_16x16x32_bf16 v[20:23], v[208:211], v[192:195], v[20:23]
	v_mfma_f32_16x16x32_bf16 v[16:19], v[216:219], v[192:195], v[16:19]
	v_mfma_f32_16x16x32_bf16 v[4:7], v[208:211], v[200:203], v[4:7]
	v_mfma_f32_16x16x32_bf16 v[0:3], v[216:219], v[200:203], v[0:3]
	v_mfma_f32_16x16x32_bf16 v[24:27], v[208:211], v[158:161], v[24:27]
	v_mfma_f32_16x16x32_bf16 v[28:31], v[216:219], v[158:161], v[28:31]
	v_mfma_f32_16x16x32_bf16 v[32:35], v[208:211], v[184:187], v[32:35]
	v_mfma_f32_16x16x32_bf16 v[36:39], v[216:219], v[184:187], v[36:39]
	s_add_i32 s53, 0, 0x18000
	v_add_u32_e32 v68, s53, v164
	s_barrier
	ds_read_b128 v[48:51], v68
	ds_read_b128 v[52:55], v68 offset:1024
	ds_read_b128 v[64:67], v68 offset:2048
	ds_read_b128 v[68:71], v68 offset:3072
	s_add_u32 s22, s22, 0x40000
	s_addc_u32 s23, s23, 0
	s_mov_b32 m0, s39
	v_lshl_add_u64 v[204:205], s[22:23], 0, v[144:145]
	ds_read_b128 v[154:157], v165 offset:32768
	ds_read_b128 v[158:161], v165 offset:33792
	ds_read_b128 v[180:183], v165 offset:34816
	ds_read_b128 v[184:187], v165 offset:35840
	ds_read_b128 v[188:191], v165 offset:36864
	ds_read_b128 v[192:195], v165 offset:37888
	ds_read_b128 v[196:199], v165 offset:38912
	ds_read_b128 v[200:203], v165 offset:39936
	global_load_lds_dwordx4 v[204:205], off
	s_mov_b32 m0, s40
	v_lshl_add_u64 v[204:205], s[22:23], 0, v[146:147]
	global_load_lds_dwordx4 v[204:205], off
	s_waitcnt lgkmcnt(8)
	s_barrier
	s_waitcnt lgkmcnt(0)
	v_mfma_f32_16x16x32_bf16 v[140:143], v[48:51], v[154:157], v[140:143]
	v_mfma_f32_16x16x32_bf16 v[136:139], v[64:67], v[154:157], v[136:139]
	v_mfma_f32_16x16x32_bf16 v[124:127], v[48:51], v[180:183], v[124:127]
	v_mfma_f32_16x16x32_bf16 v[120:123], v[64:67], v[180:183], v[120:123]
	v_mfma_f32_16x16x32_bf16 v[108:111], v[48:51], v[188:191], v[108:111]
	v_mfma_f32_16x16x32_bf16 v[104:107], v[64:67], v[188:191], v[104:107]
	v_mfma_f32_16x16x32_bf16 v[92:95], v[48:51], v[196:199], v[92:95]
	v_mfma_f32_16x16x32_bf16 v[88:91], v[64:67], v[196:199], v[88:91]
	v_mfma_f32_16x16x32_bf16 v[140:143], v[52:55], v[158:161], v[140:143]
	v_mfma_f32_16x16x32_bf16 v[136:139], v[68:71], v[158:161], v[136:139]
	v_mfma_f32_16x16x32_bf16 v[124:127], v[52:55], v[184:187], v[124:127]
	v_mfma_f32_16x16x32_bf16 v[120:123], v[68:71], v[184:187], v[120:123]
	v_mfma_f32_16x16x32_bf16 v[108:111], v[52:55], v[192:195], v[108:111]
	v_mfma_f32_16x16x32_bf16 v[104:107], v[68:71], v[192:195], v[104:107]
	v_mfma_f32_16x16x32_bf16 v[92:95], v[52:55], v[200:203], v[92:95]
	v_mfma_f32_16x16x32_bf16 v[88:91], v[68:71], v[200:203], v[88:91]
	s_barrier
	s_add_i32 s22, 0, 0x1c000
	s_add_i32 s23, s53, s36
	v_add_u32_e32 v216, s22, v164
	v_lshl_add_u64 v[166:167], v[166:167], 0, s[78:79]
	s_mov_b32 m0, s23
	ds_read_b128 v[204:207], v216
	ds_read_b128 v[208:211], v216 offset:1024
	ds_read_b128 v[212:215], v216 offset:2048
	ds_read_b128 v[216:219], v216 offset:3072
	global_load_lds_dwordx4 v[166:167], off
	s_add_i32 m0, s23, 0x2000
	v_lshl_add_u64 v[166:167], v[220:221], 0, s[78:79]
	global_load_lds_dwordx4 v[166:167], off
	s_barrier
	s_waitcnt lgkmcnt(0)
	v_mfma_f32_16x16x32_bf16 v[132:135], v[204:207], v[154:157], v[132:135]
	v_mfma_f32_16x16x32_bf16 v[128:131], v[212:215], v[154:157], v[128:131]
	v_mfma_f32_16x16x32_bf16 v[116:119], v[204:207], v[180:183], v[116:119]
	v_mfma_f32_16x16x32_bf16 v[112:115], v[212:215], v[180:183], v[112:115]
	v_mfma_f32_16x16x32_bf16 v[100:103], v[204:207], v[188:191], v[100:103]
	v_mfma_f32_16x16x32_bf16 v[96:99], v[212:215], v[188:191], v[96:99]
	v_mfma_f32_16x16x32_bf16 v[84:87], v[204:207], v[196:199], v[84:87]
	v_mfma_f32_16x16x32_bf16 v[80:83], v[212:215], v[196:199], v[80:83]
	v_mfma_f32_16x16x32_bf16 v[132:135], v[208:211], v[158:161], v[132:135]
	v_mfma_f32_16x16x32_bf16 v[128:131], v[216:219], v[158:161], v[128:131]
	v_mfma_f32_16x16x32_bf16 v[116:119], v[208:211], v[184:187], v[116:119]
	v_mfma_f32_16x16x32_bf16 v[112:115], v[216:219], v[184:187], v[112:115]
	v_mfma_f32_16x16x32_bf16 v[100:103], v[208:211], v[192:195], v[100:103]
	v_mfma_f32_16x16x32_bf16 v[96:99], v[216:219], v[192:195], v[96:99]
	v_mfma_f32_16x16x32_bf16 v[84:87], v[208:211], v[200:203], v[84:87]
	v_mfma_f32_16x16x32_bf16 v[80:83], v[216:219], v[200:203], v[80:83]
	s_mov_b32 m0, s45
	v_lshl_add_u64 v[166:167], v[222:223], 0, s[78:79]
	s_barrier
	ds_read_b128 v[154:157], v165 offset:49152
	ds_read_b128 v[158:161], v165 offset:50176
	ds_read_b128 v[180:183], v165 offset:51200
	ds_read_b128 v[184:187], v165 offset:52224
	ds_read_b128 v[188:191], v165 offset:53248
	ds_read_b128 v[192:195], v165 offset:54272
	ds_read_b128 v[196:199], v165 offset:55296
	ds_read_b128 v[200:203], v165 offset:56320
	global_load_lds_dwordx4 v[166:167], off
	s_mov_b32 m0, s46
	v_lshl_add_u64 v[166:167], v[236:237], 0, s[78:79]
	global_load_lds_dwordx4 v[166:167], off
	s_barrier
	s_waitcnt lgkmcnt(0)
	v_mfma_f32_16x16x32_bf16 v[76:79], v[48:51], v[154:157], v[76:79]
	v_mfma_f32_16x16x32_bf16 v[72:75], v[64:67], v[154:157], v[72:75]
	v_mfma_f32_16x16x32_bf16 v[60:63], v[48:51], v[180:183], v[60:63]
	v_mfma_f32_16x16x32_bf16 v[56:59], v[64:67], v[180:183], v[56:59]
	v_mfma_f32_16x16x32_bf16 v[44:47], v[48:51], v[188:191], v[44:47]
	v_mfma_f32_16x16x32_bf16 v[40:43], v[64:67], v[188:191], v[40:43]
	v_mfma_f32_16x16x32_bf16 v[12:15], v[48:51], v[196:199], v[12:15]
	v_mfma_f32_16x16x32_bf16 v[8:11], v[64:67], v[196:199], v[8:11]
	v_mfma_f32_16x16x32_bf16 v[76:79], v[52:55], v[158:161], v[76:79]
	v_mfma_f32_16x16x32_bf16 v[72:75], v[68:71], v[158:161], v[72:75]
	v_mfma_f32_16x16x32_bf16 v[60:63], v[52:55], v[184:187], v[60:63]
	v_mfma_f32_16x16x32_bf16 v[56:59], v[68:71], v[184:187], v[56:59]
	v_mfma_f32_16x16x32_bf16 v[44:47], v[52:55], v[192:195], v[44:47]
	v_mfma_f32_16x16x32_bf16 v[40:43], v[68:71], v[192:195], v[40:43]
	v_mfma_f32_16x16x32_bf16 v[12:15], v[52:55], v[200:203], v[12:15]
	v_mfma_f32_16x16x32_bf16 v[8:11], v[68:71], v[200:203], v[8:11]
	s_barrier
	s_add_u32 s2, s2, 0x40080
	s_addc_u32 s3, s3, 0
	s_add_i32 s22, s22, s36
	s_mov_b32 m0, s22
	v_lshl_add_u64 v[48:49], s[2:3], 0, v[168:169]
	global_load_lds_dwordx4 v[48:49], off
	s_add_i32 m0, s22, 0x2000
	v_lshl_add_u64 v[48:49], s[2:3], 0, v[148:149]
	global_load_lds_dwordx4 v[48:49], off
	s_waitcnt vmcnt(6)
	s_barrier
	v_mfma_f32_16x16x32_bf16 v[24:27], v[204:207], v[154:157], v[24:27]
	v_mfma_f32_16x16x32_bf16 v[68:71], v[208:211], v[158:161], v[24:27]
	v_mfma_f32_16x16x32_bf16 v[24:27], v[212:215], v[154:157], v[28:31]
	v_mfma_f32_16x16x32_bf16 v[64:67], v[216:219], v[158:161], v[24:27]
	v_mfma_f32_16x16x32_bf16 v[24:27], v[204:207], v[180:183], v[32:35]
	v_mfma_f32_16x16x32_bf16 v[52:55], v[208:211], v[184:187], v[24:27]
	v_mfma_f32_16x16x32_bf16 v[24:27], v[212:215], v[180:183], v[36:39]
	v_mfma_f32_16x16x32_bf16 v[20:23], v[204:207], v[188:191], v[20:23]
	v_mfma_f32_16x16x32_bf16 v[16:19], v[212:215], v[188:191], v[16:19]
	v_mfma_f32_16x16x32_bf16 v[4:7], v[204:207], v[196:199], v[4:7]
	v_mfma_f32_16x16x32_bf16 v[0:3], v[212:215], v[196:199], v[0:3]
	v_mfma_f32_16x16x32_bf16 v[48:51], v[216:219], v[184:187], v[24:27]
	v_mfma_f32_16x16x32_bf16 v[20:23], v[208:211], v[192:195], v[20:23]
	v_mfma_f32_16x16x32_bf16 v[16:19], v[216:219], v[192:195], v[16:19]
	v_mfma_f32_16x16x32_bf16 v[4:7], v[208:211], v[200:203], v[4:7]
	v_mfma_f32_16x16x32_bf16 v[0:3], v[216:219], v[200:203], v[0:3]
	s_add_i32 s52, s52, 2
	s_add_u32 s20, s20, 0x100
	s_addc_u32 s21, s21, 0
	s_add_u32 s50, s50, 0x100
	s_addc_u32 s51, s51, 0
	s_cmp_gt_u32 s52, 13
	s_barrier
	s_cbranch_scc0 .LBB0_123
	s_lshl_b32 s2, s6, 8
	s_add_i32 s3, s2, s43
	s_lshl_b32 s2, s8, 8
	s_cmp_gt_i32 s8, 3
	s_cselect_b64 s[20:21], -1, 0
	s_and_b64 s[22:23], s[20:21], exec
	s_mov_b32 s7, 0x8982000
	s_cselect_b32 s7, s7, 0x7182000
	s_add_u32 s22, s26, s7
	s_addc_u32 s23, s25, 0
	s_add_i32 s7, s6, -16
	v_mov_b32_e32 v160, v163
	v_mov_b32_e32 v24, v162
	s_lshr_b32 s7, s7, 3
	s_add_i32 s96, s7, 1
	v_add_u32_e32 v154, s3, v24
	s_lshl_b64 s[50:51], s[96:97], 11
	v_ashrrev_i32_e32 v155, 31, v154
	s_cmp_gt_i32 s6, 15
	v_lshl_add_u64 v[156:157], v[154:155], 2, s[10:11]
	s_cselect_b32 s7, s51, 0
	s_cselect_b32 s6, s50, 0
	global_load_dword v166, v[156:157], off
	global_load_dword v191, v[156:157], off offset:64
	global_load_dword v192, v[156:157], off offset:128
	global_load_dword v193, v[156:157], off offset:192
	global_load_dword v194, v[156:157], off offset:512
	global_load_dword v195, v[156:157], off offset:576
	global_load_dword v196, v[156:157], off offset:640
	global_load_dword v197, v[156:157], off offset:704
	s_lshl_b64 s[6:7], s[6:7], 2
	s_add_u32 s9, s41, s6
	s_addc_u32 s13, s42, s7
	s_ashr_i32 s3, s2, 31
	s_lshl_b64 s[6:7], s[2:3], 2
	s_add_u32 s3, s9, s6
	s_addc_u32 s7, s13, s7
	v_lshlrev_b32_e32 v158, 3, v160
	s_add_u32 s6, s3, s49
	s_addc_u32 s7, s7, 0
	v_ashrrev_i32_e32 v159, 31, v158
	v_lshl_add_u64 v[24:25], v[158:159], 2, s[6:7]
	global_load_dwordx4 v[36:39], v[24:25], off
	global_load_dwordx4 v[32:35], v[24:25], off offset:16
	global_load_dwordx4 v[28:31], v[24:25], off offset:512
	s_nop 0
	global_load_dwordx4 v[24:27], v[24:25], off offset:528
	s_and_b32 s2, s2, 0x300
	s_or_b32 s2, s2, s44
	v_add_u32_e32 v158, s2, v158
	v_cmp_eq_u32_e64 s[6:7], 0, v160
	v_lshlrev_b64 v[160:161], 11, v[154:155]
	s_cmp_lt_i32 s8, 4
	s_waitcnt vmcnt(0)
	v_ashrrev_i32_e32 v159, 31, v158
	v_lshl_add_u64 v[158:159], v[158:159], 1, s[22:23]
	v_lshl_add_u64 v[160:161], v[158:159], 0, v[160:161]
	v_lshl_add_u64 v[156:157], v[154:155], 2, s[0:1]
	s_and_b64 s[6:7], s[6:7], s[20:21]
	s_mov_b64 s[2:3], 0x8000
	s_mov_b64 s[50:51], 0x28000
	v_mov_b32_e32 v180, 0xc0135761
	v_mov_b32_e32 v181, 0xc0135761
	v_mov_b32_e32 v182, 0xbdd2d3e7
	v_mov_b32_e32 v183, 0xbdd2d3e7
	v_fmamk_f32 v166, v166, 0x3a800000, v225
	v_fmamk_f32 v190, v191, 0x3a800000, v225
	v_fmamk_f32 v192, v192, 0x3a800000, v225
	v_fmamk_f32 v188, v193, 0x3a800000, v225
	v_fmamk_f32 v194, v194, 0x3a800000, v225
	v_fmamk_f32 v186, v195, 0x3a800000, v225
	v_fmamk_f32 v196, v196, 0x3a800000, v225
	v_fmamk_f32 v184, v197, 0x3a800000, v225
	v_rsq_f32_e32 v166, v166
	v_rsq_f32_e32 v190, v190
	v_rsq_f32_e32 v192, v192
	v_rsq_f32_e32 v188, v188
	v_rsq_f32_e32 v194, v194
	v_rsq_f32_e32 v186, v186
	v_rsq_f32_e32 v196, v196
	v_rsq_f32_e32 v184, v184
	v_pk_fma_f32 v[140:141], v[140:141], v[166:167], v[36:37] op_sel_hi:[1,0,1]
	v_pk_fma_f32 v[142:143], v[142:143], v[166:167], v[38:39] op_sel_hi:[1,0,1]
	v_pk_fma_f32 v[136:137], v[136:137], v[166:167], v[32:33] op_sel_hi:[1,0,1]
	v_pk_fma_f32 v[138:139], v[138:139], v[166:167], v[34:35] op_sel_hi:[1,0,1]
	v_pk_fma_f32 v[132:133], v[132:133], v[166:167], v[28:29] op_sel_hi:[1,0,1]
	v_pk_fma_f32 v[134:135], v[134:135], v[166:167], v[30:31] op_sel_hi:[1,0,1]
	v_pk_fma_f32 v[128:129], v[128:129], v[166:167], v[24:25] op_sel_hi:[1,0,1]
	v_pk_fma_f32 v[130:131], v[130:131], v[166:167], v[26:27] op_sel_hi:[1,0,1]
	v_pk_fma_f32 v[124:125], v[124:125], v[190:191], v[36:37] op_sel_hi:[1,0,1]
	v_pk_fma_f32 v[126:127], v[126:127], v[190:191], v[38:39] op_sel_hi:[1,0,1]
	v_pk_fma_f32 v[120:121], v[120:121], v[190:191], v[32:33] op_sel_hi:[1,0,1]
	v_pk_fma_f32 v[122:123], v[122:123], v[190:191], v[34:35] op_sel_hi:[1,0,1]
	v_pk_fma_f32 v[116:117], v[116:117], v[190:191], v[28:29] op_sel_hi:[1,0,1]
	v_pk_fma_f32 v[118:119], v[118:119], v[190:191], v[30:31] op_sel_hi:[1,0,1]
	v_pk_fma_f32 v[112:113], v[112:113], v[190:191], v[24:25] op_sel_hi:[1,0,1]
	v_pk_fma_f32 v[114:115], v[114:115], v[190:191], v[26:27] op_sel_hi:[1,0,1]
	v_pk_fma_f32 v[108:109], v[108:109], v[192:193], v[36:37] op_sel_hi:[1,0,1]
	v_pk_fma_f32 v[110:111], v[110:111], v[192:193], v[38:39] op_sel_hi:[1,0,1]
	v_pk_fma_f32 v[104:105], v[104:105], v[192:193], v[32:33] op_sel_hi:[1,0,1]
	v_pk_fma_f32 v[106:107], v[106:107], v[192:193], v[34:35] op_sel_hi:[1,0,1]
	v_pk_fma_f32 v[100:101], v[100:101], v[192:193], v[28:29] op_sel_hi:[1,0,1]
	v_pk_fma_f32 v[102:103], v[102:103], v[192:193], v[30:31] op_sel_hi:[1,0,1]
	v_pk_fma_f32 v[96:97], v[96:97], v[192:193], v[24:25] op_sel_hi:[1,0,1]
	v_pk_fma_f32 v[98:99], v[98:99], v[192:193], v[26:27] op_sel_hi:[1,0,1]
	v_pk_fma_f32 v[92:93], v[92:93], v[188:189], v[36:37] op_sel_hi:[1,0,1]
	v_pk_fma_f32 v[94:95], v[94:95], v[188:189], v[38:39] op_sel_hi:[1,0,1]
	v_pk_fma_f32 v[88:89], v[88:89], v[188:189], v[32:33] op_sel_hi:[1,0,1]
	v_pk_fma_f32 v[90:91], v[90:91], v[188:189], v[34:35] op_sel_hi:[1,0,1]
	v_pk_fma_f32 v[84:85], v[84:85], v[188:189], v[28:29] op_sel_hi:[1,0,1]
	v_pk_fma_f32 v[86:87], v[86:87], v[188:189], v[30:31] op_sel_hi:[1,0,1]
	v_pk_fma_f32 v[80:81], v[80:81], v[188:189], v[24:25] op_sel_hi:[1,0,1]
	v_pk_fma_f32 v[82:83], v[82:83], v[188:189], v[26:27] op_sel_hi:[1,0,1]
	v_pk_fma_f32 v[76:77], v[76:77], v[194:195], v[36:37] op_sel_hi:[1,0,1]
	v_pk_fma_f32 v[78:79], v[78:79], v[194:195], v[38:39] op_sel_hi:[1,0,1]
	v_pk_fma_f32 v[72:73], v[72:73], v[194:195], v[32:33] op_sel_hi:[1,0,1]
	v_pk_fma_f32 v[74:75], v[74:75], v[194:195], v[34:35] op_sel_hi:[1,0,1]
	v_pk_fma_f32 v[68:69], v[68:69], v[194:195], v[28:29] op_sel_hi:[1,0,1]
	v_pk_fma_f32 v[70:71], v[70:71], v[194:195], v[30:31] op_sel_hi:[1,0,1]
	v_pk_fma_f32 v[64:65], v[64:65], v[194:195], v[24:25] op_sel_hi:[1,0,1]
	v_pk_fma_f32 v[66:67], v[66:67], v[194:195], v[26:27] op_sel_hi:[1,0,1]
	v_pk_fma_f32 v[60:61], v[60:61], v[186:187], v[36:37] op_sel_hi:[1,0,1]
	v_pk_fma_f32 v[62:63], v[62:63], v[186:187], v[38:39] op_sel_hi:[1,0,1]
	v_pk_fma_f32 v[56:57], v[56:57], v[186:187], v[32:33] op_sel_hi:[1,0,1]
	v_pk_fma_f32 v[58:59], v[58:59], v[186:187], v[34:35] op_sel_hi:[1,0,1]
	v_pk_fma_f32 v[52:53], v[52:53], v[186:187], v[28:29] op_sel_hi:[1,0,1]
	v_pk_fma_f32 v[54:55], v[54:55], v[186:187], v[30:31] op_sel_hi:[1,0,1]
	v_pk_fma_f32 v[48:49], v[48:49], v[186:187], v[24:25] op_sel_hi:[1,0,1]
	v_pk_fma_f32 v[50:51], v[50:51], v[186:187], v[26:27] op_sel_hi:[1,0,1]
	v_pk_fma_f32 v[44:45], v[44:45], v[196:197], v[36:37] op_sel_hi:[1,0,1]
	v_pk_fma_f32 v[46:47], v[46:47], v[196:197], v[38:39] op_sel_hi:[1,0,1]
	v_pk_fma_f32 v[40:41], v[40:41], v[196:197], v[32:33] op_sel_hi:[1,0,1]
	v_pk_fma_f32 v[42:43], v[42:43], v[196:197], v[34:35] op_sel_hi:[1,0,1]
	v_pk_fma_f32 v[20:21], v[20:21], v[196:197], v[28:29] op_sel_hi:[1,0,1]
	v_pk_fma_f32 v[22:23], v[22:23], v[196:197], v[30:31] op_sel_hi:[1,0,1]
	v_pk_fma_f32 v[16:17], v[16:17], v[196:197], v[24:25] op_sel_hi:[1,0,1]
	v_pk_fma_f32 v[18:19], v[18:19], v[196:197], v[26:27] op_sel_hi:[1,0,1]
	v_pk_fma_f32 v[12:13], v[12:13], v[184:185], v[36:37] op_sel_hi:[1,0,1]
	v_pk_fma_f32 v[14:15], v[14:15], v[184:185], v[38:39] op_sel_hi:[1,0,1]
	v_pk_fma_f32 v[8:9], v[8:9], v[184:185], v[32:33] op_sel_hi:[1,0,1]
	v_pk_fma_f32 v[10:11], v[10:11], v[184:185], v[34:35] op_sel_hi:[1,0,1]
	v_pk_fma_f32 v[4:5], v[4:5], v[184:185], v[28:29] op_sel_hi:[1,0,1]
	v_pk_fma_f32 v[6:7], v[6:7], v[184:185], v[30:31] op_sel_hi:[1,0,1]
	v_pk_fma_f32 v[0:1], v[0:1], v[184:185], v[24:25] op_sel_hi:[1,0,1]
	v_pk_fma_f32 v[2:3], v[2:3], v[184:185], v[26:27] op_sel_hi:[1,0,1]
	v_pk_mul_f32 v[24:25], v[140:141], v[140:141]
	v_pk_mul_f32 v[26:27], v[142:143], v[142:143]
	v_pk_mul_f32 v[28:29], v[136:137], v[136:137]
	v_pk_mul_f32 v[30:31], v[138:139], v[138:139]
	v_pk_mul_f32 v[32:33], v[132:133], v[132:133]
	v_pk_mul_f32 v[34:35], v[134:135], v[134:135]
	v_pk_mul_f32 v[36:37], v[128:129], v[128:129]
	v_pk_mul_f32 v[38:39], v[130:131], v[130:131]
	v_pk_fma_f32 v[24:25], v[24:25], v[182:183], v[180:181]
	v_pk_fma_f32 v[26:27], v[26:27], v[182:183], v[180:181]
	v_pk_fma_f32 v[28:29], v[28:29], v[182:183], v[180:181]
	v_pk_fma_f32 v[30:31], v[30:31], v[182:183], v[180:181]
	v_pk_fma_f32 v[32:33], v[32:33], v[182:183], v[180:181]
	v_pk_fma_f32 v[34:35], v[34:35], v[182:183], v[180:181]
	v_pk_fma_f32 v[36:37], v[36:37], v[182:183], v[180:181]
	v_pk_fma_f32 v[38:39], v[38:39], v[182:183], v[180:181]
	v_pk_mul_f32 v[24:25], v[24:25], v[140:141]
	v_pk_mul_f32 v[26:27], v[26:27], v[142:143]
	v_pk_mul_f32 v[28:29], v[28:29], v[136:137]
	v_pk_mul_f32 v[30:31], v[30:31], v[138:139]
	v_pk_mul_f32 v[32:33], v[32:33], v[132:133]
	v_pk_mul_f32 v[34:35], v[34:35], v[134:135]
	v_pk_mul_f32 v[36:37], v[36:37], v[128:129]
	v_pk_mul_f32 v[38:39], v[38:39], v[130:131]
	v_exp_f32_e32 v24, v24
	v_exp_f32_e32 v25, v25
	v_exp_f32_e32 v26, v26
	v_exp_f32_e32 v27, v27
	v_exp_f32_e32 v28, v28
	v_exp_f32_e32 v29, v29
	v_exp_f32_e32 v30, v30
	v_exp_f32_e32 v31, v31
	v_exp_f32_e32 v32, v32
	v_exp_f32_e32 v33, v33
	v_exp_f32_e32 v34, v34
	v_exp_f32_e32 v35, v35
	v_exp_f32_e32 v36, v36
	v_exp_f32_e32 v37, v37
	v_exp_f32_e32 v38, v38
	v_exp_f32_e32 v39, v39
	v_pk_add_f32 v[24:25], v[24:25], 1.0 op_sel_hi:[1,0]
	v_pk_add_f32 v[26:27], v[26:27], 1.0 op_sel_hi:[1,0]
	v_pk_add_f32 v[28:29], v[28:29], 1.0 op_sel_hi:[1,0]
	v_pk_add_f32 v[30:31], v[30:31], 1.0 op_sel_hi:[1,0]
	v_pk_add_f32 v[32:33], v[32:33], 1.0 op_sel_hi:[1,0]
	v_pk_add_f32 v[34:35], v[34:35], 1.0 op_sel_hi:[1,0]
	v_pk_add_f32 v[36:37], v[36:37], 1.0 op_sel_hi:[1,0]
	v_pk_add_f32 v[38:39], v[38:39], 1.0 op_sel_hi:[1,0]
	v_rcp_f32_e32 v24, v24
	v_rcp_f32_e32 v25, v25
	v_rcp_f32_e32 v26, v26
	v_rcp_f32_e32 v27, v27
	v_rcp_f32_e32 v28, v28
	v_rcp_f32_e32 v29, v29
	v_rcp_f32_e32 v30, v30
	v_rcp_f32_e32 v31, v31
	v_rcp_f32_e32 v32, v32
	v_rcp_f32_e32 v33, v33
	v_rcp_f32_e32 v34, v34
	v_rcp_f32_e32 v35, v35
	v_rcp_f32_e32 v36, v36
	v_rcp_f32_e32 v37, v37
	v_rcp_f32_e32 v38, v38
	v_rcp_f32_e32 v39, v39
	v_pk_mul_f32 v[140:141], v[140:141], v[24:25]
	v_pk_mul_f32 v[142:143], v[142:143], v[26:27]
	v_pk_mul_f32 v[136:137], v[136:137], v[28:29]
	v_pk_mul_f32 v[138:139], v[138:139], v[30:31]
	v_pk_mul_f32 v[132:133], v[132:133], v[32:33]
	v_pk_mul_f32 v[134:135], v[134:135], v[34:35]
	v_pk_mul_f32 v[128:129], v[128:129], v[36:37]
	v_pk_mul_f32 v[130:131], v[130:131], v[38:39]
	v_cvt_pk_bf16_f32 v24, v140, v141
	v_cvt_pk_bf16_f32 v25, v142, v143
	v_cvt_pk_bf16_f32 v26, v136, v137
	v_cvt_pk_bf16_f32 v27, v138, v139
	v_cvt_pk_bf16_f32 v28, v132, v133
	v_cvt_pk_bf16_f32 v29, v134, v135
	v_cvt_pk_bf16_f32 v30, v128, v129
	v_cvt_pk_bf16_f32 v31, v130, v131
	global_store_dwordx4 v[160:161], v[24:27], off
	global_store_dwordx4 v[160:161], v[28:31], off offset:256
	s_and_b64 vcc, exec, s[20:21]
	s_cbranch_vccz .Lio_skip_0
	v_pk_mul_f32 v[32:33], v[140:141], v[140:141]
	v_pk_fma_f32 v[32:33], v[142:143], v[142:143], v[32:33]
	v_pk_fma_f32 v[32:33], v[136:137], v[136:137], v[32:33]
	v_pk_fma_f32 v[32:33], v[138:139], v[138:139], v[32:33]
	v_pk_fma_f32 v[32:33], v[132:133], v[132:133], v[32:33]
	v_pk_fma_f32 v[32:33], v[134:135], v[134:135], v[32:33]
	v_pk_fma_f32 v[32:33], v[128:129], v[128:129], v[32:33]
	v_pk_fma_f32 v[32:33], v[130:131], v[130:131], v[32:33]
	s_nop 0
	v_add_f32_e32 v32, v32, v33
	v_mov_b32_e32 v33, v32
	s_nop 1
	v_permlane16_swap_b32_e32 v32, v33
	v_add_f32_e32 v32, v32, v33
	v_mov_b32_e32 v33, v32
	s_nop 1
	v_permlane32_swap_b32_e32 v32, v33
	s_and_saveexec_b64 vcc, s[6:7]
	v_add_f32_e32 v32, v32, v33
	global_atomic_add_f32 v[156:157], v32, off
	s_mov_b64 exec, vcc

.Lie_done_b:
.LBB0_354:
	s_ashr_i32 s31, s30, 31
	v_cmp_lt_i64_e32 vcc, s[8:9], v[170:171]
	s_lshl_b64 s[8:9], s[30:31], 19
	s_add_u32 s34, s52, s8
	s_addc_u32 s35, s53, s9
	s_and_b64 s[8:9], vcc, exec
	s_cselect_b32 s1, s35, s7
	s_cselect_b32 s31, s34, s6
	s_ashr_i32 s29, s28, 31
	s_lshl_b64 s[8:9], s[28:29], 19
	s_add_u32 s36, s43, s8
	s_addc_u32 s37, s42, s9
	s_and_b64 s[8:9], vcc, exec
	s_cselect_b32 s29, s37, s3
	s_cselect_b32 s38, s36, s2
	s_add_u32 s6, s6, 0x40080
	s_addc_u32 s7, s7, 0
	s_add_u32 s39, s2, 0x100
	s_addc_u32 s40, s3, 0
	s_mov_b32 s41, -2
	s_add_u32 s2, s6, 0xfffc0080
	s_addc_u32 s3, s7, -1
	s_add_i32 s64, 0, 0x10000
	v_add_u32_e32 v140, s64, v208
	ds_read_b128 v[128:131], v140
	ds_read_b128 v[132:135], v140 offset:1024
	ds_read_b128 v[136:139], v140 offset:2048
	ds_read_b128 v[140:143], v140 offset:3072
	s_cmp_eq_u32 s41, 12
	s_cselect_b32 s9, s1, s3
	s_cselect_b32 s8, s31, s2
	s_cselect_b32 s3, s29, s40
	s_cselect_b32 s2, s38, s39
	v_lshl_add_u64 v[196:197], s[6:7], 0, v[164:165]
	s_add_i32 m0, s21, 0xc000
	ds_read_b128 v[144:147], v209
	ds_read_b128 v[148:151], v209 offset:1024
	ds_read_b128 v[152:155], v209 offset:2048
	ds_read_b128 v[156:159], v209 offset:3072
	ds_read_b128 v[180:183], v209 offset:4096
	ds_read_b128 v[184:187], v209 offset:5120
	ds_read_b128 v[188:191], v209 offset:6144
	ds_read_b128 v[192:195], v209 offset:7168
	global_load_lds_dwordx4 v[196:197], off
	s_add_i32 m0, s21, 0xe000
	v_lshl_add_u64 v[196:197], s[6:7], 0, v[166:167]
	global_load_lds_dwordx4 v[196:197], off
	s_waitcnt lgkmcnt(8)
	s_barrier
	s_waitcnt lgkmcnt(0)
	v_mfma_f32_16x16x32_bf16 v[124:127], v[128:131], v[144:147], 0
	v_mfma_f32_16x16x32_bf16 v[120:123], v[136:139], v[144:147], 0
	v_mfma_f32_16x16x32_bf16 v[116:119], v[128:131], v[152:155], 0
	v_mfma_f32_16x16x32_bf16 v[112:115], v[136:139], v[152:155], 0
	v_mfma_f32_16x16x32_bf16 v[100:103], v[128:131], v[180:183], 0
	v_mfma_f32_16x16x32_bf16 v[96:99], v[136:139], v[180:183], 0
	v_mfma_f32_16x16x32_bf16 v[84:87], v[128:131], v[188:191], 0
	v_mfma_f32_16x16x32_bf16 v[80:83], v[136:139], v[188:191], 0
	v_mfma_f32_16x16x32_bf16 v[124:127], v[132:135], v[148:151], v[124:127]
	v_mfma_f32_16x16x32_bf16 v[120:123], v[140:143], v[148:151], v[120:123]
	v_mfma_f32_16x16x32_bf16 v[116:119], v[132:135], v[156:159], v[116:119]
	v_mfma_f32_16x16x32_bf16 v[112:115], v[140:143], v[156:159], v[112:115]
	v_mfma_f32_16x16x32_bf16 v[100:103], v[132:135], v[184:187], v[100:103]
	v_mfma_f32_16x16x32_bf16 v[96:99], v[140:143], v[184:187], v[96:99]
	v_mfma_f32_16x16x32_bf16 v[84:87], v[132:135], v[192:195], v[84:87]
	v_mfma_f32_16x16x32_bf16 v[80:83], v[140:143], v[192:195], v[80:83]
	s_barrier
	s_add_i32 s66, 0, 0x14000
	s_add_i32 s64, s64, s54
	v_add_u32_e32 v168, s66, v208
	v_lshl_add_u64 v[204:205], s[2:3], 0, v[160:161]
	s_mov_b32 m0, s64
	ds_read_b128 v[196:199], v168
	ds_read_b128 v[200:203], v168 offset:1024
	ds_read_b128 v[210:213], v168 offset:2048
	ds_read_b128 v[214:217], v168 offset:3072
	global_load_lds_dwordx4 v[204:205], off
	s_add_i32 m0, s64, 0x2000
	v_lshl_add_u64 v[218:219], s[2:3], 0, v[162:163]
	global_load_lds_dwordx4 v[218:219], off
	s_barrier
	s_waitcnt lgkmcnt(0)
	v_mfma_f32_16x16x32_bf16 v[108:111], v[196:199], v[144:147], 0
	v_mfma_f32_16x16x32_bf16 v[104:107], v[210:213], v[144:147], 0
	v_mfma_f32_16x16x32_bf16 v[92:95], v[196:199], v[152:155], 0
	v_mfma_f32_16x16x32_bf16 v[88:91], v[210:213], v[152:155], 0
	v_mfma_f32_16x16x32_bf16 v[76:79], v[196:199], v[180:183], 0
	v_mfma_f32_16x16x32_bf16 v[72:75], v[210:213], v[180:183], 0
	v_mfma_f32_16x16x32_bf16 v[68:71], v[196:199], v[188:191], 0
	v_mfma_f32_16x16x32_bf16 v[64:67], v[210:213], v[188:191], 0
	v_mfma_f32_16x16x32_bf16 v[108:111], v[200:203], v[148:151], v[108:111]
	v_mfma_f32_16x16x32_bf16 v[104:107], v[214:217], v[148:151], v[104:107]
	v_mfma_f32_16x16x32_bf16 v[92:95], v[200:203], v[156:159], v[92:95]
	v_mfma_f32_16x16x32_bf16 v[88:91], v[214:217], v[156:159], v[88:91]
	v_mfma_f32_16x16x32_bf16 v[76:79], v[200:203], v[184:187], v[76:79]
	v_mfma_f32_16x16x32_bf16 v[72:75], v[214:217], v[184:187], v[72:75]
	v_mfma_f32_16x16x32_bf16 v[68:71], v[200:203], v[192:195], v[68:71]
	v_mfma_f32_16x16x32_bf16 v[64:67], v[214:217], v[192:195], v[64:67]
	s_mov_b32 m0, s21
	v_lshl_add_u64 v[220:221], s[8:9], 0, v[160:161]
	s_barrier
	ds_read_b128 v[144:147], v209 offset:16384
	ds_read_b128 v[148:151], v209 offset:17408
	ds_read_b128 v[152:155], v209 offset:18432
	ds_read_b128 v[156:159], v209 offset:19456
	ds_read_b128 v[180:183], v209 offset:20480
	ds_read_b128 v[184:187], v209 offset:21504
	ds_read_b128 v[188:191], v209 offset:22528
	ds_read_b128 v[192:195], v209 offset:23552
	global_load_lds_dwordx4 v[220:221], off
	s_mov_b32 m0, s55
	v_lshl_add_u64 v[222:223], s[8:9], 0, v[162:163]
	global_load_lds_dwordx4 v[222:223], off
	s_barrier
	s_waitcnt lgkmcnt(0)
	v_mfma_f32_16x16x32_bf16 v[60:63], v[128:131], v[144:147], 0
	v_mfma_f32_16x16x32_bf16 v[56:59], v[136:139], v[144:147], 0
	v_mfma_f32_16x16x32_bf16 v[52:55], v[128:131], v[152:155], 0
	v_mfma_f32_16x16x32_bf16 v[48:51], v[136:139], v[152:155], 0
	v_mfma_f32_16x16x32_bf16 v[36:39], v[128:131], v[180:183], 0
	v_mfma_f32_16x16x32_bf16 v[32:35], v[136:139], v[180:183], 0
	v_mfma_f32_16x16x32_bf16 v[20:23], v[128:131], v[188:191], 0
	v_mfma_f32_16x16x32_bf16 v[16:19], v[136:139], v[188:191], 0
	v_mfma_f32_16x16x32_bf16 v[60:63], v[132:135], v[148:151], v[60:63]
	v_mfma_f32_16x16x32_bf16 v[56:59], v[140:143], v[148:151], v[56:59]
	v_mfma_f32_16x16x32_bf16 v[52:55], v[132:135], v[156:159], v[52:55]
	v_mfma_f32_16x16x32_bf16 v[48:51], v[140:143], v[156:159], v[48:51]
	v_mfma_f32_16x16x32_bf16 v[36:39], v[132:135], v[184:187], v[36:39]
	v_mfma_f32_16x16x32_bf16 v[32:35], v[140:143], v[184:187], v[32:35]
	v_mfma_f32_16x16x32_bf16 v[20:23], v[132:135], v[192:195], v[20:23]
	v_mfma_f32_16x16x32_bf16 v[16:19], v[140:143], v[192:195], v[16:19]
	s_barrier
	s_add_u32 s64, s2, 0x40000
	s_addc_u32 s65, s3, 0
	s_add_i32 s66, s66, s54
	s_mov_b32 m0, s66
	v_lshl_add_u64 v[128:129], s[64:65], 0, v[160:161]
	global_load_lds_dwordx4 v[128:129], off
	s_add_i32 m0, s66, 0x2000
	v_lshl_add_u64 v[128:129], s[64:65], 0, v[162:163]
	global_load_lds_dwordx4 v[128:129], off
	s_waitcnt vmcnt(6)
	s_barrier
	v_mfma_f32_16x16x32_bf16 v[44:47], v[196:199], v[144:147], 0
	v_mfma_f32_16x16x32_bf16 v[40:43], v[210:213], v[144:147], 0
	v_mfma_f32_16x16x32_bf16 v[28:31], v[196:199], v[152:155], 0
	v_mfma_f32_16x16x32_bf16 v[24:27], v[210:213], v[152:155], 0
	v_mfma_f32_16x16x32_bf16 v[12:15], v[196:199], v[180:183], 0
	v_mfma_f32_16x16x32_bf16 v[8:11], v[210:213], v[180:183], 0
	v_mfma_f32_16x16x32_bf16 v[4:7], v[196:199], v[188:191], 0
	v_mfma_f32_16x16x32_bf16 v[0:3], v[210:213], v[188:191], 0
	v_mfma_f32_16x16x32_bf16 v[44:47], v[200:203], v[148:151], v[44:47]
	v_mfma_f32_16x16x32_bf16 v[40:43], v[214:217], v[148:151], v[40:43]
	v_mfma_f32_16x16x32_bf16 v[28:31], v[200:203], v[156:159], v[28:31]
	v_mfma_f32_16x16x32_bf16 v[24:27], v[214:217], v[156:159], v[24:27]
	v_mfma_f32_16x16x32_bf16 v[12:15], v[200:203], v[184:187], v[12:15]
	v_mfma_f32_16x16x32_bf16 v[8:11], v[214:217], v[184:187], v[8:11]
	v_mfma_f32_16x16x32_bf16 v[4:7], v[200:203], v[192:195], v[4:7]
	v_mfma_f32_16x16x32_bf16 v[0:3], v[214:217], v[192:195], v[0:3]
	s_add_i32 s64, 0, 0x18000
	v_add_u32_e32 v140, s64, v208
	s_barrier
	ds_read_b128 v[128:131], v140
	ds_read_b128 v[132:135], v140 offset:1024
	ds_read_b128 v[136:139], v140 offset:2048
	ds_read_b128 v[140:143], v140 offset:3072
	s_add_u32 s8, s8, 0x40000
	s_addc_u32 s9, s9, 0
	s_mov_b32 m0, s56
	v_lshl_add_u64 v[196:197], s[8:9], 0, v[160:161]
	ds_read_b128 v[144:147], v209 offset:32768
	ds_read_b128 v[148:151], v209 offset:33792
	ds_read_b128 v[152:155], v209 offset:34816
	ds_read_b128 v[156:159], v209 offset:35840
	ds_read_b128 v[180:183], v209 offset:36864
	ds_read_b128 v[184:187], v209 offset:37888
	ds_read_b128 v[188:191], v209 offset:38912
	ds_read_b128 v[192:195], v209 offset:39936
	global_load_lds_dwordx4 v[196:197], off
	s_mov_b32 m0, s57
	v_lshl_add_u64 v[196:197], s[8:9], 0, v[162:163]
	global_load_lds_dwordx4 v[196:197], off
	s_waitcnt lgkmcnt(8)
	s_barrier
	s_waitcnt lgkmcnt(0)
	v_mfma_f32_16x16x32_bf16 v[124:127], v[128:131], v[144:147], v[124:127]
	v_mfma_f32_16x16x32_bf16 v[120:123], v[136:139], v[144:147], v[120:123]
	v_mfma_f32_16x16x32_bf16 v[116:119], v[128:131], v[152:155], v[116:119]
	v_mfma_f32_16x16x32_bf16 v[112:115], v[136:139], v[152:155], v[112:115]
	v_mfma_f32_16x16x32_bf16 v[100:103], v[128:131], v[180:183], v[100:103]
	v_mfma_f32_16x16x32_bf16 v[96:99], v[136:139], v[180:183], v[96:99]
	v_mfma_f32_16x16x32_bf16 v[84:87], v[128:131], v[188:191], v[84:87]
	v_mfma_f32_16x16x32_bf16 v[80:83], v[136:139], v[188:191], v[80:83]
	v_mfma_f32_16x16x32_bf16 v[124:127], v[132:135], v[148:151], v[124:127]
	v_mfma_f32_16x16x32_bf16 v[120:123], v[140:143], v[148:151], v[120:123]
	v_mfma_f32_16x16x32_bf16 v[116:119], v[132:135], v[156:159], v[116:119]
	v_mfma_f32_16x16x32_bf16 v[112:115], v[140:143], v[156:159], v[112:115]
	v_mfma_f32_16x16x32_bf16 v[100:103], v[132:135], v[184:187], v[100:103]
	v_mfma_f32_16x16x32_bf16 v[96:99], v[140:143], v[184:187], v[96:99]
	v_mfma_f32_16x16x32_bf16 v[84:87], v[132:135], v[192:195], v[84:87]
	v_mfma_f32_16x16x32_bf16 v[80:83], v[140:143], v[192:195], v[80:83]
	s_barrier
	s_add_i32 s8, 0, 0x1c000
	s_add_i32 s9, s64, s54
	v_add_u32_e32 v168, s8, v208
	v_lshl_add_u64 v[204:205], v[204:205], 0, s[78:79]
	s_mov_b32 m0, s9
	ds_read_b128 v[196:199], v168
	ds_read_b128 v[200:203], v168 offset:1024
	ds_read_b128 v[210:213], v168 offset:2048
	ds_read_b128 v[214:217], v168 offset:3072
	global_load_lds_dwordx4 v[204:205], off
	s_add_i32 m0, s9, 0x2000
	v_lshl_add_u64 v[204:205], v[218:219], 0, s[78:79]
	global_load_lds_dwordx4 v[204:205], off
	s_barrier
	s_waitcnt lgkmcnt(0)
	v_mfma_f32_16x16x32_bf16 v[108:111], v[196:199], v[144:147], v[108:111]
	v_mfma_f32_16x16x32_bf16 v[104:107], v[210:213], v[144:147], v[104:107]
	v_mfma_f32_16x16x32_bf16 v[92:95], v[196:199], v[152:155], v[92:95]
	v_mfma_f32_16x16x32_bf16 v[88:91], v[210:213], v[152:155], v[88:91]
	v_mfma_f32_16x16x32_bf16 v[76:79], v[196:199], v[180:183], v[76:79]
	v_mfma_f32_16x16x32_bf16 v[72:75], v[210:213], v[180:183], v[72:75]
	v_mfma_f32_16x16x32_bf16 v[68:71], v[196:199], v[188:191], v[68:71]
	v_mfma_f32_16x16x32_bf16 v[64:67], v[210:213], v[188:191], v[64:67]
	v_mfma_f32_16x16x32_bf16 v[108:111], v[200:203], v[148:151], v[108:111]
	v_mfma_f32_16x16x32_bf16 v[104:107], v[214:217], v[148:151], v[104:107]
	v_mfma_f32_16x16x32_bf16 v[92:95], v[200:203], v[156:159], v[92:95]
	v_mfma_f32_16x16x32_bf16 v[88:91], v[214:217], v[156:159], v[88:91]
	v_mfma_f32_16x16x32_bf16 v[76:79], v[200:203], v[184:187], v[76:79]
	v_mfma_f32_16x16x32_bf16 v[72:75], v[214:217], v[184:187], v[72:75]
	v_mfma_f32_16x16x32_bf16 v[68:71], v[200:203], v[192:195], v[68:71]
	v_mfma_f32_16x16x32_bf16 v[64:67], v[214:217], v[192:195], v[64:67]
	s_mov_b32 m0, s60
	v_lshl_add_u64 v[204:205], v[220:221], 0, s[78:79]
	s_barrier
	ds_read_b128 v[144:147], v209 offset:49152
	ds_read_b128 v[148:151], v209 offset:50176
	ds_read_b128 v[152:155], v209 offset:51200
	ds_read_b128 v[156:159], v209 offset:52224
	ds_read_b128 v[180:183], v209 offset:53248
	ds_read_b128 v[184:187], v209 offset:54272
	ds_read_b128 v[188:191], v209 offset:55296
	ds_read_b128 v[192:195], v209 offset:56320
	global_load_lds_dwordx4 v[204:205], off
	s_mov_b32 m0, s61
	v_lshl_add_u64 v[204:205], v[222:223], 0, s[78:79]
	global_load_lds_dwordx4 v[204:205], off
	s_barrier
	s_waitcnt lgkmcnt(0)
	v_mfma_f32_16x16x32_bf16 v[60:63], v[128:131], v[144:147], v[60:63]
	v_mfma_f32_16x16x32_bf16 v[56:59], v[136:139], v[144:147], v[56:59]
	v_mfma_f32_16x16x32_bf16 v[52:55], v[128:131], v[152:155], v[52:55]
	v_mfma_f32_16x16x32_bf16 v[48:51], v[136:139], v[152:155], v[48:51]
	v_mfma_f32_16x16x32_bf16 v[36:39], v[128:131], v[180:183], v[36:39]
	v_mfma_f32_16x16x32_bf16 v[32:35], v[136:139], v[180:183], v[32:35]
	v_mfma_f32_16x16x32_bf16 v[20:23], v[128:131], v[188:191], v[20:23]
	v_mfma_f32_16x16x32_bf16 v[16:19], v[136:139], v[188:191], v[16:19]
	v_mfma_f32_16x16x32_bf16 v[60:63], v[132:135], v[148:151], v[60:63]
	v_mfma_f32_16x16x32_bf16 v[56:59], v[140:143], v[148:151], v[56:59]
	v_mfma_f32_16x16x32_bf16 v[52:55], v[132:135], v[156:159], v[52:55]
	v_mfma_f32_16x16x32_bf16 v[48:51], v[140:143], v[156:159], v[48:51]
	v_mfma_f32_16x16x32_bf16 v[36:39], v[132:135], v[184:187], v[36:39]
	v_mfma_f32_16x16x32_bf16 v[32:35], v[140:143], v[184:187], v[32:35]
	v_mfma_f32_16x16x32_bf16 v[20:23], v[132:135], v[192:195], v[20:23]
	v_mfma_f32_16x16x32_bf16 v[16:19], v[140:143], v[192:195], v[16:19]
	s_barrier
	s_add_u32 s2, s2, 0x40080
	s_addc_u32 s3, s3, 0
	s_add_i32 s8, s8, s54
	s_mov_b32 m0, s8
	v_lshl_add_u64 v[128:129], s[2:3], 0, v[160:161]
	global_load_lds_dwordx4 v[128:129], off
	s_add_i32 m0, s8, 0x2000
	v_lshl_add_u64 v[128:129], s[2:3], 0, v[162:163]
	global_load_lds_dwordx4 v[128:129], off
	s_waitcnt vmcnt(6)
	s_barrier
	v_mfma_f32_16x16x32_bf16 v[44:47], v[196:199], v[144:147], v[44:47]
	v_mfma_f32_16x16x32_bf16 v[40:43], v[210:213], v[144:147], v[40:43]
	v_mfma_f32_16x16x32_bf16 v[28:31], v[196:199], v[152:155], v[28:31]
	v_mfma_f32_16x16x32_bf16 v[24:27], v[210:213], v[152:155], v[24:27]
	v_mfma_f32_16x16x32_bf16 v[12:15], v[196:199], v[180:183], v[12:15]
	v_mfma_f32_16x16x32_bf16 v[8:11], v[210:213], v[180:183], v[8:11]
	v_mfma_f32_16x16x32_bf16 v[4:7], v[196:199], v[188:191], v[4:7]
	v_mfma_f32_16x16x32_bf16 v[0:3], v[210:213], v[188:191], v[0:3]
	v_mfma_f32_16x16x32_bf16 v[44:47], v[200:203], v[148:151], v[44:47]
	v_mfma_f32_16x16x32_bf16 v[40:43], v[214:217], v[148:151], v[40:43]
	v_mfma_f32_16x16x32_bf16 v[28:31], v[200:203], v[156:159], v[28:31]
	v_mfma_f32_16x16x32_bf16 v[24:27], v[214:217], v[156:159], v[24:27]
	v_mfma_f32_16x16x32_bf16 v[12:15], v[200:203], v[184:187], v[12:15]
	v_mfma_f32_16x16x32_bf16 v[8:11], v[214:217], v[184:187], v[8:11]
	v_mfma_f32_16x16x32_bf16 v[4:7], v[200:203], v[192:195], v[4:7]
	v_mfma_f32_16x16x32_bf16 v[0:3], v[214:217], v[192:195], v[0:3]
	s_add_i32 s41, s41, 2
	s_add_u32 s6, s6, 0x100
	s_addc_u32 s7, s7, 0
	s_add_u32 s39, s39, 0x100
	s_addc_u32 s40, s40, 0
	s_cmp_gt_u32 s41, 13
	s_barrier
.LBB0_355:
	s_add_u32 s2, s6, 0xfffc0080
	s_addc_u32 s3, s7, -1
	s_add_i32 s64, 0, 0x10000
	v_add_u32_e32 v140, s64, v208
	ds_read_b128 v[128:131], v140
	ds_read_b128 v[132:135], v140 offset:1024
	ds_read_b128 v[136:139], v140 offset:2048
	ds_read_b128 v[140:143], v140 offset:3072
	s_cmp_eq_u32 s41, 12
	s_cselect_b32 s9, s1, s3
	s_cselect_b32 s8, s31, s2
	s_cselect_b32 s3, s29, s40
	s_cselect_b32 s2, s38, s39
	v_lshl_add_u64 v[196:197], s[6:7], 0, v[164:165]
	s_add_i32 m0, s21, 0xc000
	ds_read_b128 v[144:147], v209
	ds_read_b128 v[148:151], v209 offset:1024
	ds_read_b128 v[152:155], v209 offset:2048
	ds_read_b128 v[156:159], v209 offset:3072
	ds_read_b128 v[180:183], v209 offset:4096
	ds_read_b128 v[184:187], v209 offset:5120
	ds_read_b128 v[188:191], v209 offset:6144
	ds_read_b128 v[192:195], v209 offset:7168
	global_load_lds_dwordx4 v[196:197], off
	s_add_i32 m0, s21, 0xe000
	v_lshl_add_u64 v[196:197], s[6:7], 0, v[166:167]
	global_load_lds_dwordx4 v[196:197], off
	s_waitcnt lgkmcnt(8)
	s_barrier
	s_waitcnt lgkmcnt(0)
	v_mfma_f32_16x16x32_bf16 v[124:127], v[128:131], v[144:147], v[124:127]
	v_mfma_f32_16x16x32_bf16 v[120:123], v[136:139], v[144:147], v[120:123]
	v_mfma_f32_16x16x32_bf16 v[116:119], v[128:131], v[152:155], v[116:119]
	v_mfma_f32_16x16x32_bf16 v[112:115], v[136:139], v[152:155], v[112:115]
	v_mfma_f32_16x16x32_bf16 v[100:103], v[128:131], v[180:183], v[100:103]
	v_mfma_f32_16x16x32_bf16 v[96:99], v[136:139], v[180:183], v[96:99]
	v_mfma_f32_16x16x32_bf16 v[84:87], v[128:131], v[188:191], v[84:87]
	v_mfma_f32_16x16x32_bf16 v[80:83], v[136:139], v[188:191], v[80:83]
	v_mfma_f32_16x16x32_bf16 v[124:127], v[132:135], v[148:151], v[124:127]
	v_mfma_f32_16x16x32_bf16 v[120:123], v[140:143], v[148:151], v[120:123]
	v_mfma_f32_16x16x32_bf16 v[116:119], v[132:135], v[156:159], v[116:119]
	v_mfma_f32_16x16x32_bf16 v[112:115], v[140:143], v[156:159], v[112:115]
	v_mfma_f32_16x16x32_bf16 v[100:103], v[132:135], v[184:187], v[100:103]
	v_mfma_f32_16x16x32_bf16 v[96:99], v[140:143], v[184:187], v[96:99]
	v_mfma_f32_16x16x32_bf16 v[84:87], v[132:135], v[192:195], v[84:87]
	v_mfma_f32_16x16x32_bf16 v[80:83], v[140:143], v[192:195], v[80:83]
	s_barrier
	s_add_i32 s66, 0, 0x14000
	s_add_i32 s64, s64, s54
	v_add_u32_e32 v168, s66, v208
	v_lshl_add_u64 v[204:205], s[2:3], 0, v[160:161]
	s_mov_b32 m0, s64
	ds_read_b128 v[196:199], v168
	ds_read_b128 v[200:203], v168 offset:1024
	ds_read_b128 v[210:213], v168 offset:2048
	ds_read_b128 v[214:217], v168 offset:3072
	global_load_lds_dwordx4 v[204:205], off
	s_add_i32 m0, s64, 0x2000
	v_lshl_add_u64 v[218:219], s[2:3], 0, v[162:163]
	global_load_lds_dwordx4 v[218:219], off
	s_barrier
	s_waitcnt lgkmcnt(0)
	v_mfma_f32_16x16x32_bf16 v[108:111], v[196:199], v[144:147], v[108:111]
	v_mfma_f32_16x16x32_bf16 v[104:107], v[210:213], v[144:147], v[104:107]
	v_mfma_f32_16x16x32_bf16 v[92:95], v[196:199], v[152:155], v[92:95]
	v_mfma_f32_16x16x32_bf16 v[88:91], v[210:213], v[152:155], v[88:91]
	v_mfma_f32_16x16x32_bf16 v[76:79], v[196:199], v[180:183], v[76:79]
	v_mfma_f32_16x16x32_bf16 v[72:75], v[210:213], v[180:183], v[72:75]
	v_mfma_f32_16x16x32_bf16 v[68:71], v[196:199], v[188:191], v[68:71]
	v_mfma_f32_16x16x32_bf16 v[64:67], v[210:213], v[188:191], v[64:67]
	v_mfma_f32_16x16x32_bf16 v[108:111], v[200:203], v[148:151], v[108:111]
	v_mfma_f32_16x16x32_bf16 v[104:107], v[214:217], v[148:151], v[104:107]
	v_mfma_f32_16x16x32_bf16 v[92:95], v[200:203], v[156:159], v[92:95]
	v_mfma_f32_16x16x32_bf16 v[88:91], v[214:217], v[156:159], v[88:91]
	v_mfma_f32_16x16x32_bf16 v[76:79], v[200:203], v[184:187], v[76:79]
	v_mfma_f32_16x16x32_bf16 v[72:75], v[214:217], v[184:187], v[72:75]
	v_mfma_f32_16x16x32_bf16 v[68:71], v[200:203], v[192:195], v[68:71]
	v_mfma_f32_16x16x32_bf16 v[64:67], v[214:217], v[192:195], v[64:67]
	s_mov_b32 m0, s21
	v_lshl_add_u64 v[220:221], s[8:9], 0, v[160:161]
	s_barrier
	ds_read_b128 v[144:147], v209 offset:16384
	ds_read_b128 v[148:151], v209 offset:17408
	ds_read_b128 v[152:155], v209 offset:18432
	ds_read_b128 v[156:159], v209 offset:19456
	ds_read_b128 v[180:183], v209 offset:20480
	ds_read_b128 v[184:187], v209 offset:21504
	ds_read_b128 v[188:191], v209 offset:22528
	ds_read_b128 v[192:195], v209 offset:23552
	global_load_lds_dwordx4 v[220:221], off
	s_mov_b32 m0, s55
	v_lshl_add_u64 v[222:223], s[8:9], 0, v[162:163]
	global_load_lds_dwordx4 v[222:223], off
	s_barrier
	s_waitcnt lgkmcnt(0)
	v_mfma_f32_16x16x32_bf16 v[60:63], v[128:131], v[144:147], v[60:63]
	v_mfma_f32_16x16x32_bf16 v[56:59], v[136:139], v[144:147], v[56:59]
	v_mfma_f32_16x16x32_bf16 v[52:55], v[128:131], v[152:155], v[52:55]
	v_mfma_f32_16x16x32_bf16 v[48:51], v[136:139], v[152:155], v[48:51]
	v_mfma_f32_16x16x32_bf16 v[36:39], v[128:131], v[180:183], v[36:39]
	v_mfma_f32_16x16x32_bf16 v[32:35], v[136:139], v[180:183], v[32:35]
	v_mfma_f32_16x16x32_bf16 v[20:23], v[128:131], v[188:191], v[20:23]
	v_mfma_f32_16x16x32_bf16 v[16:19], v[136:139], v[188:191], v[16:19]
	v_mfma_f32_16x16x32_bf16 v[60:63], v[132:135], v[148:151], v[60:63]
	v_mfma_f32_16x16x32_bf16 v[56:59], v[140:143], v[148:151], v[56:59]
	v_mfma_f32_16x16x32_bf16 v[52:55], v[132:135], v[156:159], v[52:55]
	v_mfma_f32_16x16x32_bf16 v[48:51], v[140:143], v[156:159], v[48:51]
	v_mfma_f32_16x16x32_bf16 v[36:39], v[132:135], v[184:187], v[36:39]
	v_mfma_f32_16x16x32_bf16 v[32:35], v[140:143], v[184:187], v[32:35]
	v_mfma_f32_16x16x32_bf16 v[20:23], v[132:135], v[192:195], v[20:23]
	v_mfma_f32_16x16x32_bf16 v[16:19], v[140:143], v[192:195], v[16:19]
	s_barrier
	s_add_u32 s64, s2, 0x40000
	s_addc_u32 s65, s3, 0
	s_add_i32 s66, s66, s54
	s_mov_b32 m0, s66
	v_lshl_add_u64 v[128:129], s[64:65], 0, v[160:161]
	global_load_lds_dwordx4 v[128:129], off
	s_add_i32 m0, s66, 0x2000
	v_lshl_add_u64 v[128:129], s[64:65], 0, v[162:163]
	global_load_lds_dwordx4 v[128:129], off
	s_waitcnt vmcnt(6)
	s_barrier
	v_mfma_f32_16x16x32_bf16 v[44:47], v[196:199], v[144:147], v[44:47]
	v_mfma_f32_16x16x32_bf16 v[40:43], v[210:213], v[144:147], v[40:43]
	v_mfma_f32_16x16x32_bf16 v[28:31], v[196:199], v[152:155], v[28:31]
	v_mfma_f32_16x16x32_bf16 v[24:27], v[210:213], v[152:155], v[24:27]
	v_mfma_f32_16x16x32_bf16 v[12:15], v[196:199], v[180:183], v[12:15]
	v_mfma_f32_16x16x32_bf16 v[8:11], v[210:213], v[180:183], v[8:11]
	v_mfma_f32_16x16x32_bf16 v[4:7], v[196:199], v[188:191], v[4:7]
	v_mfma_f32_16x16x32_bf16 v[0:3], v[210:213], v[188:191], v[0:3]
	v_mfma_f32_16x16x32_bf16 v[44:47], v[200:203], v[148:151], v[44:47]
	v_mfma_f32_16x16x32_bf16 v[40:43], v[214:217], v[148:151], v[40:43]
	v_mfma_f32_16x16x32_bf16 v[28:31], v[200:203], v[156:159], v[28:31]
	v_mfma_f32_16x16x32_bf16 v[24:27], v[214:217], v[156:159], v[24:27]
	v_mfma_f32_16x16x32_bf16 v[12:15], v[200:203], v[184:187], v[12:15]
	v_mfma_f32_16x16x32_bf16 v[8:11], v[214:217], v[184:187], v[8:11]
	v_mfma_f32_16x16x32_bf16 v[4:7], v[200:203], v[192:195], v[4:7]
	v_mfma_f32_16x16x32_bf16 v[0:3], v[214:217], v[192:195], v[0:3]
	s_add_i32 s64, 0, 0x18000
	v_add_u32_e32 v140, s64, v208
	s_barrier
	ds_read_b128 v[128:131], v140
	ds_read_b128 v[132:135], v140 offset:1024
	ds_read_b128 v[136:139], v140 offset:2048
	ds_read_b128 v[140:143], v140 offset:3072
	s_add_u32 s8, s8, 0x40000
	s_addc_u32 s9, s9, 0
	s_mov_b32 m0, s56
	v_lshl_add_u64 v[196:197], s[8:9], 0, v[160:161]
	ds_read_b128 v[144:147], v209 offset:32768
	ds_read_b128 v[148:151], v209 offset:33792
	ds_read_b128 v[152:155], v209 offset:34816
	ds_read_b128 v[156:159], v209 offset:35840
	ds_read_b128 v[180:183], v209 offset:36864
	ds_read_b128 v[184:187], v209 offset:37888
	ds_read_b128 v[188:191], v209 offset:38912
	ds_read_b128 v[192:195], v209 offset:39936
	global_load_lds_dwordx4 v[196:197], off
	s_mov_b32 m0, s57
	v_lshl_add_u64 v[196:197], s[8:9], 0, v[162:163]
	global_load_lds_dwordx4 v[196:197], off
	s_waitcnt lgkmcnt(8)
	s_barrier
	s_waitcnt lgkmcnt(0)
	v_mfma_f32_16x16x32_bf16 v[124:127], v[128:131], v[144:147], v[124:127]
	v_mfma_f32_16x16x32_bf16 v[120:123], v[136:139], v[144:147], v[120:123]
	v_mfma_f32_16x16x32_bf16 v[116:119], v[128:131], v[152:155], v[116:119]
	v_mfma_f32_16x16x32_bf16 v[112:115], v[136:139], v[152:155], v[112:115]
	v_mfma_f32_16x16x32_bf16 v[100:103], v[128:131], v[180:183], v[100:103]
	v_mfma_f32_16x16x32_bf16 v[96:99], v[136:139], v[180:183], v[96:99]
	v_mfma_f32_16x16x32_bf16 v[84:87], v[128:131], v[188:191], v[84:87]
	v_mfma_f32_16x16x32_bf16 v[80:83], v[136:139], v[188:191], v[80:83]
	v_mfma_f32_16x16x32_bf16 v[124:127], v[132:135], v[148:151], v[124:127]
	v_mfma_f32_16x16x32_bf16 v[120:123], v[140:143], v[148:151], v[120:123]
	v_mfma_f32_16x16x32_bf16 v[116:119], v[132:135], v[156:159], v[116:119]
	v_mfma_f32_16x16x32_bf16 v[112:115], v[140:143], v[156:159], v[112:115]
	v_mfma_f32_16x16x32_bf16 v[100:103], v[132:135], v[184:187], v[100:103]
	v_mfma_f32_16x16x32_bf16 v[96:99], v[140:143], v[184:187], v[96:99]
	v_mfma_f32_16x16x32_bf16 v[84:87], v[132:135], v[192:195], v[84:87]
	v_mfma_f32_16x16x32_bf16 v[80:83], v[140:143], v[192:195], v[80:83]
	s_barrier
	s_add_i32 s8, 0, 0x1c000
	s_add_i32 s9, s64, s54
	v_add_u32_e32 v168, s8, v208
	v_lshl_add_u64 v[204:205], v[204:205], 0, s[78:79]
	s_mov_b32 m0, s9
	ds_read_b128 v[196:199], v168
	ds_read_b128 v[200:203], v168 offset:1024
	ds_read_b128 v[210:213], v168 offset:2048
	ds_read_b128 v[214:217], v168 offset:3072
	global_load_lds_dwordx4 v[204:205], off
	s_add_i32 m0, s9, 0x2000
	v_lshl_add_u64 v[204:205], v[218:219], 0, s[78:79]
	global_load_lds_dwordx4 v[204:205], off
	s_barrier
	s_waitcnt lgkmcnt(0)
	v_mfma_f32_16x16x32_bf16 v[108:111], v[196:199], v[144:147], v[108:111]
	v_mfma_f32_16x16x32_bf16 v[104:107], v[210:213], v[144:147], v[104:107]
	v_mfma_f32_16x16x32_bf16 v[92:95], v[196:199], v[152:155], v[92:95]
	v_mfma_f32_16x16x32_bf16 v[88:91], v[210:213], v[152:155], v[88:91]
	v_mfma_f32_16x16x32_bf16 v[76:79], v[196:199], v[180:183], v[76:79]
	v_mfma_f32_16x16x32_bf16 v[72:75], v[210:213], v[180:183], v[72:75]
	v_mfma_f32_16x16x32_bf16 v[68:71], v[196:199], v[188:191], v[68:71]
	v_mfma_f32_16x16x32_bf16 v[64:67], v[210:213], v[188:191], v[64:67]
	v_mfma_f32_16x16x32_bf16 v[108:111], v[200:203], v[148:151], v[108:111]
	v_mfma_f32_16x16x32_bf16 v[104:107], v[214:217], v[148:151], v[104:107]
	v_mfma_f32_16x16x32_bf16 v[92:95], v[200:203], v[156:159], v[92:95]
	v_mfma_f32_16x16x32_bf16 v[88:91], v[214:217], v[156:159], v[88:91]
	v_mfma_f32_16x16x32_bf16 v[76:79], v[200:203], v[184:187], v[76:79]
	v_mfma_f32_16x16x32_bf16 v[72:75], v[214:217], v[184:187], v[72:75]
	v_mfma_f32_16x16x32_bf16 v[68:71], v[200:203], v[192:195], v[68:71]
	v_mfma_f32_16x16x32_bf16 v[64:67], v[214:217], v[192:195], v[64:67]
	s_mov_b32 m0, s60
	v_lshl_add_u64 v[204:205], v[220:221], 0, s[78:79]
	s_barrier
	ds_read_b128 v[144:147], v209 offset:49152
	ds_read_b128 v[148:151], v209 offset:50176
	ds_read_b128 v[152:155], v209 offset:51200
	ds_read_b128 v[156:159], v209 offset:52224
	ds_read_b128 v[180:183], v209 offset:53248
	ds_read_b128 v[184:187], v209 offset:54272
	ds_read_b128 v[188:191], v209 offset:55296
	ds_read_b128 v[192:195], v209 offset:56320
	global_load_lds_dwordx4 v[204:205], off
	s_mov_b32 m0, s61
	v_lshl_add_u64 v[204:205], v[222:223], 0, s[78:79]
	global_load_lds_dwordx4 v[204:205], off
	s_barrier
	s_waitcnt lgkmcnt(0)
	v_mfma_f32_16x16x32_bf16 v[60:63], v[128:131], v[144:147], v[60:63]
	v_mfma_f32_16x16x32_bf16 v[56:59], v[136:139], v[144:147], v[56:59]
	v_mfma_f32_16x16x32_bf16 v[52:55], v[128:131], v[152:155], v[52:55]
	v_mfma_f32_16x16x32_bf16 v[48:51], v[136:139], v[152:155], v[48:51]
	v_mfma_f32_16x16x32_bf16 v[36:39], v[128:131], v[180:183], v[36:39]
	v_mfma_f32_16x16x32_bf16 v[32:35], v[136:139], v[180:183], v[32:35]
	v_mfma_f32_16x16x32_bf16 v[20:23], v[128:131], v[188:191], v[20:23]
	v_mfma_f32_16x16x32_bf16 v[16:19], v[136:139], v[188:191], v[16:19]
	v_mfma_f32_16x16x32_bf16 v[60:63], v[132:135], v[148:151], v[60:63]
	v_mfma_f32_16x16x32_bf16 v[56:59], v[140:143], v[148:151], v[56:59]
	v_mfma_f32_16x16x32_bf16 v[52:55], v[132:135], v[156:159], v[52:55]
	v_mfma_f32_16x16x32_bf16 v[48:51], v[140:143], v[156:159], v[48:51]
	v_mfma_f32_16x16x32_bf16 v[36:39], v[132:135], v[184:187], v[36:39]
	v_mfma_f32_16x16x32_bf16 v[32:35], v[140:143], v[184:187], v[32:35]
	v_mfma_f32_16x16x32_bf16 v[20:23], v[132:135], v[192:195], v[20:23]
	v_mfma_f32_16x16x32_bf16 v[16:19], v[140:143], v[192:195], v[16:19]
	s_barrier
	s_add_u32 s2, s2, 0x40080
	s_addc_u32 s3, s3, 0
	s_add_i32 s8, s8, s54
	s_mov_b32 m0, s8
	v_lshl_add_u64 v[128:129], s[2:3], 0, v[160:161]
	global_load_lds_dwordx4 v[128:129], off
	s_add_i32 m0, s8, 0x2000
	v_lshl_add_u64 v[128:129], s[2:3], 0, v[162:163]
	global_load_lds_dwordx4 v[128:129], off
	s_waitcnt vmcnt(6)
	s_barrier
	v_mfma_f32_16x16x32_bf16 v[44:47], v[196:199], v[144:147], v[44:47]
	v_mfma_f32_16x16x32_bf16 v[40:43], v[210:213], v[144:147], v[40:43]
	v_mfma_f32_16x16x32_bf16 v[28:31], v[196:199], v[152:155], v[28:31]
	v_mfma_f32_16x16x32_bf16 v[24:27], v[210:213], v[152:155], v[24:27]
	v_mfma_f32_16x16x32_bf16 v[12:15], v[196:199], v[180:183], v[12:15]
	v_mfma_f32_16x16x32_bf16 v[8:11], v[210:213], v[180:183], v[8:11]
	v_mfma_f32_16x16x32_bf16 v[4:7], v[196:199], v[188:191], v[4:7]
	v_mfma_f32_16x16x32_bf16 v[0:3], v[210:213], v[188:191], v[0:3]
	v_mfma_f32_16x16x32_bf16 v[44:47], v[200:203], v[148:151], v[44:47]
	v_mfma_f32_16x16x32_bf16 v[40:43], v[214:217], v[148:151], v[40:43]
	v_mfma_f32_16x16x32_bf16 v[28:31], v[200:203], v[156:159], v[28:31]
	v_mfma_f32_16x16x32_bf16 v[24:27], v[214:217], v[156:159], v[24:27]
	v_mfma_f32_16x16x32_bf16 v[12:15], v[200:203], v[184:187], v[12:15]
	v_mfma_f32_16x16x32_bf16 v[8:11], v[214:217], v[184:187], v[8:11]
	v_mfma_f32_16x16x32_bf16 v[4:7], v[200:203], v[192:195], v[4:7]
	v_mfma_f32_16x16x32_bf16 v[0:3], v[214:217], v[192:195], v[0:3]
	s_add_i32 s41, s41, 2
	s_add_u32 s6, s6, 0x100
	s_addc_u32 s7, s7, 0
	s_add_u32 s39, s39, 0x100
	s_addc_u32 s40, s40, 0
	s_cmp_gt_u32 s41, 13
	s_barrier
	s_cbranch_scc0 .LBB0_355
	s_lshl_b32 s1, s0, 8
	v_mov_b32_e32 v211, v206
	v_mov_b32_e32 v210, v207
	s_add_i32 s1, s1, s59
	s_cmp_lt_i32 s20, 3
	v_add_u32_e32 v180, s1, v211
	s_mov_b64 s[2:3], -1
	s_cbranch_scc0 .LBB0_490
	s_cmp_gt_i32 s0, 15
	s_cselect_b64 s[2:3], -1, 0
	s_cmp_lt_i32 s0, 16
	s_cselect_b64 s[38:39], -1, 0
	s_cmp_eq_u32 s20, 2
	s_cselect_b64 s[8:9], -1, 0
	s_cmp_lg_u32 s20, 2
	s_cselect_b64 s[0:1], -1, 0
	s_and_b64 s[40:41], s[8:9], s[22:23]
	v_lshlrev_b32_e32 v182, 2, v210
	s_mov_b64 s[6:7], -1
	s_and_b64 vcc, exec, s[40:41]
	v_ashrrev_i32_e32 v183, 31, v182
	s_cbranch_vccnz .LBB0_447
	s_and_b64 s[6:7], s[8:9], exec
	s_cselect_b32 s6, s46, s44
	s_cselect_b32 s7, s47, s45
	v_mov_b32_e32 v128, s7
	v_mov_b32_e32 v129, s6
	v_lshl_add_u64 v[128:129], v[182:183], 2, v[128:129]
	global_load_dwordx4 v[140:143], v[128:129], off
	global_load_dwordx4 v[136:139], v[128:129], off offset:64
	global_load_dwordx4 v[132:135], v[128:129], off offset:128
	s_nop 0
	global_load_dwordx4 v[128:131], v[128:129], off offset:192
	v_mul_f32_e32 v144, v125, v125
	v_mul_f32_e32 v145, v127, v127
	v_fmac_f32_e32 v144, v124, v124
	v_fmac_f32_e32 v145, v126, v126
	v_add_f32_e32 v144, v144, v145
	v_mul_f32_e32 v145, v121, v121
	v_mul_f32_e32 v146, v123, v123
	v_fmac_f32_e32 v145, v120, v120
	v_fmac_f32_e32 v146, v122, v122
	v_add_f32_e32 v145, v145, v146
	v_add_f32_e32 v144, v144, v145
	v_mul_f32_e32 v145, v109, v109
	v_mul_f32_e32 v146, v111, v111
	v_fmac_f32_e32 v145, v108, v108
	v_fmac_f32_e32 v146, v110, v110
	v_add_f32_e32 v145, v145, v146
	v_add_f32_e32 v144, v144, v145
	v_mul_f32_e32 v145, v105, v105
	v_mul_f32_e32 v146, v107, v107
	v_fmac_f32_e32 v145, v104, v104
	v_fmac_f32_e32 v146, v106, v106
	v_add_f32_e32 v145, v145, v146
	v_add_f32_e32 v144, v144, v145
	v_mov_b32_e32 v145, v144
	s_nop 1
	v_permlane16_swap_b32_e32 v144, v145
	v_add_f32_e32 v144, v144, v145
	v_mov_b32_e32 v145, v144
	s_nop 1
	v_permlane32_swap_b32_e32 v144, v145
	v_add_f32_e32 v144, v144, v145
	v_fmamk_f32 v144, v144, 0x3c800000, v225
	v_cmp_gt_f32_e32 vcc, s93, v144
	v_mul_f32_e32 v145, 0x4b800000, v144
	v_and_b32_e32 v202, 63, v211
	v_cndmask_b32_e32 v144, v144, v145, vcc
	v_rsq_f32_e32 v144, v144
	v_cndmask_b32_e64 v168, 0, 1, s[2:3]
	v_cmp_ne_u32_e64 s[6:7], 1, v168
	v_lshlrev_b32_e32 v186, 7, v202
	v_mul_f32_e32 v145, 0x45800000, v144
	v_cndmask_b32_e32 v152, v144, v145, vcc
	v_pk_mul_f32 v[144:145], v[124:125], v[152:153] op_sel_hi:[1,0]
	v_pk_mul_f32 v[146:147], v[126:127], v[152:153] op_sel_hi:[1,0]
	v_pk_mul_f32 v[148:149], v[108:109], v[152:153] op_sel_hi:[1,0]
	v_pk_mul_f32 v[150:151], v[110:111], v[152:153] op_sel_hi:[1,0]
	v_pk_mul_f32 v[184:185], v[104:105], v[152:153] op_sel_hi:[1,0]
	s_andn2_b64 vcc, exec, s[2:3]
	s_waitcnt vmcnt(0)
	v_pk_mul_f32 v[158:159], v[142:143], v[146:147]
	v_pk_mul_f32 v[156:157], v[140:141], v[144:145]
	v_pk_mul_f32 v[144:145], v[120:121], v[152:153] op_sel_hi:[1,0]
	v_pk_mul_f32 v[146:147], v[122:123], v[152:153] op_sel_hi:[1,0]
	v_pk_mul_f32 v[152:153], v[106:107], v[152:153] op_sel_hi:[1,0]
	v_pk_mul_f32 v[146:147], v[138:139], v[146:147]
	v_pk_mul_f32 v[144:145], v[136:137], v[144:145]
	v_pk_mul_f32 v[150:151], v[134:135], v[150:151]
	v_pk_mul_f32 v[148:149], v[132:133], v[148:149]
	v_pk_mul_f32 v[154:155], v[130:131], v[152:153]
	v_pk_mul_f32 v[152:153], v[128:129], v[184:185]
	v_lshl_add_u64 v[184:185], v[182:183], 3, s[18:19]
	s_cbranch_vccnz .LBB0_360
	v_lshlrev_b32_e32 v168, 1, v180
	v_and_b32_e32 v168, 0xf80, v168
	v_lshl_add_u64 v[188:189], v[184:185], 0, v[168:169]
	global_load_dwordx4 v[190:193], v[188:189], off offset:16
	global_load_dwordx4 v[194:197], v[188:189], off
	v_mov_b32_e32 v187, v169
	s_waitcnt vmcnt(0)
	v_mul_f32_e32 v198, v158, v190
	v_mov_b32_e32 v188, v194
	v_mov_b32_e32 v189, v196
	v_mov_b32_e32 v196, v195
	v_mul_f32_e32 v200, v146, v191
	v_mul_f32_e32 v204, v146, v190
	v_mul_f32_e32 v212, v158, v191
	v_mov_b32_e32 v146, v159
	v_mov_b32_e32 v158, v147
	v_pk_mul_f32 v[194:195], v[144:145], v[196:197]
	v_pk_mul_f32 v[144:145], v[144:145], v[188:189]
	v_pk_mul_f32 v[190:191], v[146:147], v[192:193]
	v_pk_mul_f32 v[146:147], v[158:159], v[192:193]
	v_lshl_add_u64 v[192:193], v[184:185], 0, v[186:187]
	v_mov_b32_e32 v199, v190
	v_mov_b32_e32 v201, v191
	v_pk_fma_f32 v[190:191], v[156:157], v[188:189], v[194:195] neg_lo:[0,0,1] neg_hi:[0,0,1]
	v_pk_fma_f32 v[144:145], v[156:157], v[196:197], v[144:145]
	global_load_dwordx4 v[156:159], v[192:193], off offset:16
	s_nop 0
	global_load_dwordx4 v[192:195], v[192:193], off
	v_pk_add_f32 v[188:189], v[198:199], v[200:201] neg_lo:[0,1] neg_hi:[0,1]
	v_mov_b32_e32 v213, v147
	v_mov_b32_e32 v205, v146
	v_pk_add_f32 v[146:147], v[212:213], v[204:205]
	s_waitcnt vmcnt(0)
	v_mul_f32_e32 v198, v150, v156
	v_mul_f32_e32 v200, v154, v157
	v_mul_f32_e32 v156, v154, v156
	v_mov_b32_e32 v154, v151
	v_mov_b32_e32 v197, v194
	v_mov_b32_e32 v194, v193
	v_mul_f32_e32 v204, v150, v157
	v_pk_mul_f32 v[212:213], v[154:155], v[158:159]
	v_mov_b32_e32 v150, v155
	v_mov_b32_e32 v196, v192
	v_pk_mul_f32 v[192:193], v[152:153], v[194:195]
	v_mov_b32_e32 v199, v212
	v_mov_b32_e32 v201, v213
	v_pk_mul_f32 v[150:151], v[150:151], v[158:159]
	v_pk_mul_f32 v[152:153], v[152:153], v[196:197]
	v_pk_fma_f32 v[192:193], v[148:149], v[196:197], v[192:193] neg_lo:[0,0,1] neg_hi:[0,0,1]
	v_pk_add_f32 v[196:197], v[198:199], v[200:201] neg_lo:[0,1] neg_hi:[0,1]
	v_mov_b32_e32 v205, v151
	v_mov_b32_e32 v157, v150
	v_pk_fma_f32 v[152:153], v[148:149], v[194:195], v[152:153]
	v_pk_add_f32 v[154:155], v[204:205], v[156:157]
	v_mov_b32_e32 v148, v192
	v_mov_b32_e32 v149, v193
	v_mov_b32_e32 v150, v196
	v_mov_b32_e32 v151, v197
	v_mov_b32_e32 v156, v190
	v_mov_b32_e32 v157, v191
	v_mov_b32_e32 v158, v188
	v_mov_b32_e32 v159, v189

.LBB0_677:
	s_ashr_i32 s23, s22, 31
	v_cmp_lt_i64_e32 vcc, s[24:25], v[174:175]
	s_lshl_b64 s[24:25], s[22:23], 19
	s_add_u32 s24, s36, s24
	s_addc_u32 s25, s37, s25
	s_and_b64 s[26:27], vcc, exec
	s_cselect_b32 s1, s25, s9
	s_cselect_b32 s7, s24, s8
	s_ashr_i32 s21, s20, 31
	s_lshl_b64 s[26:27], s[20:21], 19
	s_add_u32 s26, s38, s26
	s_addc_u32 s27, s39, s27
	s_and_b64 s[28:29], vcc, exec
	s_cselect_b32 s21, s27, s3
	s_cselect_b32 s23, s26, s2
	s_add_u32 s8, s8, 0x40080
	s_addc_u32 s9, s9, 0
	s_add_u32 s56, s2, 0x100
	s_addc_u32 s57, s3, 0
	s_mov_b32 s58, -2
	s_add_u32 s2, s8, 0xfffc0080
	s_addc_u32 s3, s9, -1
	s_add_i32 s59, 0, 0x10000
	v_add_u32_e32 v68, s59, v206
	ds_read_b128 v[48:51], v68
	ds_read_b128 v[52:55], v68 offset:1024
	ds_read_b128 v[60:63], v68 offset:2048
	ds_read_b128 v[68:71], v68 offset:3072
	s_cmp_eq_u32 s58, 12
	s_cselect_b32 s29, s1, s3
	s_cselect_b32 s28, s7, s2
	s_cselect_b32 s3, s21, s57
	s_cselect_b32 s2, s23, s56
	v_lshl_add_u64 v[200:201], s[8:9], 0, v[188:189]
	s_add_i32 m0, s41, 0xc000
	ds_read_b128 v[72:75], v207
	ds_read_b128 v[76:79], v207 offset:1024
	ds_read_b128 v[80:83], v207 offset:2048
	ds_read_b128 v[84:87], v207 offset:3072
	ds_read_b128 v[160:163], v207 offset:4096
	ds_read_b128 v[164:167], v207 offset:5120
	ds_read_b128 v[192:195], v207 offset:6144
	ds_read_b128 v[196:199], v207 offset:7168
	global_load_lds_dwordx4 v[200:201], off
	s_add_i32 m0, s41, 0xe000
	v_lshl_add_u64 v[200:201], s[8:9], 0, v[190:191]
	global_load_lds_dwordx4 v[200:201], off
	s_waitcnt lgkmcnt(8)
	s_barrier
	s_waitcnt lgkmcnt(0)
	v_mfma_f32_16x16x32_bf16 v[156:159], v[48:51], v[72:75], 0
	v_mfma_f32_16x16x32_bf16 v[152:155], v[60:63], v[72:75], 0
	v_mfma_f32_16x16x32_bf16 v[140:143], v[48:51], v[80:83], 0
	v_mfma_f32_16x16x32_bf16 v[136:139], v[60:63], v[80:83], 0
	v_mfma_f32_16x16x32_bf16 v[124:127], v[48:51], v[160:163], 0
	v_mfma_f32_16x16x32_bf16 v[120:123], v[60:63], v[160:163], 0
	v_mfma_f32_16x16x32_bf16 v[108:111], v[48:51], v[192:195], 0
	v_mfma_f32_16x16x32_bf16 v[104:107], v[60:63], v[192:195], 0
	v_mfma_f32_16x16x32_bf16 v[156:159], v[52:55], v[76:79], v[156:159]
	v_mfma_f32_16x16x32_bf16 v[152:155], v[68:71], v[76:79], v[152:155]
	v_mfma_f32_16x16x32_bf16 v[140:143], v[52:55], v[84:87], v[140:143]
	v_mfma_f32_16x16x32_bf16 v[136:139], v[68:71], v[84:87], v[136:139]
	v_mfma_f32_16x16x32_bf16 v[124:127], v[52:55], v[164:167], v[124:127]
	v_mfma_f32_16x16x32_bf16 v[120:123], v[68:71], v[164:167], v[120:123]
	v_mfma_f32_16x16x32_bf16 v[108:111], v[52:55], v[196:199], v[108:111]
	v_mfma_f32_16x16x32_bf16 v[104:107], v[68:71], v[196:199], v[104:107]
	s_barrier
	s_add_i32 s62, 0, 0x14000
	s_add_i32 s59, s59, s40
	v_add_u32_e32 v168, s62, v206
	v_lshl_add_u64 v[240:241], s[2:3], 0, v[182:183]
	s_mov_b32 m0, s59
	ds_read_b128 v[200:203], v168
	ds_read_b128 v[208:211], v168 offset:1024
	ds_read_b128 v[212:215], v168 offset:2048
	ds_read_b128 v[216:219], v168 offset:3072
	global_load_lds_dwordx4 v[240:241], off
	s_add_i32 m0, s59, 0x2000
	v_lshl_add_u64 v[242:243], s[2:3], 0, v[186:187]
	global_load_lds_dwordx4 v[242:243], off
	s_barrier
	s_waitcnt lgkmcnt(0)
	v_mfma_f32_16x16x32_bf16 v[148:151], v[200:203], v[72:75], 0
	v_mfma_f32_16x16x32_bf16 v[72:75], v[212:215], v[72:75], 0
	v_mfma_f32_16x16x32_bf16 v[148:151], v[208:211], v[76:79], v[148:151]
	v_mfma_f32_16x16x32_bf16 v[72:75], v[216:219], v[76:79], v[72:75]
	v_mfma_f32_16x16x32_bf16 v[76:79], v[200:203], v[80:83], 0
	v_mfma_f32_16x16x32_bf16 v[80:83], v[212:215], v[80:83], 0
	v_mfma_f32_16x16x32_bf16 v[112:115], v[212:215], v[160:163], 0
	v_mfma_f32_16x16x32_bf16 v[100:103], v[200:203], v[192:195], 0
	v_mfma_f32_16x16x32_bf16 v[96:99], v[212:215], v[192:195], 0
	v_mfma_f32_16x16x32_bf16 v[76:79], v[208:211], v[84:87], v[76:79]
	v_mfma_f32_16x16x32_bf16 v[80:83], v[216:219], v[84:87], v[80:83]
	v_mfma_f32_16x16x32_bf16 v[84:87], v[200:203], v[160:163], 0
	v_mfma_f32_16x16x32_bf16 v[112:115], v[216:219], v[164:167], v[112:115]
	v_mfma_f32_16x16x32_bf16 v[100:103], v[208:211], v[196:199], v[100:103]
	v_mfma_f32_16x16x32_bf16 v[96:99], v[216:219], v[196:199], v[96:99]
	v_mfma_f32_16x16x32_bf16 v[84:87], v[208:211], v[164:167], v[84:87]
	s_mov_b32 m0, s41
	v_lshl_add_u64 v[244:245], s[28:29], 0, v[180:181]
	s_barrier
	ds_read_b128 v[116:119], v207 offset:16384
	ds_read_b128 v[128:131], v207 offset:17408
	ds_read_b128 v[132:135], v207 offset:18432
	ds_read_b128 v[144:147], v207 offset:19456
	ds_read_b128 v[160:163], v207 offset:20480
	ds_read_b128 v[164:167], v207 offset:21504
	ds_read_b128 v[192:195], v207 offset:22528
	ds_read_b128 v[196:199], v207 offset:23552
	global_load_lds_dwordx4 v[244:245], off
	s_mov_b32 m0, s42
	v_lshl_add_u64 v[246:247], s[28:29], 0, v[184:185]
	global_load_lds_dwordx4 v[246:247], off
	s_barrier
	s_waitcnt lgkmcnt(0)
	v_mfma_f32_16x16x32_bf16 v[92:95], v[48:51], v[116:119], 0
	v_mfma_f32_16x16x32_bf16 v[88:91], v[60:63], v[116:119], 0
	v_mfma_f32_16x16x32_bf16 v[44:47], v[48:51], v[132:135], 0
	v_mfma_f32_16x16x32_bf16 v[40:43], v[60:63], v[132:135], 0
	v_mfma_f32_16x16x32_bf16 v[28:31], v[48:51], v[160:163], 0
	v_mfma_f32_16x16x32_bf16 v[24:27], v[60:63], v[160:163], 0
	v_mfma_f32_16x16x32_bf16 v[12:15], v[48:51], v[192:195], 0
	v_mfma_f32_16x16x32_bf16 v[8:11], v[60:63], v[192:195], 0
	v_mfma_f32_16x16x32_bf16 v[92:95], v[52:55], v[128:131], v[92:95]
	v_mfma_f32_16x16x32_bf16 v[88:91], v[68:71], v[128:131], v[88:91]
	v_mfma_f32_16x16x32_bf16 v[44:47], v[52:55], v[144:147], v[44:47]
	v_mfma_f32_16x16x32_bf16 v[40:43], v[68:71], v[144:147], v[40:43]
	v_mfma_f32_16x16x32_bf16 v[28:31], v[52:55], v[164:167], v[28:31]
	v_mfma_f32_16x16x32_bf16 v[24:27], v[68:71], v[164:167], v[24:27]
	v_mfma_f32_16x16x32_bf16 v[12:15], v[52:55], v[196:199], v[12:15]
	v_mfma_f32_16x16x32_bf16 v[8:11], v[68:71], v[196:199], v[8:11]
	s_barrier
	s_add_u32 s60, s2, 0x40000
	s_addc_u32 s61, s3, 0
	s_add_i32 s59, s62, s40
	s_mov_b32 m0, s59
	v_lshl_add_u64 v[48:49], s[60:61], 0, v[182:183]
	global_load_lds_dwordx4 v[48:49], off
	s_add_i32 m0, s59, 0x2000
	v_lshl_add_u64 v[48:49], s[60:61], 0, v[186:187]
	global_load_lds_dwordx4 v[48:49], off
	s_waitcnt vmcnt(6)
	s_barrier
	v_mfma_f32_16x16x32_bf16 v[36:39], v[200:203], v[132:135], 0
	v_mfma_f32_16x16x32_bf16 v[32:35], v[212:215], v[132:135], 0
	v_mfma_f32_16x16x32_bf16 v[20:23], v[200:203], v[160:163], 0
	v_mfma_f32_16x16x32_bf16 v[16:19], v[212:215], v[160:163], 0
	v_mfma_f32_16x16x32_bf16 v[4:7], v[200:203], v[192:195], 0
	v_mfma_f32_16x16x32_bf16 v[0:3], v[212:215], v[192:195], 0
	v_mfma_f32_16x16x32_bf16 v[48:51], v[200:203], v[116:119], 0
	v_mfma_f32_16x16x32_bf16 v[52:55], v[212:215], v[116:119], 0
	v_mfma_f32_16x16x32_bf16 v[36:39], v[208:211], v[144:147], v[36:39]
	v_mfma_f32_16x16x32_bf16 v[32:35], v[216:219], v[144:147], v[32:35]
	v_mfma_f32_16x16x32_bf16 v[20:23], v[208:211], v[164:167], v[20:23]
	v_mfma_f32_16x16x32_bf16 v[16:19], v[216:219], v[164:167], v[16:19]
	v_mfma_f32_16x16x32_bf16 v[4:7], v[208:211], v[196:199], v[4:7]
	v_mfma_f32_16x16x32_bf16 v[0:3], v[216:219], v[196:199], v[0:3]
	v_mfma_f32_16x16x32_bf16 v[48:51], v[208:211], v[128:131], v[48:51]
	v_mfma_f32_16x16x32_bf16 v[52:55], v[216:219], v[128:131], v[52:55]
	s_add_i32 s59, 0, 0x18000
	v_add_u32_e32 v68, s59, v206
	s_barrier
	ds_read_b128 v[56:59], v68
	ds_read_b128 v[60:63], v68 offset:1024
	ds_read_b128 v[64:67], v68 offset:2048
	ds_read_b128 v[68:71], v68 offset:3072
	s_add_u32 s28, s28, 0x40000
	s_addc_u32 s29, s29, 0
	s_mov_b32 m0, s43
	v_lshl_add_u64 v[132:133], s[28:29], 0, v[180:181]
	ds_read_b128 v[116:119], v207 offset:32768
	ds_read_b128 v[128:131], v207 offset:33792
	ds_read_b128 v[160:163], v207 offset:34816
	ds_read_b128 v[164:167], v207 offset:35840
	ds_read_b128 v[192:195], v207 offset:36864
	ds_read_b128 v[196:199], v207 offset:37888
	ds_read_b128 v[200:203], v207 offset:38912
	ds_read_b128 v[208:211], v207 offset:39936
	global_load_lds_dwordx4 v[132:133], off
	s_mov_b32 m0, s44
	v_lshl_add_u64 v[132:133], s[28:29], 0, v[184:185]
	global_load_lds_dwordx4 v[132:133], off
	s_waitcnt lgkmcnt(8)
	s_barrier
	s_waitcnt lgkmcnt(0)
	v_mfma_f32_16x16x32_bf16 v[132:135], v[56:59], v[116:119], v[156:159]
	v_mfma_f32_16x16x32_bf16 v[156:159], v[60:63], v[128:131], v[132:135]
	v_mfma_f32_16x16x32_bf16 v[132:135], v[64:67], v[116:119], v[152:155]
	v_mfma_f32_16x16x32_bf16 v[152:155], v[68:71], v[128:131], v[132:135]
	v_mfma_f32_16x16x32_bf16 v[132:135], v[56:59], v[160:163], v[140:143]
	v_mfma_f32_16x16x32_bf16 v[140:143], v[60:63], v[164:167], v[132:135]
	v_mfma_f32_16x16x32_bf16 v[132:135], v[64:67], v[160:163], v[136:139]
	v_mfma_f32_16x16x32_bf16 v[124:127], v[56:59], v[192:195], v[124:127]
	v_mfma_f32_16x16x32_bf16 v[120:123], v[64:67], v[192:195], v[120:123]
	v_mfma_f32_16x16x32_bf16 v[108:111], v[56:59], v[200:203], v[108:111]
	v_mfma_f32_16x16x32_bf16 v[104:107], v[64:67], v[200:203], v[104:107]
	v_mfma_f32_16x16x32_bf16 v[136:139], v[68:71], v[164:167], v[132:135]
	v_mfma_f32_16x16x32_bf16 v[124:127], v[60:63], v[196:199], v[124:127]
	v_mfma_f32_16x16x32_bf16 v[120:123], v[68:71], v[196:199], v[120:123]
	v_mfma_f32_16x16x32_bf16 v[108:111], v[60:63], v[208:211], v[108:111]
	v_mfma_f32_16x16x32_bf16 v[104:107], v[68:71], v[208:211], v[104:107]
	s_barrier
	s_add_i32 s28, 0, 0x1c000
	v_add_u32_e32 v132, s28, v206
	s_add_i32 s29, s59, s40
	ds_read_b128 v[212:215], v132
	ds_read_b128 v[216:219], v132 offset:1024
	ds_read_b128 v[220:223], v132 offset:2048
	ds_read_b128 v[236:239], v132 offset:3072
	s_mov_b32 m0, s29
	v_lshl_add_u64 v[132:133], v[240:241], 0, s[78:79]
	global_load_lds_dwordx4 v[132:133], off
	s_add_i32 m0, s29, 0x2000
	v_lshl_add_u64 v[132:133], v[242:243], 0, s[78:79]
	global_load_lds_dwordx4 v[132:133], off
	s_barrier
	s_waitcnt lgkmcnt(0)
	v_mfma_f32_16x16x32_bf16 v[72:75], v[220:223], v[116:119], v[72:75]
	v_mfma_f32_16x16x32_bf16 v[132:135], v[212:215], v[116:119], v[148:151]
	v_mfma_f32_16x16x32_bf16 v[144:147], v[236:239], v[128:131], v[72:75]
	v_mfma_f32_16x16x32_bf16 v[72:75], v[212:215], v[160:163], v[76:79]
	v_mfma_f32_16x16x32_bf16 v[148:151], v[216:219], v[128:131], v[132:135]
	v_mfma_f32_16x16x32_bf16 v[132:135], v[216:219], v[164:167], v[72:75]
	v_mfma_f32_16x16x32_bf16 v[72:75], v[220:223], v[160:163], v[80:83]
	v_mfma_f32_16x16x32_bf16 v[128:131], v[236:239], v[164:167], v[72:75]
	v_mfma_f32_16x16x32_bf16 v[72:75], v[212:215], v[192:195], v[84:87]
	v_mfma_f32_16x16x32_bf16 v[116:119], v[216:219], v[196:199], v[72:75]
	v_mfma_f32_16x16x32_bf16 v[72:75], v[220:223], v[192:195], v[112:115]
	v_mfma_f32_16x16x32_bf16 v[112:115], v[236:239], v[196:199], v[72:75]
	v_mfma_f32_16x16x32_bf16 v[72:75], v[212:215], v[200:203], v[100:103]
	v_mfma_f32_16x16x32_bf16 v[100:103], v[216:219], v[208:211], v[72:75]
	v_mfma_f32_16x16x32_bf16 v[72:75], v[220:223], v[200:203], v[96:99]
	v_mfma_f32_16x16x32_bf16 v[96:99], v[236:239], v[208:211], v[72:75]
	s_mov_b32 m0, s53
	v_lshl_add_u64 v[200:201], v[244:245], 0, s[78:79]
	s_barrier
	s_nop 2
	ds_read_b128 v[72:75], v207 offset:49152
	ds_read_b128 v[76:79], v207 offset:50176
	ds_read_b128 v[80:83], v207 offset:51200
	ds_read_b128 v[84:87], v207 offset:52224
	ds_read_b128 v[160:163], v207 offset:53248
	ds_read_b128 v[164:167], v207 offset:54272
	ds_read_b128 v[192:195], v207 offset:55296
	ds_read_b128 v[196:199], v207 offset:56320
	global_load_lds_dwordx4 v[200:201], off
	s_mov_b32 m0, s54
	v_lshl_add_u64 v[200:201], v[246:247], 0, s[78:79]
	global_load_lds_dwordx4 v[200:201], off
	s_barrier
	s_waitcnt lgkmcnt(0)
	v_mfma_f32_16x16x32_bf16 v[92:95], v[56:59], v[72:75], v[92:95]
	v_mfma_f32_16x16x32_bf16 v[88:91], v[64:67], v[72:75], v[88:91]
	v_mfma_f32_16x16x32_bf16 v[44:47], v[56:59], v[80:83], v[44:47]
	v_mfma_f32_16x16x32_bf16 v[40:43], v[64:67], v[80:83], v[40:43]
	v_mfma_f32_16x16x32_bf16 v[28:31], v[56:59], v[160:163], v[28:31]
	v_mfma_f32_16x16x32_bf16 v[24:27], v[64:67], v[160:163], v[24:27]
	v_mfma_f32_16x16x32_bf16 v[12:15], v[56:59], v[192:195], v[12:15]
	v_mfma_f32_16x16x32_bf16 v[8:11], v[64:67], v[192:195], v[8:11]
	v_mfma_f32_16x16x32_bf16 v[92:95], v[60:63], v[76:79], v[92:95]
	v_mfma_f32_16x16x32_bf16 v[88:91], v[68:71], v[76:79], v[88:91]
	v_mfma_f32_16x16x32_bf16 v[44:47], v[60:63], v[84:87], v[44:47]
	v_mfma_f32_16x16x32_bf16 v[40:43], v[68:71], v[84:87], v[40:43]
	v_mfma_f32_16x16x32_bf16 v[28:31], v[60:63], v[164:167], v[28:31]
	v_mfma_f32_16x16x32_bf16 v[24:27], v[68:71], v[164:167], v[24:27]
	v_mfma_f32_16x16x32_bf16 v[12:15], v[60:63], v[196:199], v[12:15]
	v_mfma_f32_16x16x32_bf16 v[8:11], v[68:71], v[196:199], v[8:11]
	s_barrier
	s_add_u32 s2, s2, 0x40080
	s_addc_u32 s3, s3, 0
	s_add_i32 s28, s28, s40
	s_mov_b32 m0, s28
	v_lshl_add_u64 v[56:57], s[2:3], 0, v[182:183]
	global_load_lds_dwordx4 v[56:57], off
	s_add_i32 m0, s28, 0x2000
	v_lshl_add_u64 v[56:57], s[2:3], 0, v[186:187]
	global_load_lds_dwordx4 v[56:57], off
	s_waitcnt vmcnt(6)
	s_barrier
	v_mfma_f32_16x16x32_bf16 v[48:51], v[212:215], v[72:75], v[48:51]
	v_mfma_f32_16x16x32_bf16 v[64:67], v[216:219], v[76:79], v[48:51]
	v_mfma_f32_16x16x32_bf16 v[48:51], v[220:223], v[72:75], v[52:55]
	v_mfma_f32_16x16x32_bf16 v[36:39], v[212:215], v[80:83], v[36:39]
	v_mfma_f32_16x16x32_bf16 v[32:35], v[220:223], v[80:83], v[32:35]
	v_mfma_f32_16x16x32_bf16 v[20:23], v[212:215], v[160:163], v[20:23]
	v_mfma_f32_16x16x32_bf16 v[16:19], v[220:223], v[160:163], v[16:19]
	v_mfma_f32_16x16x32_bf16 v[4:7], v[212:215], v[192:195], v[4:7]
	v_mfma_f32_16x16x32_bf16 v[0:3], v[220:223], v[192:195], v[0:3]
	v_mfma_f32_16x16x32_bf16 v[56:59], v[236:239], v[76:79], v[48:51]
	v_mfma_f32_16x16x32_bf16 v[36:39], v[216:219], v[84:87], v[36:39]
	v_mfma_f32_16x16x32_bf16 v[32:35], v[236:239], v[84:87], v[32:35]
	v_mfma_f32_16x16x32_bf16 v[20:23], v[216:219], v[164:167], v[20:23]
	v_mfma_f32_16x16x32_bf16 v[16:19], v[236:239], v[164:167], v[16:19]
	v_mfma_f32_16x16x32_bf16 v[4:7], v[216:219], v[196:199], v[4:7]
	v_mfma_f32_16x16x32_bf16 v[0:3], v[236:239], v[196:199], v[0:3]
	s_add_i32 s58, s58, 2
	s_add_u32 s8, s8, 0x100
	s_addc_u32 s9, s9, 0
	s_add_u32 s56, s56, 0x100
	s_addc_u32 s57, s57, 0
	s_cmp_gt_u32 s58, 13
	s_barrier
.LBB0_678:
	s_add_u32 s2, s8, 0xfffc0080
	s_addc_u32 s3, s9, -1
	s_add_i32 s59, 0, 0x10000
	v_add_u32_e32 v68, s59, v206
	ds_read_b128 v[48:51], v68
	ds_read_b128 v[52:55], v68 offset:1024
	ds_read_b128 v[60:63], v68 offset:2048
	ds_read_b128 v[68:71], v68 offset:3072
	s_cmp_eq_u32 s58, 12
	s_cselect_b32 s29, s1, s3
	s_cselect_b32 s28, s7, s2
	s_cselect_b32 s3, s21, s57
	s_cselect_b32 s2, s23, s56
	v_lshl_add_u64 v[200:201], s[8:9], 0, v[188:189]
	s_add_i32 m0, s41, 0xc000
	ds_read_b128 v[72:75], v207
	ds_read_b128 v[76:79], v207 offset:1024
	ds_read_b128 v[80:83], v207 offset:2048
	ds_read_b128 v[84:87], v207 offset:3072
	ds_read_b128 v[160:163], v207 offset:4096
	ds_read_b128 v[164:167], v207 offset:5120
	ds_read_b128 v[192:195], v207 offset:6144
	ds_read_b128 v[196:199], v207 offset:7168
	global_load_lds_dwordx4 v[200:201], off
	s_add_i32 m0, s41, 0xe000
	v_lshl_add_u64 v[200:201], s[8:9], 0, v[190:191]
	global_load_lds_dwordx4 v[200:201], off
	s_waitcnt lgkmcnt(8)
	s_barrier
	s_waitcnt lgkmcnt(0)
	v_mfma_f32_16x16x32_bf16 v[156:159], v[48:51], v[72:75], v[156:159]
	v_mfma_f32_16x16x32_bf16 v[152:155], v[60:63], v[72:75], v[152:155]
	v_mfma_f32_16x16x32_bf16 v[140:143], v[48:51], v[80:83], v[140:143]
	v_mfma_f32_16x16x32_bf16 v[136:139], v[60:63], v[80:83], v[136:139]
	v_mfma_f32_16x16x32_bf16 v[124:127], v[48:51], v[160:163], v[124:127]
	v_mfma_f32_16x16x32_bf16 v[120:123], v[60:63], v[160:163], v[120:123]
	v_mfma_f32_16x16x32_bf16 v[108:111], v[48:51], v[192:195], v[108:111]
	v_mfma_f32_16x16x32_bf16 v[104:107], v[60:63], v[192:195], v[104:107]
	v_mfma_f32_16x16x32_bf16 v[156:159], v[52:55], v[76:79], v[156:159]
	v_mfma_f32_16x16x32_bf16 v[152:155], v[68:71], v[76:79], v[152:155]
	v_mfma_f32_16x16x32_bf16 v[140:143], v[52:55], v[84:87], v[140:143]
	v_mfma_f32_16x16x32_bf16 v[136:139], v[68:71], v[84:87], v[136:139]
	v_mfma_f32_16x16x32_bf16 v[124:127], v[52:55], v[164:167], v[124:127]
	v_mfma_f32_16x16x32_bf16 v[120:123], v[68:71], v[164:167], v[120:123]
	v_mfma_f32_16x16x32_bf16 v[108:111], v[52:55], v[196:199], v[108:111]
	v_mfma_f32_16x16x32_bf16 v[104:107], v[68:71], v[196:199], v[104:107]
	s_barrier
	s_add_i32 s62, 0, 0x14000
	s_add_i32 s59, s59, s40
	v_add_u32_e32 v168, s62, v206
	v_lshl_add_u64 v[240:241], s[2:3], 0, v[182:183]
	s_mov_b32 m0, s59
	ds_read_b128 v[200:203], v168
	ds_read_b128 v[208:211], v168 offset:1024
	ds_read_b128 v[212:215], v168 offset:2048
	ds_read_b128 v[216:219], v168 offset:3072
	global_load_lds_dwordx4 v[240:241], off
	s_add_i32 m0, s59, 0x2000
	v_lshl_add_u64 v[242:243], s[2:3], 0, v[186:187]
	global_load_lds_dwordx4 v[242:243], off
	s_barrier
	s_waitcnt lgkmcnt(0)
	v_mfma_f32_16x16x32_bf16 v[148:151], v[200:203], v[72:75], v[148:151]
	v_mfma_f32_16x16x32_bf16 v[72:75], v[212:215], v[72:75], v[144:147]
	v_mfma_f32_16x16x32_bf16 v[148:151], v[208:211], v[76:79], v[148:151]
	v_mfma_f32_16x16x32_bf16 v[72:75], v[216:219], v[76:79], v[72:75]
	v_mfma_f32_16x16x32_bf16 v[76:79], v[200:203], v[80:83], v[132:135]
	v_mfma_f32_16x16x32_bf16 v[80:83], v[212:215], v[80:83], v[128:131]
	v_mfma_f32_16x16x32_bf16 v[112:115], v[212:215], v[160:163], v[112:115]
	v_mfma_f32_16x16x32_bf16 v[100:103], v[200:203], v[192:195], v[100:103]
	v_mfma_f32_16x16x32_bf16 v[96:99], v[212:215], v[192:195], v[96:99]
	v_mfma_f32_16x16x32_bf16 v[76:79], v[208:211], v[84:87], v[76:79]
	v_mfma_f32_16x16x32_bf16 v[80:83], v[216:219], v[84:87], v[80:83]
	v_mfma_f32_16x16x32_bf16 v[84:87], v[200:203], v[160:163], v[116:119]
	v_mfma_f32_16x16x32_bf16 v[112:115], v[216:219], v[164:167], v[112:115]
	v_mfma_f32_16x16x32_bf16 v[100:103], v[208:211], v[196:199], v[100:103]
	v_mfma_f32_16x16x32_bf16 v[96:99], v[216:219], v[196:199], v[96:99]
	v_mfma_f32_16x16x32_bf16 v[84:87], v[208:211], v[164:167], v[84:87]
	s_mov_b32 m0, s41
	v_lshl_add_u64 v[244:245], s[28:29], 0, v[180:181]
	s_barrier
	ds_read_b128 v[116:119], v207 offset:16384
	ds_read_b128 v[128:131], v207 offset:17408
	ds_read_b128 v[132:135], v207 offset:18432
	ds_read_b128 v[144:147], v207 offset:19456
	ds_read_b128 v[160:163], v207 offset:20480
	ds_read_b128 v[164:167], v207 offset:21504
	ds_read_b128 v[192:195], v207 offset:22528
	ds_read_b128 v[196:199], v207 offset:23552
	global_load_lds_dwordx4 v[244:245], off
	s_mov_b32 m0, s42
	v_lshl_add_u64 v[246:247], s[28:29], 0, v[184:185]
	global_load_lds_dwordx4 v[246:247], off
	s_barrier
	s_waitcnt lgkmcnt(0)
	v_mfma_f32_16x16x32_bf16 v[92:95], v[48:51], v[116:119], v[92:95]
	v_mfma_f32_16x16x32_bf16 v[88:91], v[60:63], v[116:119], v[88:91]
	v_mfma_f32_16x16x32_bf16 v[44:47], v[48:51], v[132:135], v[44:47]
	v_mfma_f32_16x16x32_bf16 v[40:43], v[60:63], v[132:135], v[40:43]
	v_mfma_f32_16x16x32_bf16 v[28:31], v[48:51], v[160:163], v[28:31]
	v_mfma_f32_16x16x32_bf16 v[24:27], v[60:63], v[160:163], v[24:27]
	v_mfma_f32_16x16x32_bf16 v[12:15], v[48:51], v[192:195], v[12:15]
	v_mfma_f32_16x16x32_bf16 v[8:11], v[60:63], v[192:195], v[8:11]
	v_mfma_f32_16x16x32_bf16 v[92:95], v[52:55], v[128:131], v[92:95]
	v_mfma_f32_16x16x32_bf16 v[88:91], v[68:71], v[128:131], v[88:91]
	v_mfma_f32_16x16x32_bf16 v[44:47], v[52:55], v[144:147], v[44:47]
	v_mfma_f32_16x16x32_bf16 v[40:43], v[68:71], v[144:147], v[40:43]
	v_mfma_f32_16x16x32_bf16 v[28:31], v[52:55], v[164:167], v[28:31]
	v_mfma_f32_16x16x32_bf16 v[24:27], v[68:71], v[164:167], v[24:27]
	v_mfma_f32_16x16x32_bf16 v[12:15], v[52:55], v[196:199], v[12:15]
	v_mfma_f32_16x16x32_bf16 v[8:11], v[68:71], v[196:199], v[8:11]
	s_barrier
	s_add_u32 s60, s2, 0x40000
	s_addc_u32 s61, s3, 0
	s_add_i32 s59, s62, s40
	s_mov_b32 m0, s59
	v_lshl_add_u64 v[48:49], s[60:61], 0, v[182:183]
	global_load_lds_dwordx4 v[48:49], off
	s_add_i32 m0, s59, 0x2000
	v_lshl_add_u64 v[48:49], s[60:61], 0, v[186:187]
	global_load_lds_dwordx4 v[48:49], off
	s_waitcnt vmcnt(6)
	s_barrier
	v_mfma_f32_16x16x32_bf16 v[36:39], v[200:203], v[132:135], v[36:39]
	v_mfma_f32_16x16x32_bf16 v[32:35], v[212:215], v[132:135], v[32:35]
	v_mfma_f32_16x16x32_bf16 v[20:23], v[200:203], v[160:163], v[20:23]
	v_mfma_f32_16x16x32_bf16 v[16:19], v[212:215], v[160:163], v[16:19]
	v_mfma_f32_16x16x32_bf16 v[4:7], v[200:203], v[192:195], v[4:7]
	v_mfma_f32_16x16x32_bf16 v[0:3], v[212:215], v[192:195], v[0:3]
	v_mfma_f32_16x16x32_bf16 v[48:51], v[200:203], v[116:119], v[64:67]
	v_mfma_f32_16x16x32_bf16 v[52:55], v[212:215], v[116:119], v[56:59]
	v_mfma_f32_16x16x32_bf16 v[36:39], v[208:211], v[144:147], v[36:39]
	v_mfma_f32_16x16x32_bf16 v[32:35], v[216:219], v[144:147], v[32:35]
	v_mfma_f32_16x16x32_bf16 v[20:23], v[208:211], v[164:167], v[20:23]
	v_mfma_f32_16x16x32_bf16 v[16:19], v[216:219], v[164:167], v[16:19]
	v_mfma_f32_16x16x32_bf16 v[4:7], v[208:211], v[196:199], v[4:7]
	v_mfma_f32_16x16x32_bf16 v[0:3], v[216:219], v[196:199], v[0:3]
	v_mfma_f32_16x16x32_bf16 v[48:51], v[208:211], v[128:131], v[48:51]
	v_mfma_f32_16x16x32_bf16 v[52:55], v[216:219], v[128:131], v[52:55]
	s_add_i32 s59, 0, 0x18000
	v_add_u32_e32 v68, s59, v206
	s_barrier
	ds_read_b128 v[56:59], v68
	ds_read_b128 v[60:63], v68 offset:1024
	ds_read_b128 v[64:67], v68 offset:2048
	ds_read_b128 v[68:71], v68 offset:3072
	s_add_u32 s28, s28, 0x40000
	s_addc_u32 s29, s29, 0
	s_mov_b32 m0, s43
	v_lshl_add_u64 v[132:133], s[28:29], 0, v[180:181]
	ds_read_b128 v[116:119], v207 offset:32768
	ds_read_b128 v[128:131], v207 offset:33792
	ds_read_b128 v[160:163], v207 offset:34816
	ds_read_b128 v[164:167], v207 offset:35840
	ds_read_b128 v[192:195], v207 offset:36864
	ds_read_b128 v[196:199], v207 offset:37888
	ds_read_b128 v[200:203], v207 offset:38912
	ds_read_b128 v[208:211], v207 offset:39936
	global_load_lds_dwordx4 v[132:133], off
	s_mov_b32 m0, s44
	v_lshl_add_u64 v[132:133], s[28:29], 0, v[184:185]
	global_load_lds_dwordx4 v[132:133], off
	s_waitcnt lgkmcnt(8)
	s_barrier
	s_waitcnt lgkmcnt(0)
	v_mfma_f32_16x16x32_bf16 v[132:135], v[56:59], v[116:119], v[156:159]
	v_mfma_f32_16x16x32_bf16 v[156:159], v[60:63], v[128:131], v[132:135]
	v_mfma_f32_16x16x32_bf16 v[132:135], v[64:67], v[116:119], v[152:155]
	v_mfma_f32_16x16x32_bf16 v[152:155], v[68:71], v[128:131], v[132:135]
	v_mfma_f32_16x16x32_bf16 v[132:135], v[56:59], v[160:163], v[140:143]
	v_mfma_f32_16x16x32_bf16 v[140:143], v[60:63], v[164:167], v[132:135]
	v_mfma_f32_16x16x32_bf16 v[132:135], v[64:67], v[160:163], v[136:139]
	v_mfma_f32_16x16x32_bf16 v[124:127], v[56:59], v[192:195], v[124:127]
	v_mfma_f32_16x16x32_bf16 v[120:123], v[64:67], v[192:195], v[120:123]
	v_mfma_f32_16x16x32_bf16 v[108:111], v[56:59], v[200:203], v[108:111]
	v_mfma_f32_16x16x32_bf16 v[104:107], v[64:67], v[200:203], v[104:107]
	v_mfma_f32_16x16x32_bf16 v[136:139], v[68:71], v[164:167], v[132:135]
	v_mfma_f32_16x16x32_bf16 v[124:127], v[60:63], v[196:199], v[124:127]
	v_mfma_f32_16x16x32_bf16 v[120:123], v[68:71], v[196:199], v[120:123]
	v_mfma_f32_16x16x32_bf16 v[108:111], v[60:63], v[208:211], v[108:111]
	v_mfma_f32_16x16x32_bf16 v[104:107], v[68:71], v[208:211], v[104:107]
	s_barrier
	s_add_i32 s28, 0, 0x1c000
	v_add_u32_e32 v132, s28, v206
	s_add_i32 s29, s59, s40
	ds_read_b128 v[212:215], v132
	ds_read_b128 v[216:219], v132 offset:1024
	ds_read_b128 v[220:223], v132 offset:2048
	ds_read_b128 v[236:239], v132 offset:3072
	s_mov_b32 m0, s29
	v_lshl_add_u64 v[132:133], v[240:241], 0, s[78:79]
	global_load_lds_dwordx4 v[132:133], off
	s_add_i32 m0, s29, 0x2000
	v_lshl_add_u64 v[132:133], v[242:243], 0, s[78:79]
	global_load_lds_dwordx4 v[132:133], off
	s_barrier
	s_waitcnt lgkmcnt(0)
	v_mfma_f32_16x16x32_bf16 v[72:75], v[220:223], v[116:119], v[72:75]
	v_mfma_f32_16x16x32_bf16 v[132:135], v[212:215], v[116:119], v[148:151]
	v_mfma_f32_16x16x32_bf16 v[144:147], v[236:239], v[128:131], v[72:75]
	v_mfma_f32_16x16x32_bf16 v[72:75], v[212:215], v[160:163], v[76:79]
	v_mfma_f32_16x16x32_bf16 v[148:151], v[216:219], v[128:131], v[132:135]
	v_mfma_f32_16x16x32_bf16 v[132:135], v[216:219], v[164:167], v[72:75]
	v_mfma_f32_16x16x32_bf16 v[72:75], v[220:223], v[160:163], v[80:83]
	v_mfma_f32_16x16x32_bf16 v[128:131], v[236:239], v[164:167], v[72:75]
	v_mfma_f32_16x16x32_bf16 v[72:75], v[212:215], v[192:195], v[84:87]
	v_mfma_f32_16x16x32_bf16 v[116:119], v[216:219], v[196:199], v[72:75]
	v_mfma_f32_16x16x32_bf16 v[72:75], v[220:223], v[192:195], v[112:115]
	v_mfma_f32_16x16x32_bf16 v[112:115], v[236:239], v[196:199], v[72:75]
	v_mfma_f32_16x16x32_bf16 v[72:75], v[212:215], v[200:203], v[100:103]
	v_mfma_f32_16x16x32_bf16 v[100:103], v[216:219], v[208:211], v[72:75]
	v_mfma_f32_16x16x32_bf16 v[72:75], v[220:223], v[200:203], v[96:99]
	v_mfma_f32_16x16x32_bf16 v[96:99], v[236:239], v[208:211], v[72:75]
	s_mov_b32 m0, s53
	v_lshl_add_u64 v[200:201], v[244:245], 0, s[78:79]
	s_barrier
	s_nop 2
	ds_read_b128 v[72:75], v207 offset:49152
	ds_read_b128 v[76:79], v207 offset:50176
	ds_read_b128 v[80:83], v207 offset:51200
	ds_read_b128 v[84:87], v207 offset:52224
	ds_read_b128 v[160:163], v207 offset:53248
	ds_read_b128 v[164:167], v207 offset:54272
	ds_read_b128 v[192:195], v207 offset:55296
	ds_read_b128 v[196:199], v207 offset:56320
	global_load_lds_dwordx4 v[200:201], off
	s_mov_b32 m0, s54
	v_lshl_add_u64 v[200:201], v[246:247], 0, s[78:79]
	global_load_lds_dwordx4 v[200:201], off
	s_barrier
	s_waitcnt lgkmcnt(0)
	v_mfma_f32_16x16x32_bf16 v[92:95], v[56:59], v[72:75], v[92:95]
	v_mfma_f32_16x16x32_bf16 v[88:91], v[64:67], v[72:75], v[88:91]
	v_mfma_f32_16x16x32_bf16 v[44:47], v[56:59], v[80:83], v[44:47]
	v_mfma_f32_16x16x32_bf16 v[40:43], v[64:67], v[80:83], v[40:43]
	v_mfma_f32_16x16x32_bf16 v[28:31], v[56:59], v[160:163], v[28:31]
	v_mfma_f32_16x16x32_bf16 v[24:27], v[64:67], v[160:163], v[24:27]
	v_mfma_f32_16x16x32_bf16 v[12:15], v[56:59], v[192:195], v[12:15]
	v_mfma_f32_16x16x32_bf16 v[8:11], v[64:67], v[192:195], v[8:11]
	v_mfma_f32_16x16x32_bf16 v[92:95], v[60:63], v[76:79], v[92:95]
	v_mfma_f32_16x16x32_bf16 v[88:91], v[68:71], v[76:79], v[88:91]
	v_mfma_f32_16x16x32_bf16 v[44:47], v[60:63], v[84:87], v[44:47]
	v_mfma_f32_16x16x32_bf16 v[40:43], v[68:71], v[84:87], v[40:43]
	v_mfma_f32_16x16x32_bf16 v[28:31], v[60:63], v[164:167], v[28:31]
	v_mfma_f32_16x16x32_bf16 v[24:27], v[68:71], v[164:167], v[24:27]
	v_mfma_f32_16x16x32_bf16 v[12:15], v[60:63], v[196:199], v[12:15]
	v_mfma_f32_16x16x32_bf16 v[8:11], v[68:71], v[196:199], v[8:11]
	s_barrier
	s_add_u32 s2, s2, 0x40080
	s_addc_u32 s3, s3, 0
	s_add_i32 s28, s28, s40
	s_mov_b32 m0, s28
	v_lshl_add_u64 v[56:57], s[2:3], 0, v[182:183]
	global_load_lds_dwordx4 v[56:57], off
	s_add_i32 m0, s28, 0x2000
	v_lshl_add_u64 v[56:57], s[2:3], 0, v[186:187]
	global_load_lds_dwordx4 v[56:57], off
	s_waitcnt vmcnt(6)
	s_barrier
	v_mfma_f32_16x16x32_bf16 v[48:51], v[212:215], v[72:75], v[48:51]
	v_mfma_f32_16x16x32_bf16 v[64:67], v[216:219], v[76:79], v[48:51]
	v_mfma_f32_16x16x32_bf16 v[48:51], v[220:223], v[72:75], v[52:55]
	v_mfma_f32_16x16x32_bf16 v[36:39], v[212:215], v[80:83], v[36:39]
	v_mfma_f32_16x16x32_bf16 v[32:35], v[220:223], v[80:83], v[32:35]
	v_mfma_f32_16x16x32_bf16 v[20:23], v[212:215], v[160:163], v[20:23]
	v_mfma_f32_16x16x32_bf16 v[16:19], v[220:223], v[160:163], v[16:19]
	v_mfma_f32_16x16x32_bf16 v[4:7], v[212:215], v[192:195], v[4:7]
	v_mfma_f32_16x16x32_bf16 v[0:3], v[220:223], v[192:195], v[0:3]
	v_mfma_f32_16x16x32_bf16 v[56:59], v[236:239], v[76:79], v[48:51]
	v_mfma_f32_16x16x32_bf16 v[36:39], v[216:219], v[84:87], v[36:39]
	v_mfma_f32_16x16x32_bf16 v[32:35], v[236:239], v[84:87], v[32:35]
	v_mfma_f32_16x16x32_bf16 v[20:23], v[216:219], v[164:167], v[20:23]
	v_mfma_f32_16x16x32_bf16 v[16:19], v[236:239], v[164:167], v[16:19]
	v_mfma_f32_16x16x32_bf16 v[4:7], v[216:219], v[196:199], v[4:7]
	v_mfma_f32_16x16x32_bf16 v[0:3], v[236:239], v[196:199], v[0:3]
	s_add_i32 s58, s58, 2
	s_add_u32 s8, s8, 0x100
	s_addc_u32 s9, s9, 0
	s_add_u32 s56, s56, 0x100
	s_addc_u32 s57, s57, 0
	s_cmp_gt_u32 s58, 13
	s_barrier
	s_cbranch_scc0 .LBB0_678
	s_lshl_b32 s1, s0, 8
	s_add_i32 s2, s1, s51
	s_lshl_b32 s1, s6, 8
	v_mov_b32_e32 v160, v205
	v_mov_b32_e32 v208, v204
	s_or_b32 s1, s1, s52
	s_nop 0
	v_lshl_add_u32 v192, v208, 3, s1
	s_add_i32 s1, s0, -16
	s_lshr_b32 s1, s1, 3
	s_add_i32 s1, s1, 1
	s_cmp_gt_i32 s0, 15
	s_cselect_b32 s3, s1, 0
	s_mul_i32 s96, s3, 0x1800
	s_lshl_b64 s[0:1], s[96:97], 2
	s_add_u32 s0, s45, s0
	v_ashrrev_i32_e32 v193, 31, v192
	s_addc_u32 s1, s46, s1
	v_lshlrev_b64 v[196:197], 2, v[192:193]
	s_lshl_b32 s96, s3, 10
	v_lshl_add_u64 v[48:49], s[0:1], 0, v[196:197]
	s_lshl_b64 s[0:1], s[96:97], 2
	s_add_u32 s0, s49, s0
	s_addc_u32 s1, s50, s1
	v_lshl_add_u64 v[52:53], s[0:1], 0, v[196:197]
	global_load_dwordx4 v[80:83], v[48:49], off offset:16
	global_load_dwordx4 v[84:87], v[48:49], off
	global_load_dwordx4 v[72:75], v[52:53], off offset:16
	global_load_dwordx4 v[76:79], v[52:53], off
	global_load_dwordx4 v[60:63], v[48:49], off offset:528
	global_load_dwordx4 v[68:71], v[48:49], off offset:512
	s_nop 0
	global_load_dwordx4 v[48:51], v[52:53], off offset:528
	s_nop 0
	global_load_dwordx4 v[52:55], v[52:53], off offset:512
	v_add_u32_e32 v194, s2, v160
	v_ashrrev_i32_e32 v195, 31, v194
	v_lshlrev_b64 v[160:161], 10, v[194:195]
	v_lshl_add_u64 v[198:199], v[160:161], 0, v[192:193]
	v_cndmask_b32_e64 v160, 0, 1, s[74:75]
	v_cmp_gt_i32_e64 s[0:1], s71, v194
	v_cmp_ne_u32_e64 s[6:7], 1, v160
	s_andn2_b64 vcc, exec, s[74:75]
	s_mov_b64 s[2:3], -1
	s_cbranch_vccnz .LBB0_681
	v_lshl_add_u64 v[160:161], v[198:199], 1, s[14:15]
	v_mov_b32_e32 v222, v160
	v_mov_b32_e32 v223, v161
	global_load_dwordx4 v[210:213], v[222:223], off
	global_load_dwordx4 v[214:217], v[222:223], off offset:256
	s_mov_b64 s[80:81], 0x8000
	v_lshl_add_u64 v[222:223], v[222:223], 0, s[80:81]
	global_load_dwordx4 v[218:221], v[222:223], off
	global_load_dwordx4 v[236:239], v[222:223], off offset:256
	s_mov_b64 s[2:3], 0
	s_waitcnt vmcnt(3)
	v_lshlrev_b32_e32 v164, 16, v210
	v_and_b32_e32 v165, 0xffff0000, v210
	v_lshlrev_b32_e32 v166, 16, v211
	v_and_b32_e32 v167, 0xffff0000, v211
	v_lshlrev_b32_e32 v160, 16, v212
	v_and_b32_e32 v161, 0xffff0000, v212
	v_lshlrev_b32_e32 v162, 16, v213
	v_and_b32_e32 v163, 0xffff0000, v213
	s_mov_b64 s[80:81], 0x8000
	v_lshl_add_u64 v[222:223], v[222:223], 0, s[80:81]
	global_load_dwordx4 v[210:213], v[222:223], off

.LBB0_879:
	s_ashr_i32 s39, s38, 31
	v_cmp_lt_i64_e32 vcc, s[12:13], v[178:179]
	s_lshl_b64 s[12:13], s[38:39], 19
	s_add_u32 s40, s49, s12
	s_addc_u32 s41, s50, s13
	s_lshl_b32 s84, s82, 18
	s_add_u32 s40, s40, s84
	s_addc_u32 s41, s41, 0
	s_and_b64 s[12:13], vcc, exec
	s_cselect_b32 s1, s41, s11
	s_cselect_b32 s9, s40, s10
	s_ashr_i32 s37, s36, 31
	s_lshl_b64 s[12:13], s[36:37], 19
	s_add_u32 s42, s51, s12
	s_addc_u32 s43, s52, s13
	s_and_b64 s[12:13], vcc, exec
	s_cselect_b32 s14, s43, s3
	s_cselect_b32 s15, s42, s2
	s_add_u32 s10, s10, 0x40080
	s_addc_u32 s11, s11, 0
	s_add_u32 s37, s2, 0x100
	s_addc_u32 s39, s3, 0
	s_mov_b32 s67, -2
	s_cmp_lg_u32 s83, 0
	s_cbranch_scc1 .Lup_half_peel
	s_add_u32 s2, s10, 0xfffc0080
	s_addc_u32 s3, s11, -1
	s_add_i32 s68, 0, 0x10000
	v_add_u32_e32 v108, s68, v237
	ds_read_b128 v[48:51], v108
	ds_read_b128 v[52:55], v108 offset:1024
	ds_read_b128 v[104:107], v108 offset:2048
	ds_read_b128 v[108:111], v108 offset:3072
	s_cmp_eq_u32 s67, 12
	s_cselect_b32 s13, s1, s3
	s_cselect_b32 s12, s9, s2
	s_cselect_b32 s3, s14, s39
	s_cselect_b32 s2, s15, s37
	v_lshl_add_u64 v[198:199], s[10:11], 0, v[186:187]
	s_add_i32 m0, s54, 0xc000
	ds_read_b128 v[112:115], v238
	ds_read_b128 v[116:119], v238 offset:1024
	ds_read_b128 v[120:123], v238 offset:2048
	ds_read_b128 v[156:159], v238 offset:3072
	ds_read_b128 v[160:163], v238 offset:4096
	ds_read_b128 v[164:167], v238 offset:5120
	ds_read_b128 v[190:193], v238 offset:6144
	ds_read_b128 v[194:197], v238 offset:7168
	global_load_lds_dwordx4 v[198:199], off
	s_add_i32 m0, s54, 0xe000
	v_lshl_add_u64 v[198:199], s[10:11], 0, v[188:189]
	global_load_lds_dwordx4 v[198:199], off
	s_waitcnt lgkmcnt(8)
	s_barrier
	s_waitcnt lgkmcnt(0)
	v_mfma_f32_16x16x32_bf16 v[152:155], v[48:51], v[112:115], 0
	v_mfma_f32_16x16x32_bf16 v[68:71], v[104:107], v[112:115], 0
	v_mfma_f32_16x16x32_bf16 v[148:151], v[48:51], v[120:123], 0
	v_mfma_f32_16x16x32_bf16 v[64:67], v[104:107], v[120:123], 0
	v_mfma_f32_16x16x32_bf16 v[136:139], v[48:51], v[160:163], 0
	v_mfma_f32_16x16x32_bf16 v[44:47], v[104:107], v[160:163], 0
	v_mfma_f32_16x16x32_bf16 v[128:131], v[48:51], v[190:193], 0
	v_mfma_f32_16x16x32_bf16 v[40:43], v[104:107], v[190:193], 0
	v_mfma_f32_16x16x32_bf16 v[152:155], v[52:55], v[116:119], v[152:155]
	v_mfma_f32_16x16x32_bf16 v[68:71], v[108:111], v[116:119], v[68:71]
	v_mfma_f32_16x16x32_bf16 v[148:151], v[52:55], v[156:159], v[148:151]
	v_mfma_f32_16x16x32_bf16 v[64:67], v[108:111], v[156:159], v[64:67]
	v_mfma_f32_16x16x32_bf16 v[136:139], v[52:55], v[164:167], v[136:139]
	v_mfma_f32_16x16x32_bf16 v[44:47], v[108:111], v[164:167], v[44:47]
	v_mfma_f32_16x16x32_bf16 v[128:131], v[52:55], v[194:197], v[128:131]
	v_mfma_f32_16x16x32_bf16 v[40:43], v[108:111], v[194:197], v[40:43]
	s_barrier
	s_add_i32 s70, 0, 0x14000
	s_add_i32 s68, s68, s53
	v_add_u32_e32 v210, s70, v237
	v_lshl_add_u64 v[218:219], s[2:3], 0, v[168:169]
	s_mov_b32 m0, s68
	ds_read_b128 v[198:201], v210
	ds_read_b128 v[202:205], v210 offset:1024
	ds_read_b128 v[206:209], v210 offset:2048
	ds_read_b128 v[210:213], v210 offset:3072
	global_load_lds_dwordx4 v[218:219], off
	s_add_i32 m0, s68, 0x2000
	v_lshl_add_u64 v[220:221], s[2:3], 0, v[184:185]
	global_load_lds_dwordx4 v[220:221], off
	s_barrier
	s_waitcnt lgkmcnt(0)
	v_mfma_f32_16x16x32_bf16 v[144:147], v[198:201], v[112:115], 0
	v_mfma_f32_16x16x32_bf16 v[60:63], v[206:209], v[112:115], 0
	v_mfma_f32_16x16x32_bf16 v[56:59], v[206:209], v[120:123], 0
	v_mfma_f32_16x16x32_bf16 v[36:39], v[206:209], v[160:163], 0
	v_mfma_f32_16x16x32_bf16 v[32:35], v[206:209], v[190:193], 0
	v_mfma_f32_16x16x32_bf16 v[144:147], v[202:205], v[116:119], v[144:147]
	v_mfma_f32_16x16x32_bf16 v[60:63], v[210:213], v[116:119], v[60:63]
	v_mfma_f32_16x16x32_bf16 v[112:115], v[198:201], v[120:123], 0
	v_mfma_f32_16x16x32_bf16 v[56:59], v[210:213], v[156:159], v[56:59]
	v_mfma_f32_16x16x32_bf16 v[116:119], v[198:201], v[160:163], 0
	v_mfma_f32_16x16x32_bf16 v[36:39], v[210:213], v[164:167], v[36:39]
	v_mfma_f32_16x16x32_bf16 v[120:123], v[198:201], v[190:193], 0
	v_mfma_f32_16x16x32_bf16 v[32:35], v[210:213], v[194:197], v[32:35]
	v_mfma_f32_16x16x32_bf16 v[112:115], v[202:205], v[156:159], v[112:115]
	v_mfma_f32_16x16x32_bf16 v[116:119], v[202:205], v[164:167], v[116:119]
	v_mfma_f32_16x16x32_bf16 v[120:123], v[202:205], v[194:197], v[120:123]
	s_mov_b32 m0, s54
	v_lshl_add_u64 v[222:223], s[12:13], 0, v[180:181]
	s_barrier
	ds_read_b128 v[124:127], v238 offset:16384
	ds_read_b128 v[132:135], v238 offset:17408
	ds_read_b128 v[140:143], v238 offset:18432
	ds_read_b128 v[156:159], v238 offset:19456
	ds_read_b128 v[160:163], v238 offset:20480
	ds_read_b128 v[164:167], v238 offset:21504
	ds_read_b128 v[190:193], v238 offset:22528
	ds_read_b128 v[194:197], v238 offset:23552
	global_load_lds_dwordx4 v[222:223], off
	s_mov_b32 m0, s55
	v_lshl_add_u64 v[240:241], s[12:13], 0, v[182:183]
	global_load_lds_dwordx4 v[240:241], off
	s_barrier
	s_waitcnt lgkmcnt(0)
	v_mfma_f32_16x16x32_bf16 v[100:103], v[48:51], v[124:127], 0
	v_mfma_f32_16x16x32_bf16 v[28:31], v[104:107], v[124:127], 0
	v_mfma_f32_16x16x32_bf16 v[96:99], v[48:51], v[140:143], 0
	v_mfma_f32_16x16x32_bf16 v[24:27], v[104:107], v[140:143], 0
	v_mfma_f32_16x16x32_bf16 v[84:87], v[48:51], v[160:163], 0
	v_mfma_f32_16x16x32_bf16 v[12:15], v[104:107], v[160:163], 0
	v_mfma_f32_16x16x32_bf16 v[8:11], v[104:107], v[190:193], 0
	v_mfma_f32_16x16x32_bf16 v[100:103], v[52:55], v[132:135], v[100:103]
	v_mfma_f32_16x16x32_bf16 v[28:31], v[108:111], v[132:135], v[28:31]
	v_mfma_f32_16x16x32_bf16 v[96:99], v[52:55], v[156:159], v[96:99]
	v_mfma_f32_16x16x32_bf16 v[24:27], v[108:111], v[156:159], v[24:27]
	v_mfma_f32_16x16x32_bf16 v[84:87], v[52:55], v[164:167], v[84:87]
	v_mfma_f32_16x16x32_bf16 v[12:15], v[108:111], v[164:167], v[12:15]
	v_mfma_f32_16x16x32_bf16 v[48:51], v[48:51], v[190:193], 0
	v_mfma_f32_16x16x32_bf16 v[8:11], v[108:111], v[194:197], v[8:11]
	v_mfma_f32_16x16x32_bf16 v[48:51], v[52:55], v[194:197], v[48:51]
	s_barrier
	s_add_u32 s68, s2, 0x40000
	s_addc_u32 s69, s3, 0
	s_add_i32 s70, s70, s53
	s_mov_b32 m0, s70
	v_lshl_add_u64 v[52:53], s[68:69], 0, v[168:169]
	global_load_lds_dwordx4 v[52:53], off
	s_add_i32 m0, s70, 0x2000
	v_lshl_add_u64 v[52:53], s[68:69], 0, v[184:185]
	global_load_lds_dwordx4 v[52:53], off
	s_waitcnt vmcnt(6)
	s_barrier
	v_mfma_f32_16x16x32_bf16 v[76:79], v[198:201], v[140:143], 0
	v_mfma_f32_16x16x32_bf16 v[20:23], v[206:209], v[124:127], 0
	v_mfma_f32_16x16x32_bf16 v[88:91], v[202:205], v[156:159], v[76:79]
	v_mfma_f32_16x16x32_bf16 v[16:19], v[206:209], v[140:143], 0
	v_mfma_f32_16x16x32_bf16 v[76:79], v[198:201], v[160:163], 0
	v_mfma_f32_16x16x32_bf16 v[4:7], v[206:209], v[160:163], 0
	v_mfma_f32_16x16x32_bf16 v[72:75], v[198:201], v[190:193], 0
	v_mfma_f32_16x16x32_bf16 v[0:3], v[206:209], v[190:193], 0
	v_mfma_f32_16x16x32_bf16 v[52:55], v[198:201], v[124:127], 0
	v_mfma_f32_16x16x32_bf16 v[20:23], v[210:213], v[132:135], v[20:23]
	v_mfma_f32_16x16x32_bf16 v[16:19], v[210:213], v[156:159], v[16:19]
	v_mfma_f32_16x16x32_bf16 v[80:83], v[202:205], v[164:167], v[76:79]
	v_mfma_f32_16x16x32_bf16 v[4:7], v[210:213], v[164:167], v[4:7]
	v_mfma_f32_16x16x32_bf16 v[72:75], v[202:205], v[194:197], v[72:75]
	v_mfma_f32_16x16x32_bf16 v[0:3], v[210:213], v[194:197], v[0:3]
	v_mfma_f32_16x16x32_bf16 v[52:55], v[202:205], v[132:135], v[52:55]
	s_add_i32 s68, 0, 0x18000
	v_add_u32_e32 v108, s68, v237
	s_barrier
	ds_read_b128 v[76:79], v108
	ds_read_b128 v[92:95], v108 offset:1024
	ds_read_b128 v[104:107], v108 offset:2048
	ds_read_b128 v[108:111], v108 offset:3072
	s_add_u32 s12, s12, 0x40000
	s_addc_u32 s13, s13, 0
	s_mov_b32 m0, s56
	v_lshl_add_u64 v[140:141], s[12:13], 0, v[180:181]
	ds_read_b128 v[124:127], v238 offset:32768
	ds_read_b128 v[132:135], v238 offset:33792
	ds_read_b128 v[156:159], v238 offset:34816
	ds_read_b128 v[160:163], v238 offset:35840
	ds_read_b128 v[164:167], v238 offset:36864
	ds_read_b128 v[190:193], v238 offset:37888
	ds_read_b128 v[194:197], v238 offset:38912
	ds_read_b128 v[198:201], v238 offset:39936
	global_load_lds_dwordx4 v[140:141], off
	s_mov_b32 m0, s57
	v_lshl_add_u64 v[140:141], s[12:13], 0, v[182:183]
	global_load_lds_dwordx4 v[140:141], off
	s_waitcnt lgkmcnt(8)
	s_barrier
	s_waitcnt lgkmcnt(0)
	v_mfma_f32_16x16x32_bf16 v[140:143], v[76:79], v[124:127], v[152:155]
	v_mfma_f32_16x16x32_bf16 v[152:155], v[92:95], v[132:135], v[140:143]
	v_mfma_f32_16x16x32_bf16 v[68:71], v[104:107], v[124:127], v[68:71]
	v_mfma_f32_16x16x32_bf16 v[140:143], v[76:79], v[156:159], v[148:151]
	v_mfma_f32_16x16x32_bf16 v[64:67], v[104:107], v[156:159], v[64:67]
	v_mfma_f32_16x16x32_bf16 v[136:139], v[76:79], v[164:167], v[136:139]
	v_mfma_f32_16x16x32_bf16 v[44:47], v[104:107], v[164:167], v[44:47]
	v_mfma_f32_16x16x32_bf16 v[128:131], v[76:79], v[194:197], v[128:131]
	v_mfma_f32_16x16x32_bf16 v[40:43], v[104:107], v[194:197], v[40:43]
	v_mfma_f32_16x16x32_bf16 v[68:71], v[108:111], v[132:135], v[68:71]
	v_mfma_f32_16x16x32_bf16 v[148:151], v[92:95], v[160:163], v[140:143]
	v_mfma_f32_16x16x32_bf16 v[64:67], v[108:111], v[160:163], v[64:67]
	v_mfma_f32_16x16x32_bf16 v[136:139], v[92:95], v[190:193], v[136:139]
	v_mfma_f32_16x16x32_bf16 v[44:47], v[108:111], v[190:193], v[44:47]
	v_mfma_f32_16x16x32_bf16 v[128:131], v[92:95], v[198:201], v[128:131]
	v_mfma_f32_16x16x32_bf16 v[40:43], v[108:111], v[198:201], v[40:43]
	s_barrier
	s_add_i32 s12, 0, 0x1c000
	v_add_u32_e32 v140, s12, v237
	s_add_i32 s13, s68, s53
	ds_read_b128 v[202:205], v140
	ds_read_b128 v[206:209], v140 offset:1024
	ds_read_b128 v[210:213], v140 offset:2048
	ds_read_b128 v[214:217], v140 offset:3072
	s_mov_b32 m0, s13
	v_lshl_add_u64 v[140:141], v[218:219], 0, s[78:79]
	global_load_lds_dwordx4 v[140:141], off
	s_add_i32 m0, s13, 0x2000
	v_lshl_add_u64 v[140:141], v[220:221], 0, s[78:79]
	global_load_lds_dwordx4 v[140:141], off
	s_barrier
	s_waitcnt lgkmcnt(0)
	v_mfma_f32_16x16x32_bf16 v[140:143], v[202:205], v[124:127], v[144:147]
	v_mfma_f32_16x16x32_bf16 v[112:115], v[202:205], v[156:159], v[112:115]
	v_mfma_f32_16x16x32_bf16 v[144:147], v[206:209], v[132:135], v[140:143]
	v_mfma_f32_16x16x32_bf16 v[60:63], v[210:213], v[124:127], v[60:63]
	v_mfma_f32_16x16x32_bf16 v[140:143], v[206:209], v[160:163], v[112:115]
	v_mfma_f32_16x16x32_bf16 v[112:115], v[202:205], v[164:167], v[116:119]
	v_mfma_f32_16x16x32_bf16 v[60:63], v[214:217], v[132:135], v[60:63]
	v_mfma_f32_16x16x32_bf16 v[56:59], v[210:213], v[156:159], v[56:59]
	v_mfma_f32_16x16x32_bf16 v[132:135], v[206:209], v[190:193], v[112:115]
	v_mfma_f32_16x16x32_bf16 v[36:39], v[210:213], v[164:167], v[36:39]
	v_mfma_f32_16x16x32_bf16 v[112:115], v[202:205], v[194:197], v[120:123]
	v_mfma_f32_16x16x32_bf16 v[32:35], v[210:213], v[194:197], v[32:35]
	v_mfma_f32_16x16x32_bf16 v[56:59], v[214:217], v[160:163], v[56:59]
	v_mfma_f32_16x16x32_bf16 v[36:39], v[214:217], v[190:193], v[36:39]
	v_mfma_f32_16x16x32_bf16 v[124:127], v[206:209], v[198:201], v[112:115]
	v_mfma_f32_16x16x32_bf16 v[32:35], v[214:217], v[198:201], v[32:35]
	s_mov_b32 m0, s62
	v_lshl_add_u64 v[198:199], v[222:223], 0, s[78:79]
	s_barrier
	ds_read_b128 v[112:115], v238 offset:49152
	ds_read_b128 v[116:119], v238 offset:50176
	ds_read_b128 v[120:123], v238 offset:51200
	ds_read_b128 v[156:159], v238 offset:52224
	ds_read_b128 v[160:163], v238 offset:53248
	ds_read_b128 v[164:167], v238 offset:54272
	ds_read_b128 v[190:193], v238 offset:55296
	ds_read_b128 v[194:197], v238 offset:56320
	global_load_lds_dwordx4 v[198:199], off
	s_mov_b32 m0, s63
	v_lshl_add_u64 v[198:199], v[240:241], 0, s[78:79]
	global_load_lds_dwordx4 v[198:199], off
	s_barrier
	s_waitcnt lgkmcnt(0)
	v_mfma_f32_16x16x32_bf16 v[100:103], v[76:79], v[112:115], v[100:103]
	v_mfma_f32_16x16x32_bf16 v[28:31], v[104:107], v[112:115], v[28:31]
	v_mfma_f32_16x16x32_bf16 v[96:99], v[76:79], v[120:123], v[96:99]
	v_mfma_f32_16x16x32_bf16 v[24:27], v[104:107], v[120:123], v[24:27]
	v_mfma_f32_16x16x32_bf16 v[84:87], v[76:79], v[160:163], v[84:87]
	v_mfma_f32_16x16x32_bf16 v[12:15], v[104:107], v[160:163], v[12:15]
	v_mfma_f32_16x16x32_bf16 v[48:51], v[76:79], v[190:193], v[48:51]
	v_mfma_f32_16x16x32_bf16 v[8:11], v[104:107], v[190:193], v[8:11]
	v_mfma_f32_16x16x32_bf16 v[100:103], v[92:95], v[116:119], v[100:103]
	v_mfma_f32_16x16x32_bf16 v[28:31], v[108:111], v[116:119], v[28:31]
	v_mfma_f32_16x16x32_bf16 v[96:99], v[92:95], v[156:159], v[96:99]
	v_mfma_f32_16x16x32_bf16 v[24:27], v[108:111], v[156:159], v[24:27]
	v_mfma_f32_16x16x32_bf16 v[84:87], v[92:95], v[164:167], v[84:87]
	v_mfma_f32_16x16x32_bf16 v[12:15], v[108:111], v[164:167], v[12:15]
	v_mfma_f32_16x16x32_bf16 v[76:79], v[92:95], v[194:197], v[48:51]
	v_mfma_f32_16x16x32_bf16 v[8:11], v[108:111], v[194:197], v[8:11]
	s_barrier
	s_add_u32 s2, s2, 0x40080
	s_addc_u32 s3, s3, 0
	s_add_i32 s12, s12, s53
	s_mov_b32 m0, s12
	v_lshl_add_u64 v[48:49], s[2:3], 0, v[168:169]
	global_load_lds_dwordx4 v[48:49], off
	s_add_i32 m0, s12, 0x2000
	v_lshl_add_u64 v[48:49], s[2:3], 0, v[184:185]
	global_load_lds_dwordx4 v[48:49], off
	s_waitcnt vmcnt(6)
	s_barrier
	v_mfma_f32_16x16x32_bf16 v[48:51], v[202:205], v[112:115], v[52:55]
	v_mfma_f32_16x16x32_bf16 v[92:95], v[206:209], v[116:119], v[48:51]
	v_mfma_f32_16x16x32_bf16 v[48:51], v[202:205], v[120:123], v[88:91]
	v_mfma_f32_16x16x32_bf16 v[88:91], v[206:209], v[156:159], v[48:51]
	v_mfma_f32_16x16x32_bf16 v[48:51], v[202:205], v[160:163], v[80:83]
	v_mfma_f32_16x16x32_bf16 v[20:23], v[210:213], v[112:115], v[20:23]
	v_mfma_f32_16x16x32_bf16 v[16:19], v[210:213], v[120:123], v[16:19]
	v_mfma_f32_16x16x32_bf16 v[80:83], v[206:209], v[164:167], v[48:51]
	v_mfma_f32_16x16x32_bf16 v[4:7], v[210:213], v[160:163], v[4:7]
	v_mfma_f32_16x16x32_bf16 v[48:51], v[202:205], v[190:193], v[72:75]
	v_mfma_f32_16x16x32_bf16 v[0:3], v[210:213], v[190:193], v[0:3]
	v_mfma_f32_16x16x32_bf16 v[20:23], v[214:217], v[116:119], v[20:23]
	v_mfma_f32_16x16x32_bf16 v[16:19], v[214:217], v[156:159], v[16:19]
	v_mfma_f32_16x16x32_bf16 v[4:7], v[214:217], v[164:167], v[4:7]
	v_mfma_f32_16x16x32_bf16 v[72:75], v[206:209], v[194:197], v[48:51]
	v_mfma_f32_16x16x32_bf16 v[0:3], v[214:217], v[194:197], v[0:3]
	s_add_i32 s67, s67, 2
	s_add_u32 s10, s10, 0x100
	s_addc_u32 s11, s11, 0
	s_add_u32 s37, s37, 0x100
	s_addc_u32 s39, s39, 0
	s_cmp_gt_u32 s67, 13
	s_barrier
.LBB0_880:
	s_add_u32 s2, s10, 0xfffc0080
	s_addc_u32 s3, s11, -1
	s_add_i32 s68, 0, 0x10000
	v_add_u32_e32 v108, s68, v237
	ds_read_b128 v[48:51], v108
	ds_read_b128 v[52:55], v108 offset:1024
	ds_read_b128 v[104:107], v108 offset:2048
	ds_read_b128 v[108:111], v108 offset:3072
	s_cmp_eq_u32 s67, 12
	s_cselect_b32 s13, s1, s3
	s_cselect_b32 s12, s9, s2
	s_cselect_b32 s3, s14, s39
	s_cselect_b32 s2, s15, s37
	v_lshl_add_u64 v[198:199], s[10:11], 0, v[186:187]
	s_add_i32 m0, s54, 0xc000
	ds_read_b128 v[112:115], v238
	ds_read_b128 v[116:119], v238 offset:1024
	ds_read_b128 v[120:123], v238 offset:2048
	ds_read_b128 v[156:159], v238 offset:3072
	ds_read_b128 v[160:163], v238 offset:4096
	ds_read_b128 v[164:167], v238 offset:5120
	ds_read_b128 v[190:193], v238 offset:6144
	ds_read_b128 v[194:197], v238 offset:7168
	global_load_lds_dwordx4 v[198:199], off
	s_add_i32 m0, s54, 0xe000
	v_lshl_add_u64 v[198:199], s[10:11], 0, v[188:189]
	global_load_lds_dwordx4 v[198:199], off
	s_waitcnt lgkmcnt(8)
	s_barrier
	s_waitcnt lgkmcnt(0)
	v_mfma_f32_16x16x32_bf16 v[152:155], v[48:51], v[112:115], v[152:155]
	v_mfma_f32_16x16x32_bf16 v[68:71], v[104:107], v[112:115], v[68:71]
	v_mfma_f32_16x16x32_bf16 v[148:151], v[48:51], v[120:123], v[148:151]
	v_mfma_f32_16x16x32_bf16 v[64:67], v[104:107], v[120:123], v[64:67]
	v_mfma_f32_16x16x32_bf16 v[136:139], v[48:51], v[160:163], v[136:139]
	v_mfma_f32_16x16x32_bf16 v[44:47], v[104:107], v[160:163], v[44:47]
	v_mfma_f32_16x16x32_bf16 v[128:131], v[48:51], v[190:193], v[128:131]
	v_mfma_f32_16x16x32_bf16 v[40:43], v[104:107], v[190:193], v[40:43]
	v_mfma_f32_16x16x32_bf16 v[152:155], v[52:55], v[116:119], v[152:155]
	v_mfma_f32_16x16x32_bf16 v[68:71], v[108:111], v[116:119], v[68:71]
	v_mfma_f32_16x16x32_bf16 v[148:151], v[52:55], v[156:159], v[148:151]
	v_mfma_f32_16x16x32_bf16 v[64:67], v[108:111], v[156:159], v[64:67]
	v_mfma_f32_16x16x32_bf16 v[136:139], v[52:55], v[164:167], v[136:139]
	v_mfma_f32_16x16x32_bf16 v[44:47], v[108:111], v[164:167], v[44:47]
	v_mfma_f32_16x16x32_bf16 v[128:131], v[52:55], v[194:197], v[128:131]
	v_mfma_f32_16x16x32_bf16 v[40:43], v[108:111], v[194:197], v[40:43]
	s_barrier
	s_add_i32 s70, 0, 0x14000
	s_add_i32 s68, s68, s53
	v_add_u32_e32 v210, s70, v237
	v_lshl_add_u64 v[218:219], s[2:3], 0, v[168:169]
	s_mov_b32 m0, s68
	ds_read_b128 v[198:201], v210
	ds_read_b128 v[202:205], v210 offset:1024
	ds_read_b128 v[206:209], v210 offset:2048
	ds_read_b128 v[210:213], v210 offset:3072
	global_load_lds_dwordx4 v[218:219], off
	s_add_i32 m0, s68, 0x2000
	v_lshl_add_u64 v[220:221], s[2:3], 0, v[184:185]
	global_load_lds_dwordx4 v[220:221], off
	s_barrier
	s_waitcnt lgkmcnt(0)
	v_mfma_f32_16x16x32_bf16 v[144:147], v[198:201], v[112:115], v[144:147]
	v_mfma_f32_16x16x32_bf16 v[60:63], v[206:209], v[112:115], v[60:63]
	v_mfma_f32_16x16x32_bf16 v[56:59], v[206:209], v[120:123], v[56:59]
	v_mfma_f32_16x16x32_bf16 v[36:39], v[206:209], v[160:163], v[36:39]
	v_mfma_f32_16x16x32_bf16 v[32:35], v[206:209], v[190:193], v[32:35]
	v_mfma_f32_16x16x32_bf16 v[144:147], v[202:205], v[116:119], v[144:147]
	v_mfma_f32_16x16x32_bf16 v[60:63], v[210:213], v[116:119], v[60:63]
	v_mfma_f32_16x16x32_bf16 v[112:115], v[198:201], v[120:123], v[140:143]
	v_mfma_f32_16x16x32_bf16 v[56:59], v[210:213], v[156:159], v[56:59]
	v_mfma_f32_16x16x32_bf16 v[116:119], v[198:201], v[160:163], v[132:135]
	v_mfma_f32_16x16x32_bf16 v[36:39], v[210:213], v[164:167], v[36:39]
	v_mfma_f32_16x16x32_bf16 v[120:123], v[198:201], v[190:193], v[124:127]
	v_mfma_f32_16x16x32_bf16 v[32:35], v[210:213], v[194:197], v[32:35]
	v_mfma_f32_16x16x32_bf16 v[112:115], v[202:205], v[156:159], v[112:115]
	v_mfma_f32_16x16x32_bf16 v[116:119], v[202:205], v[164:167], v[116:119]
	v_mfma_f32_16x16x32_bf16 v[120:123], v[202:205], v[194:197], v[120:123]
	s_mov_b32 m0, s54
	v_lshl_add_u64 v[222:223], s[12:13], 0, v[180:181]
	s_barrier
	ds_read_b128 v[124:127], v238 offset:16384
	ds_read_b128 v[132:135], v238 offset:17408
	ds_read_b128 v[140:143], v238 offset:18432
	ds_read_b128 v[156:159], v238 offset:19456
	ds_read_b128 v[160:163], v238 offset:20480
	ds_read_b128 v[164:167], v238 offset:21504
	ds_read_b128 v[190:193], v238 offset:22528
	ds_read_b128 v[194:197], v238 offset:23552
	global_load_lds_dwordx4 v[222:223], off
	s_mov_b32 m0, s55
	v_lshl_add_u64 v[240:241], s[12:13], 0, v[182:183]
	global_load_lds_dwordx4 v[240:241], off
	s_barrier
	s_waitcnt lgkmcnt(0)
	v_mfma_f32_16x16x32_bf16 v[100:103], v[48:51], v[124:127], v[100:103]
	v_mfma_f32_16x16x32_bf16 v[28:31], v[104:107], v[124:127], v[28:31]
	v_mfma_f32_16x16x32_bf16 v[96:99], v[48:51], v[140:143], v[96:99]
	v_mfma_f32_16x16x32_bf16 v[24:27], v[104:107], v[140:143], v[24:27]
	v_mfma_f32_16x16x32_bf16 v[84:87], v[48:51], v[160:163], v[84:87]
	v_mfma_f32_16x16x32_bf16 v[12:15], v[104:107], v[160:163], v[12:15]
	v_mfma_f32_16x16x32_bf16 v[8:11], v[104:107], v[190:193], v[8:11]
	v_mfma_f32_16x16x32_bf16 v[100:103], v[52:55], v[132:135], v[100:103]
	v_mfma_f32_16x16x32_bf16 v[28:31], v[108:111], v[132:135], v[28:31]
	v_mfma_f32_16x16x32_bf16 v[96:99], v[52:55], v[156:159], v[96:99]
	v_mfma_f32_16x16x32_bf16 v[24:27], v[108:111], v[156:159], v[24:27]
	v_mfma_f32_16x16x32_bf16 v[84:87], v[52:55], v[164:167], v[84:87]
	v_mfma_f32_16x16x32_bf16 v[12:15], v[108:111], v[164:167], v[12:15]
	v_mfma_f32_16x16x32_bf16 v[48:51], v[48:51], v[190:193], v[76:79]
	v_mfma_f32_16x16x32_bf16 v[8:11], v[108:111], v[194:197], v[8:11]
	v_mfma_f32_16x16x32_bf16 v[48:51], v[52:55], v[194:197], v[48:51]
	s_barrier
	s_add_u32 s68, s2, 0x40000
	s_addc_u32 s69, s3, 0
	s_add_i32 s70, s70, s53
	s_mov_b32 m0, s70
	v_lshl_add_u64 v[52:53], s[68:69], 0, v[168:169]
	global_load_lds_dwordx4 v[52:53], off
	s_add_i32 m0, s70, 0x2000
	v_lshl_add_u64 v[52:53], s[68:69], 0, v[184:185]
	global_load_lds_dwordx4 v[52:53], off
	s_waitcnt vmcnt(6)
	s_barrier
	v_mfma_f32_16x16x32_bf16 v[76:79], v[198:201], v[140:143], v[88:91]
	v_mfma_f32_16x16x32_bf16 v[20:23], v[206:209], v[124:127], v[20:23]
	v_mfma_f32_16x16x32_bf16 v[88:91], v[202:205], v[156:159], v[76:79]
	v_mfma_f32_16x16x32_bf16 v[16:19], v[206:209], v[140:143], v[16:19]
	v_mfma_f32_16x16x32_bf16 v[76:79], v[198:201], v[160:163], v[80:83]
	v_mfma_f32_16x16x32_bf16 v[4:7], v[206:209], v[160:163], v[4:7]
	v_mfma_f32_16x16x32_bf16 v[72:75], v[198:201], v[190:193], v[72:75]
	v_mfma_f32_16x16x32_bf16 v[0:3], v[206:209], v[190:193], v[0:3]
	v_mfma_f32_16x16x32_bf16 v[52:55], v[198:201], v[124:127], v[92:95]
	v_mfma_f32_16x16x32_bf16 v[20:23], v[210:213], v[132:135], v[20:23]
	v_mfma_f32_16x16x32_bf16 v[16:19], v[210:213], v[156:159], v[16:19]
	v_mfma_f32_16x16x32_bf16 v[80:83], v[202:205], v[164:167], v[76:79]
	v_mfma_f32_16x16x32_bf16 v[4:7], v[210:213], v[164:167], v[4:7]
	v_mfma_f32_16x16x32_bf16 v[72:75], v[202:205], v[194:197], v[72:75]
	v_mfma_f32_16x16x32_bf16 v[0:3], v[210:213], v[194:197], v[0:3]
	v_mfma_f32_16x16x32_bf16 v[52:55], v[202:205], v[132:135], v[52:55]
	s_add_i32 s68, 0, 0x18000
	v_add_u32_e32 v108, s68, v237
	s_barrier
	ds_read_b128 v[76:79], v108
	ds_read_b128 v[92:95], v108 offset:1024
	ds_read_b128 v[104:107], v108 offset:2048
	ds_read_b128 v[108:111], v108 offset:3072
	s_add_u32 s12, s12, 0x40000
	s_addc_u32 s13, s13, 0
	s_mov_b32 m0, s56
	v_lshl_add_u64 v[140:141], s[12:13], 0, v[180:181]
	ds_read_b128 v[124:127], v238 offset:32768
	ds_read_b128 v[132:135], v238 offset:33792
	ds_read_b128 v[156:159], v238 offset:34816
	ds_read_b128 v[160:163], v238 offset:35840
	ds_read_b128 v[164:167], v238 offset:36864
	ds_read_b128 v[190:193], v238 offset:37888
	ds_read_b128 v[194:197], v238 offset:38912
	ds_read_b128 v[198:201], v238 offset:39936
	global_load_lds_dwordx4 v[140:141], off
	s_mov_b32 m0, s57
	v_lshl_add_u64 v[140:141], s[12:13], 0, v[182:183]
	global_load_lds_dwordx4 v[140:141], off
	s_waitcnt lgkmcnt(8)
	s_barrier
	s_waitcnt lgkmcnt(0)
	v_mfma_f32_16x16x32_bf16 v[140:143], v[76:79], v[124:127], v[152:155]
	v_mfma_f32_16x16x32_bf16 v[152:155], v[92:95], v[132:135], v[140:143]
	v_mfma_f32_16x16x32_bf16 v[68:71], v[104:107], v[124:127], v[68:71]
	v_mfma_f32_16x16x32_bf16 v[140:143], v[76:79], v[156:159], v[148:151]
	v_mfma_f32_16x16x32_bf16 v[64:67], v[104:107], v[156:159], v[64:67]
	v_mfma_f32_16x16x32_bf16 v[136:139], v[76:79], v[164:167], v[136:139]
	v_mfma_f32_16x16x32_bf16 v[44:47], v[104:107], v[164:167], v[44:47]
	v_mfma_f32_16x16x32_bf16 v[128:131], v[76:79], v[194:197], v[128:131]
	v_mfma_f32_16x16x32_bf16 v[40:43], v[104:107], v[194:197], v[40:43]
	v_mfma_f32_16x16x32_bf16 v[68:71], v[108:111], v[132:135], v[68:71]
	v_mfma_f32_16x16x32_bf16 v[148:151], v[92:95], v[160:163], v[140:143]
	v_mfma_f32_16x16x32_bf16 v[64:67], v[108:111], v[160:163], v[64:67]
	v_mfma_f32_16x16x32_bf16 v[136:139], v[92:95], v[190:193], v[136:139]
	v_mfma_f32_16x16x32_bf16 v[44:47], v[108:111], v[190:193], v[44:47]
	v_mfma_f32_16x16x32_bf16 v[128:131], v[92:95], v[198:201], v[128:131]
	v_mfma_f32_16x16x32_bf16 v[40:43], v[108:111], v[198:201], v[40:43]
	s_barrier
	s_add_i32 s12, 0, 0x1c000
	v_add_u32_e32 v140, s12, v237
	s_add_i32 s13, s68, s53
	ds_read_b128 v[202:205], v140
	ds_read_b128 v[206:209], v140 offset:1024
	ds_read_b128 v[210:213], v140 offset:2048
	ds_read_b128 v[214:217], v140 offset:3072
	s_mov_b32 m0, s13
	v_lshl_add_u64 v[140:141], v[218:219], 0, s[78:79]
	global_load_lds_dwordx4 v[140:141], off
	s_add_i32 m0, s13, 0x2000
	v_lshl_add_u64 v[140:141], v[220:221], 0, s[78:79]
	global_load_lds_dwordx4 v[140:141], off
	s_barrier
	s_waitcnt lgkmcnt(0)
	v_mfma_f32_16x16x32_bf16 v[140:143], v[202:205], v[124:127], v[144:147]
	v_mfma_f32_16x16x32_bf16 v[112:115], v[202:205], v[156:159], v[112:115]
	v_mfma_f32_16x16x32_bf16 v[144:147], v[206:209], v[132:135], v[140:143]
	v_mfma_f32_16x16x32_bf16 v[60:63], v[210:213], v[124:127], v[60:63]
	v_mfma_f32_16x16x32_bf16 v[140:143], v[206:209], v[160:163], v[112:115]
	v_mfma_f32_16x16x32_bf16 v[112:115], v[202:205], v[164:167], v[116:119]
	v_mfma_f32_16x16x32_bf16 v[60:63], v[214:217], v[132:135], v[60:63]
	v_mfma_f32_16x16x32_bf16 v[56:59], v[210:213], v[156:159], v[56:59]
	v_mfma_f32_16x16x32_bf16 v[132:135], v[206:209], v[190:193], v[112:115]
	v_mfma_f32_16x16x32_bf16 v[36:39], v[210:213], v[164:167], v[36:39]
	v_mfma_f32_16x16x32_bf16 v[112:115], v[202:205], v[194:197], v[120:123]
	v_mfma_f32_16x16x32_bf16 v[32:35], v[210:213], v[194:197], v[32:35]
	v_mfma_f32_16x16x32_bf16 v[56:59], v[214:217], v[160:163], v[56:59]
	v_mfma_f32_16x16x32_bf16 v[36:39], v[214:217], v[190:193], v[36:39]
	v_mfma_f32_16x16x32_bf16 v[124:127], v[206:209], v[198:201], v[112:115]
	v_mfma_f32_16x16x32_bf16 v[32:35], v[214:217], v[198:201], v[32:35]
	s_mov_b32 m0, s62
	v_lshl_add_u64 v[198:199], v[222:223], 0, s[78:79]
	s_barrier
	ds_read_b128 v[112:115], v238 offset:49152
	ds_read_b128 v[116:119], v238 offset:50176
	ds_read_b128 v[120:123], v238 offset:51200
	ds_read_b128 v[156:159], v238 offset:52224
	ds_read_b128 v[160:163], v238 offset:53248
	ds_read_b128 v[164:167], v238 offset:54272
	ds_read_b128 v[190:193], v238 offset:55296
	ds_read_b128 v[194:197], v238 offset:56320
	global_load_lds_dwordx4 v[198:199], off
	s_mov_b32 m0, s63
	v_lshl_add_u64 v[198:199], v[240:241], 0, s[78:79]
	global_load_lds_dwordx4 v[198:199], off
	s_barrier
	s_waitcnt lgkmcnt(0)
	v_mfma_f32_16x16x32_bf16 v[100:103], v[76:79], v[112:115], v[100:103]
	v_mfma_f32_16x16x32_bf16 v[28:31], v[104:107], v[112:115], v[28:31]
	v_mfma_f32_16x16x32_bf16 v[96:99], v[76:79], v[120:123], v[96:99]
	v_mfma_f32_16x16x32_bf16 v[24:27], v[104:107], v[120:123], v[24:27]
	v_mfma_f32_16x16x32_bf16 v[84:87], v[76:79], v[160:163], v[84:87]
	v_mfma_f32_16x16x32_bf16 v[12:15], v[104:107], v[160:163], v[12:15]
	v_mfma_f32_16x16x32_bf16 v[48:51], v[76:79], v[190:193], v[48:51]
	v_mfma_f32_16x16x32_bf16 v[8:11], v[104:107], v[190:193], v[8:11]
	v_mfma_f32_16x16x32_bf16 v[100:103], v[92:95], v[116:119], v[100:103]
	v_mfma_f32_16x16x32_bf16 v[28:31], v[108:111], v[116:119], v[28:31]
	v_mfma_f32_16x16x32_bf16 v[96:99], v[92:95], v[156:159], v[96:99]
	v_mfma_f32_16x16x32_bf16 v[24:27], v[108:111], v[156:159], v[24:27]
	v_mfma_f32_16x16x32_bf16 v[84:87], v[92:95], v[164:167], v[84:87]
	v_mfma_f32_16x16x32_bf16 v[12:15], v[108:111], v[164:167], v[12:15]
	v_mfma_f32_16x16x32_bf16 v[76:79], v[92:95], v[194:197], v[48:51]
	v_mfma_f32_16x16x32_bf16 v[8:11], v[108:111], v[194:197], v[8:11]
	s_barrier
	s_add_u32 s2, s2, 0x40080
	s_addc_u32 s3, s3, 0
	s_add_i32 s12, s12, s53
	s_mov_b32 m0, s12
	v_lshl_add_u64 v[48:49], s[2:3], 0, v[168:169]
	global_load_lds_dwordx4 v[48:49], off
	s_add_i32 m0, s12, 0x2000
	v_lshl_add_u64 v[48:49], s[2:3], 0, v[184:185]
	global_load_lds_dwordx4 v[48:49], off
	s_waitcnt vmcnt(6)
	s_barrier
	v_mfma_f32_16x16x32_bf16 v[48:51], v[202:205], v[112:115], v[52:55]
	v_mfma_f32_16x16x32_bf16 v[92:95], v[206:209], v[116:119], v[48:51]
	v_mfma_f32_16x16x32_bf16 v[48:51], v[202:205], v[120:123], v[88:91]
	v_mfma_f32_16x16x32_bf16 v[88:91], v[206:209], v[156:159], v[48:51]
	v_mfma_f32_16x16x32_bf16 v[48:51], v[202:205], v[160:163], v[80:83]
	v_mfma_f32_16x16x32_bf16 v[20:23], v[210:213], v[112:115], v[20:23]
	v_mfma_f32_16x16x32_bf16 v[16:19], v[210:213], v[120:123], v[16:19]
	v_mfma_f32_16x16x32_bf16 v[80:83], v[206:209], v[164:167], v[48:51]
	v_mfma_f32_16x16x32_bf16 v[4:7], v[210:213], v[160:163], v[4:7]
	v_mfma_f32_16x16x32_bf16 v[48:51], v[202:205], v[190:193], v[72:75]
	v_mfma_f32_16x16x32_bf16 v[0:3], v[210:213], v[190:193], v[0:3]
	v_mfma_f32_16x16x32_bf16 v[20:23], v[214:217], v[116:119], v[20:23]
	v_mfma_f32_16x16x32_bf16 v[16:19], v[214:217], v[156:159], v[16:19]
	v_mfma_f32_16x16x32_bf16 v[4:7], v[214:217], v[164:167], v[4:7]
	v_mfma_f32_16x16x32_bf16 v[72:75], v[206:209], v[194:197], v[48:51]
	v_mfma_f32_16x16x32_bf16 v[0:3], v[214:217], v[194:197], v[0:3]
	s_add_i32 s67, s67, 2
	s_add_u32 s10, s10, 0x100
	s_addc_u32 s11, s11, 0
	s_add_u32 s37, s37, 0x100
	s_addc_u32 s39, s39, 0
	s_cmp_gt_u32 s67, 13
	s_barrier
	s_cbranch_scc0 .LBB0_880

.Lup_half_peel:
	s_add_u32 s2, s10, 0xfffc0080
	s_addc_u32 s3, s11, -1
	s_add_i32 s68, 0, 0x10000
	v_add_u32_e32 v108, s68, v237
	ds_read_b128 v[48:51], v108
	ds_read_b128 v[52:55], v108 offset:1024
	ds_read_b128 v[104:107], v108 offset:2048
	ds_read_b128 v[108:111], v108 offset:3072
	s_cmp_eq_u32 s67, 12
	s_cselect_b32 s13, s1, s3
	s_cselect_b32 s12, s9, s2
	s_cselect_b32 s3, s14, s39
	s_cselect_b32 s2, s15, s37
	v_lshl_add_u64 v[198:199], s[10:11], 0, v[186:187]
	s_add_i32 m0, s54, 0xc000
	ds_read_b128 v[112:115], v238
	ds_read_b128 v[116:119], v238 offset:1024
	ds_read_b128 v[120:123], v238 offset:2048
	ds_read_b128 v[156:159], v238 offset:3072
	ds_read_b128 v[160:163], v238 offset:4096
	ds_read_b128 v[164:167], v238 offset:5120
	ds_read_b128 v[190:193], v238 offset:6144
	ds_read_b128 v[194:197], v238 offset:7168
	global_load_lds_dwordx4 v[198:199], off
	s_add_i32 m0, s54, 0xe000
	v_lshl_add_u64 v[198:199], s[10:11], 0, v[188:189]
	global_load_lds_dwordx4 v[198:199], off
	s_waitcnt lgkmcnt(8)
	s_barrier
	s_waitcnt lgkmcnt(0)
	v_mfma_f32_16x16x32_bf16 v[152:155], v[48:51], v[112:115], 0
	v_mfma_f32_16x16x32_bf16 v[68:71], v[104:107], v[112:115], 0
	v_mfma_f32_16x16x32_bf16 v[148:151], v[48:51], v[120:123], 0
	v_mfma_f32_16x16x32_bf16 v[64:67], v[104:107], v[120:123], 0
	v_mfma_f32_16x16x32_bf16 v[136:139], v[48:51], v[160:163], 0
	v_mfma_f32_16x16x32_bf16 v[44:47], v[104:107], v[160:163], 0
	v_mfma_f32_16x16x32_bf16 v[128:131], v[48:51], v[190:193], 0
	v_mfma_f32_16x16x32_bf16 v[40:43], v[104:107], v[190:193], 0
	v_mfma_f32_16x16x32_bf16 v[152:155], v[52:55], v[116:119], v[152:155]
	v_mfma_f32_16x16x32_bf16 v[68:71], v[108:111], v[116:119], v[68:71]
	v_mfma_f32_16x16x32_bf16 v[148:151], v[52:55], v[156:159], v[148:151]
	v_mfma_f32_16x16x32_bf16 v[64:67], v[108:111], v[156:159], v[64:67]
	v_mfma_f32_16x16x32_bf16 v[136:139], v[52:55], v[164:167], v[136:139]
	v_mfma_f32_16x16x32_bf16 v[44:47], v[108:111], v[164:167], v[44:47]
	v_mfma_f32_16x16x32_bf16 v[128:131], v[52:55], v[194:197], v[128:131]
	v_mfma_f32_16x16x32_bf16 v[40:43], v[108:111], v[194:197], v[40:43]
	s_barrier
	s_add_i32 s70, 0, 0x14000
	s_add_i32 s68, s68, s53
	v_add_u32_e32 v210, s70, v237
	v_lshl_add_u64 v[218:219], s[2:3], 0, v[168:169]
	s_mov_b32 m0, s68
	ds_read_b128 v[198:201], v210
	ds_read_b128 v[202:205], v210 offset:1024
	ds_read_b128 v[206:209], v210 offset:2048
	ds_read_b128 v[210:213], v210 offset:3072
	global_load_lds_dwordx4 v[218:219], off
	s_add_i32 m0, s68, 0x2000
	v_lshl_add_u64 v[220:221], s[2:3], 0, v[184:185]
	global_load_lds_dwordx4 v[220:221], off
	s_barrier
	s_waitcnt lgkmcnt(0)
	v_mfma_f32_16x16x32_bf16 v[144:147], v[198:201], v[112:115], 0
	v_mfma_f32_16x16x32_bf16 v[60:63], v[206:209], v[112:115], 0
	v_mfma_f32_16x16x32_bf16 v[56:59], v[206:209], v[120:123], 0
	v_mfma_f32_16x16x32_bf16 v[36:39], v[206:209], v[160:163], 0
	v_mfma_f32_16x16x32_bf16 v[32:35], v[206:209], v[190:193], 0
	v_mfma_f32_16x16x32_bf16 v[144:147], v[202:205], v[116:119], v[144:147]
	v_mfma_f32_16x16x32_bf16 v[60:63], v[210:213], v[116:119], v[60:63]
	v_mfma_f32_16x16x32_bf16 v[112:115], v[198:201], v[120:123], 0
	v_mfma_f32_16x16x32_bf16 v[56:59], v[210:213], v[156:159], v[56:59]
	v_mfma_f32_16x16x32_bf16 v[116:119], v[198:201], v[160:163], 0
	v_mfma_f32_16x16x32_bf16 v[36:39], v[210:213], v[164:167], v[36:39]
	v_mfma_f32_16x16x32_bf16 v[120:123], v[198:201], v[190:193], 0
	v_mfma_f32_16x16x32_bf16 v[32:35], v[210:213], v[194:197], v[32:35]
	v_mfma_f32_16x16x32_bf16 v[112:115], v[202:205], v[156:159], v[112:115]
	v_mfma_f32_16x16x32_bf16 v[116:119], v[202:205], v[164:167], v[116:119]
	v_mfma_f32_16x16x32_bf16 v[120:123], v[202:205], v[194:197], v[120:123]
	s_mov_b32 m0, s54
	v_lshl_add_u64 v[222:223], s[12:13], 0, v[180:181]
	s_barrier
	ds_read_b128 v[124:127], v238 offset:16384
	ds_read_b128 v[132:135], v238 offset:17408
	ds_read_b128 v[140:143], v238 offset:18432
	ds_read_b128 v[156:159], v238 offset:19456
	ds_read_b128 v[160:163], v238 offset:20480
	ds_read_b128 v[164:167], v238 offset:21504
	ds_read_b128 v[190:193], v238 offset:22528
	ds_read_b128 v[194:197], v238 offset:23552
	global_load_lds_dwordx4 v[222:223], off
	s_mov_b32 m0, s55
	v_lshl_add_u64 v[240:241], s[12:13], 0, v[182:183]
	global_load_lds_dwordx4 v[240:241], off
	s_barrier
	s_waitcnt lgkmcnt(0)
	s_barrier
	s_add_u32 s68, s2, 0x40000
	s_addc_u32 s69, s3, 0
	s_add_i32 s70, s70, s53
	s_mov_b32 m0, s70
	v_lshl_add_u64 v[52:53], s[68:69], 0, v[168:169]
	global_load_lds_dwordx4 v[52:53], off
	s_add_i32 m0, s70, 0x2000
	v_lshl_add_u64 v[52:53], s[68:69], 0, v[184:185]
	global_load_lds_dwordx4 v[52:53], off
	s_waitcnt vmcnt(6)
	s_barrier
	s_add_i32 s68, 0, 0x18000
	v_add_u32_e32 v108, s68, v237
	s_barrier
	ds_read_b128 v[76:79], v108
	ds_read_b128 v[92:95], v108 offset:1024
	ds_read_b128 v[104:107], v108 offset:2048
	ds_read_b128 v[108:111], v108 offset:3072
	s_add_u32 s12, s12, 0x40000
	s_addc_u32 s13, s13, 0
	s_mov_b32 m0, s56
	v_lshl_add_u64 v[140:141], s[12:13], 0, v[180:181]
	ds_read_b128 v[124:127], v238 offset:32768
	ds_read_b128 v[132:135], v238 offset:33792
	ds_read_b128 v[156:159], v238 offset:34816
	ds_read_b128 v[160:163], v238 offset:35840
	ds_read_b128 v[164:167], v238 offset:36864
	ds_read_b128 v[190:193], v238 offset:37888
	ds_read_b128 v[194:197], v238 offset:38912
	ds_read_b128 v[198:201], v238 offset:39936
	global_load_lds_dwordx4 v[140:141], off
	s_mov_b32 m0, s57
	v_lshl_add_u64 v[140:141], s[12:13], 0, v[182:183]
	global_load_lds_dwordx4 v[140:141], off
	s_waitcnt lgkmcnt(8)
	s_barrier
	s_waitcnt lgkmcnt(0)
	v_mfma_f32_16x16x32_bf16 v[140:143], v[76:79], v[124:127], v[152:155]
	v_mfma_f32_16x16x32_bf16 v[152:155], v[92:95], v[132:135], v[140:143]
	v_mfma_f32_16x16x32_bf16 v[68:71], v[104:107], v[124:127], v[68:71]
	v_mfma_f32_16x16x32_bf16 v[140:143], v[76:79], v[156:159], v[148:151]
	v_mfma_f32_16x16x32_bf16 v[64:67], v[104:107], v[156:159], v[64:67]
	v_mfma_f32_16x16x32_bf16 v[136:139], v[76:79], v[164:167], v[136:139]
	v_mfma_f32_16x16x32_bf16 v[44:47], v[104:107], v[164:167], v[44:47]
	v_mfma_f32_16x16x32_bf16 v[128:131], v[76:79], v[194:197], v[128:131]
	v_mfma_f32_16x16x32_bf16 v[40:43], v[104:107], v[194:197], v[40:43]
	v_mfma_f32_16x16x32_bf16 v[68:71], v[108:111], v[132:135], v[68:71]
	v_mfma_f32_16x16x32_bf16 v[148:151], v[92:95], v[160:163], v[140:143]
	v_mfma_f32_16x16x32_bf16 v[64:67], v[108:111], v[160:163], v[64:67]
	v_mfma_f32_16x16x32_bf16 v[136:139], v[92:95], v[190:193], v[136:139]
	v_mfma_f32_16x16x32_bf16 v[44:47], v[108:111], v[190:193], v[44:47]
	v_mfma_f32_16x16x32_bf16 v[128:131], v[92:95], v[198:201], v[128:131]
	v_mfma_f32_16x16x32_bf16 v[40:43], v[108:111], v[198:201], v[40:43]
	s_barrier
	s_add_i32 s12, 0, 0x1c000
	v_add_u32_e32 v140, s12, v237
	s_add_i32 s13, s68, s53
	ds_read_b128 v[202:205], v140
	ds_read_b128 v[206:209], v140 offset:1024
	ds_read_b128 v[210:213], v140 offset:2048
	ds_read_b128 v[214:217], v140 offset:3072
	s_mov_b32 m0, s13
	v_lshl_add_u64 v[140:141], v[218:219], 0, s[78:79]
	global_load_lds_dwordx4 v[140:141], off
	s_add_i32 m0, s13, 0x2000
	v_lshl_add_u64 v[140:141], v[220:221], 0, s[78:79]
	global_load_lds_dwordx4 v[140:141], off
	s_barrier
	s_waitcnt lgkmcnt(0)
	v_mfma_f32_16x16x32_bf16 v[140:143], v[202:205], v[124:127], v[144:147]
	v_mfma_f32_16x16x32_bf16 v[112:115], v[202:205], v[156:159], v[112:115]
	v_mfma_f32_16x16x32_bf16 v[144:147], v[206:209], v[132:135], v[140:143]
	v_mfma_f32_16x16x32_bf16 v[60:63], v[210:213], v[124:127], v[60:63]
	v_mfma_f32_16x16x32_bf16 v[140:143], v[206:209], v[160:163], v[112:115]
	v_mfma_f32_16x16x32_bf16 v[112:115], v[202:205], v[164:167], v[116:119]
	v_mfma_f32_16x16x32_bf16 v[60:63], v[214:217], v[132:135], v[60:63]
	v_mfma_f32_16x16x32_bf16 v[56:59], v[210:213], v[156:159], v[56:59]
	v_mfma_f32_16x16x32_bf16 v[132:135], v[206:209], v[190:193], v[112:115]
	v_mfma_f32_16x16x32_bf16 v[36:39], v[210:213], v[164:167], v[36:39]
	v_mfma_f32_16x16x32_bf16 v[112:115], v[202:205], v[194:197], v[120:123]
	v_mfma_f32_16x16x32_bf16 v[32:35], v[210:213], v[194:197], v[32:35]
	v_mfma_f32_16x16x32_bf16 v[56:59], v[214:217], v[160:163], v[56:59]
	v_mfma_f32_16x16x32_bf16 v[36:39], v[214:217], v[190:193], v[36:39]
	v_mfma_f32_16x16x32_bf16 v[124:127], v[206:209], v[198:201], v[112:115]
	v_mfma_f32_16x16x32_bf16 v[32:35], v[214:217], v[198:201], v[32:35]
	s_mov_b32 m0, s62
	v_lshl_add_u64 v[198:199], v[222:223], 0, s[78:79]
	s_barrier
	ds_read_b128 v[112:115], v238 offset:49152
	ds_read_b128 v[116:119], v238 offset:50176
	ds_read_b128 v[120:123], v238 offset:51200
	ds_read_b128 v[156:159], v238 offset:52224
	ds_read_b128 v[160:163], v238 offset:53248
	ds_read_b128 v[164:167], v238 offset:54272
	ds_read_b128 v[190:193], v238 offset:55296
	ds_read_b128 v[194:197], v238 offset:56320
	global_load_lds_dwordx4 v[198:199], off
	s_mov_b32 m0, s63
	v_lshl_add_u64 v[198:199], v[240:241], 0, s[78:79]
	global_load_lds_dwordx4 v[198:199], off
	s_barrier
	s_waitcnt lgkmcnt(0)
	s_barrier
	s_add_u32 s2, s2, 0x40080
	s_addc_u32 s3, s3, 0
	s_add_i32 s12, s12, s53
	s_mov_b32 m0, s12
	v_lshl_add_u64 v[48:49], s[2:3], 0, v[168:169]
	global_load_lds_dwordx4 v[48:49], off
	s_add_i32 m0, s12, 0x2000
	v_lshl_add_u64 v[48:49], s[2:3], 0, v[184:185]
	global_load_lds_dwordx4 v[48:49], off
	s_waitcnt vmcnt(6)
	s_barrier
	s_add_i32 s67, s67, 2
	s_add_u32 s10, s10, 0x100
	s_addc_u32 s11, s11, 0
	s_add_u32 s37, s37, 0x100
	s_addc_u32 s39, s39, 0
	s_cmp_gt_u32 s67, 13
	s_barrier
.Lup_half_loop:
	s_add_u32 s2, s10, 0xfffc0080
	s_addc_u32 s3, s11, -1
	s_add_i32 s68, 0, 0x10000
	v_add_u32_e32 v108, s68, v237
	ds_read_b128 v[48:51], v108
	ds_read_b128 v[52:55], v108 offset:1024
	ds_read_b128 v[104:107], v108 offset:2048
	ds_read_b128 v[108:111], v108 offset:3072
	s_cmp_eq_u32 s67, 12
	s_cselect_b32 s13, s1, s3
	s_cselect_b32 s12, s9, s2
	s_cselect_b32 s3, s14, s39
	s_cselect_b32 s2, s15, s37
	v_lshl_add_u64 v[198:199], s[10:11], 0, v[186:187]
	s_add_i32 m0, s54, 0xc000
	ds_read_b128 v[112:115], v238
	ds_read_b128 v[116:119], v238 offset:1024
	ds_read_b128 v[120:123], v238 offset:2048
	ds_read_b128 v[156:159], v238 offset:3072
	ds_read_b128 v[160:163], v238 offset:4096
	ds_read_b128 v[164:167], v238 offset:5120
	ds_read_b128 v[190:193], v238 offset:6144
	ds_read_b128 v[194:197], v238 offset:7168
	global_load_lds_dwordx4 v[198:199], off
	s_add_i32 m0, s54, 0xe000
	v_lshl_add_u64 v[198:199], s[10:11], 0, v[188:189]
	global_load_lds_dwordx4 v[198:199], off
	s_waitcnt lgkmcnt(8)
	s_barrier
	s_waitcnt lgkmcnt(0)
	v_mfma_f32_16x16x32_bf16 v[152:155], v[48:51], v[112:115], v[152:155]
	v_mfma_f32_16x16x32_bf16 v[68:71], v[104:107], v[112:115], v[68:71]
	v_mfma_f32_16x16x32_bf16 v[148:151], v[48:51], v[120:123], v[148:151]
	v_mfma_f32_16x16x32_bf16 v[64:67], v[104:107], v[120:123], v[64:67]
	v_mfma_f32_16x16x32_bf16 v[136:139], v[48:51], v[160:163], v[136:139]
	v_mfma_f32_16x16x32_bf16 v[44:47], v[104:107], v[160:163], v[44:47]
	v_mfma_f32_16x16x32_bf16 v[128:131], v[48:51], v[190:193], v[128:131]
	v_mfma_f32_16x16x32_bf16 v[40:43], v[104:107], v[190:193], v[40:43]
	v_mfma_f32_16x16x32_bf16 v[152:155], v[52:55], v[116:119], v[152:155]
	v_mfma_f32_16x16x32_bf16 v[68:71], v[108:111], v[116:119], v[68:71]
	v_mfma_f32_16x16x32_bf16 v[148:151], v[52:55], v[156:159], v[148:151]
	v_mfma_f32_16x16x32_bf16 v[64:67], v[108:111], v[156:159], v[64:67]
	v_mfma_f32_16x16x32_bf16 v[136:139], v[52:55], v[164:167], v[136:139]
	v_mfma_f32_16x16x32_bf16 v[44:47], v[108:111], v[164:167], v[44:47]
	v_mfma_f32_16x16x32_bf16 v[128:131], v[52:55], v[194:197], v[128:131]
	v_mfma_f32_16x16x32_bf16 v[40:43], v[108:111], v[194:197], v[40:43]
	s_barrier
	s_add_i32 s70, 0, 0x14000
	s_add_i32 s68, s68, s53
	v_add_u32_e32 v210, s70, v237
	v_lshl_add_u64 v[218:219], s[2:3], 0, v[168:169]
	s_mov_b32 m0, s68
	ds_read_b128 v[198:201], v210
	ds_read_b128 v[202:205], v210 offset:1024
	ds_read_b128 v[206:209], v210 offset:2048
	ds_read_b128 v[210:213], v210 offset:3072
	global_load_lds_dwordx4 v[218:219], off
	s_add_i32 m0, s68, 0x2000
	v_lshl_add_u64 v[220:221], s[2:3], 0, v[184:185]
	global_load_lds_dwordx4 v[220:221], off
	s_barrier
	s_waitcnt lgkmcnt(0)
	v_mfma_f32_16x16x32_bf16 v[144:147], v[198:201], v[112:115], v[144:147]
	v_mfma_f32_16x16x32_bf16 v[60:63], v[206:209], v[112:115], v[60:63]
	v_mfma_f32_16x16x32_bf16 v[56:59], v[206:209], v[120:123], v[56:59]
	v_mfma_f32_16x16x32_bf16 v[36:39], v[206:209], v[160:163], v[36:39]
	v_mfma_f32_16x16x32_bf16 v[32:35], v[206:209], v[190:193], v[32:35]
	v_mfma_f32_16x16x32_bf16 v[144:147], v[202:205], v[116:119], v[144:147]
	v_mfma_f32_16x16x32_bf16 v[60:63], v[210:213], v[116:119], v[60:63]
	v_mfma_f32_16x16x32_bf16 v[112:115], v[198:201], v[120:123], v[140:143]
	v_mfma_f32_16x16x32_bf16 v[56:59], v[210:213], v[156:159], v[56:59]
	v_mfma_f32_16x16x32_bf16 v[116:119], v[198:201], v[160:163], v[132:135]
	v_mfma_f32_16x16x32_bf16 v[36:39], v[210:213], v[164:167], v[36:39]
	v_mfma_f32_16x16x32_bf16 v[120:123], v[198:201], v[190:193], v[124:127]
	v_mfma_f32_16x16x32_bf16 v[32:35], v[210:213], v[194:197], v[32:35]
	v_mfma_f32_16x16x32_bf16 v[112:115], v[202:205], v[156:159], v[112:115]
	v_mfma_f32_16x16x32_bf16 v[116:119], v[202:205], v[164:167], v[116:119]
	v_mfma_f32_16x16x32_bf16 v[120:123], v[202:205], v[194:197], v[120:123]
	s_mov_b32 m0, s54
	v_lshl_add_u64 v[222:223], s[12:13], 0, v[180:181]
	s_barrier
	ds_read_b128 v[124:127], v238 offset:16384
	ds_read_b128 v[132:135], v238 offset:17408
	ds_read_b128 v[140:143], v238 offset:18432
	ds_read_b128 v[156:159], v238 offset:19456
	ds_read_b128 v[160:163], v238 offset:20480
	ds_read_b128 v[164:167], v238 offset:21504
	ds_read_b128 v[190:193], v238 offset:22528
	ds_read_b128 v[194:197], v238 offset:23552
	global_load_lds_dwordx4 v[222:223], off
	s_mov_b32 m0, s55
	v_lshl_add_u64 v[240:241], s[12:13], 0, v[182:183]
	global_load_lds_dwordx4 v[240:241], off
	s_barrier
	s_waitcnt lgkmcnt(0)
	s_barrier
	s_add_u32 s68, s2, 0x40000
	s_addc_u32 s69, s3, 0
	s_add_i32 s70, s70, s53
	s_mov_b32 m0, s70
	v_lshl_add_u64 v[52:53], s[68:69], 0, v[168:169]
	global_load_lds_dwordx4 v[52:53], off
	s_add_i32 m0, s70, 0x2000
	v_lshl_add_u64 v[52:53], s[68:69], 0, v[184:185]
	global_load_lds_dwordx4 v[52:53], off
	s_waitcnt vmcnt(6)
	s_barrier
	s_add_i32 s68, 0, 0x18000
	v_add_u32_e32 v108, s68, v237
	s_barrier
	ds_read_b128 v[76:79], v108
	ds_read_b128 v[92:95], v108 offset:1024
	ds_read_b128 v[104:107], v108 offset:2048
	ds_read_b128 v[108:111], v108 offset:3072
	s_add_u32 s12, s12, 0x40000
	s_addc_u32 s13, s13, 0
	s_mov_b32 m0, s56
	v_lshl_add_u64 v[140:141], s[12:13], 0, v[180:181]
	ds_read_b128 v[124:127], v238 offset:32768
	ds_read_b128 v[132:135], v238 offset:33792
	ds_read_b128 v[156:159], v238 offset:34816
	ds_read_b128 v[160:163], v238 offset:35840
	ds_read_b128 v[164:167], v238 offset:36864
	ds_read_b128 v[190:193], v238 offset:37888
	ds_read_b128 v[194:197], v238 offset:38912
	ds_read_b128 v[198:201], v238 offset:39936
	global_load_lds_dwordx4 v[140:141], off
	s_mov_b32 m0, s57
	v_lshl_add_u64 v[140:141], s[12:13], 0, v[182:183]
	global_load_lds_dwordx4 v[140:141], off
	s_waitcnt lgkmcnt(8)
	s_barrier
	s_waitcnt lgkmcnt(0)
	v_mfma_f32_16x16x32_bf16 v[140:143], v[76:79], v[124:127], v[152:155]
	v_mfma_f32_16x16x32_bf16 v[152:155], v[92:95], v[132:135], v[140:143]
	v_mfma_f32_16x16x32_bf16 v[68:71], v[104:107], v[124:127], v[68:71]
	v_mfma_f32_16x16x32_bf16 v[140:143], v[76:79], v[156:159], v[148:151]
	v_mfma_f32_16x16x32_bf16 v[64:67], v[104:107], v[156:159], v[64:67]
	v_mfma_f32_16x16x32_bf16 v[136:139], v[76:79], v[164:167], v[136:139]
	v_mfma_f32_16x16x32_bf16 v[44:47], v[104:107], v[164:167], v[44:47]
	v_mfma_f32_16x16x32_bf16 v[128:131], v[76:79], v[194:197], v[128:131]
	v_mfma_f32_16x16x32_bf16 v[40:43], v[104:107], v[194:197], v[40:43]
	v_mfma_f32_16x16x32_bf16 v[68:71], v[108:111], v[132:135], v[68:71]
	v_mfma_f32_16x16x32_bf16 v[148:151], v[92:95], v[160:163], v[140:143]
	v_mfma_f32_16x16x32_bf16 v[64:67], v[108:111], v[160:163], v[64:67]
	v_mfma_f32_16x16x32_bf16 v[136:139], v[92:95], v[190:193], v[136:139]
	v_mfma_f32_16x16x32_bf16 v[44:47], v[108:111], v[190:193], v[44:47]
	v_mfma_f32_16x16x32_bf16 v[128:131], v[92:95], v[198:201], v[128:131]
	v_mfma_f32_16x16x32_bf16 v[40:43], v[108:111], v[198:201], v[40:43]
	s_barrier
	s_add_i32 s12, 0, 0x1c000
	v_add_u32_e32 v140, s12, v237
	s_add_i32 s13, s68, s53
	ds_read_b128 v[202:205], v140
	ds_read_b128 v[206:209], v140 offset:1024
	ds_read_b128 v[210:213], v140 offset:2048
	ds_read_b128 v[214:217], v140 offset:3072
	s_mov_b32 m0, s13
	v_lshl_add_u64 v[140:141], v[218:219], 0, s[78:79]
	global_load_lds_dwordx4 v[140:141], off
	s_add_i32 m0, s13, 0x2000
	v_lshl_add_u64 v[140:141], v[220:221], 0, s[78:79]
	global_load_lds_dwordx4 v[140:141], off
	s_barrier
	s_waitcnt lgkmcnt(0)
	v_mfma_f32_16x16x32_bf16 v[140:143], v[202:205], v[124:127], v[144:147]
	v_mfma_f32_16x16x32_bf16 v[112:115], v[202:205], v[156:159], v[112:115]
	v_mfma_f32_16x16x32_bf16 v[144:147], v[206:209], v[132:135], v[140:143]
	v_mfma_f32_16x16x32_bf16 v[60:63], v[210:213], v[124:127], v[60:63]
	v_mfma_f32_16x16x32_bf16 v[140:143], v[206:209], v[160:163], v[112:115]
	v_mfma_f32_16x16x32_bf16 v[112:115], v[202:205], v[164:167], v[116:119]
	v_mfma_f32_16x16x32_bf16 v[60:63], v[214:217], v[132:135], v[60:63]
	v_mfma_f32_16x16x32_bf16 v[56:59], v[210:213], v[156:159], v[56:59]
	v_mfma_f32_16x16x32_bf16 v[132:135], v[206:209], v[190:193], v[112:115]
	v_mfma_f32_16x16x32_bf16 v[36:39], v[210:213], v[164:167], v[36:39]
	v_mfma_f32_16x16x32_bf16 v[112:115], v[202:205], v[194:197], v[120:123]
	v_mfma_f32_16x16x32_bf16 v[32:35], v[210:213], v[194:197], v[32:35]
	v_mfma_f32_16x16x32_bf16 v[56:59], v[214:217], v[160:163], v[56:59]
	v_mfma_f32_16x16x32_bf16 v[36:39], v[214:217], v[190:193], v[36:39]
	v_mfma_f32_16x16x32_bf16 v[124:127], v[206:209], v[198:201], v[112:115]
	v_mfma_f32_16x16x32_bf16 v[32:35], v[214:217], v[198:201], v[32:35]
	s_mov_b32 m0, s62
	v_lshl_add_u64 v[198:199], v[222:223], 0, s[78:79]
	s_barrier
	ds_read_b128 v[112:115], v238 offset:49152
	ds_read_b128 v[116:119], v238 offset:50176
	ds_read_b128 v[120:123], v238 offset:51200
	ds_read_b128 v[156:159], v238 offset:52224
	ds_read_b128 v[160:163], v238 offset:53248
	ds_read_b128 v[164:167], v238 offset:54272
	ds_read_b128 v[190:193], v238 offset:55296
	ds_read_b128 v[194:197], v238 offset:56320
	global_load_lds_dwordx4 v[198:199], off
	s_mov_b32 m0, s63
	v_lshl_add_u64 v[198:199], v[240:241], 0, s[78:79]
	global_load_lds_dwordx4 v[198:199], off
	s_barrier
	s_waitcnt lgkmcnt(0)
	s_barrier
	s_add_u32 s2, s2, 0x40080
	s_addc_u32 s3, s3, 0
	s_add_i32 s12, s12, s53
	s_mov_b32 m0, s12
	v_lshl_add_u64 v[48:49], s[2:3], 0, v[168:169]
	global_load_lds_dwordx4 v[48:49], off
	s_add_i32 m0, s12, 0x2000
	v_lshl_add_u64 v[48:49], s[2:3], 0, v[184:185]
	global_load_lds_dwordx4 v[48:49], off
	s_waitcnt vmcnt(6)
	s_barrier
	s_add_i32 s67, s67, 2
	s_add_u32 s10, s10, 0x100
	s_addc_u32 s11, s11, 0
	s_add_u32 s37, s37, 0x100
	s_addc_u32 s39, s39, 0
	s_cmp_gt_u32 s67, 13
	s_barrier
	s_cbranch_scc0 .Lup_half_loop
	s_branch .Lup_epi

.LBB0_1048:
	s_add_u32 s56, s2, 0x100
	s_addc_u32 s57, s3, 0
	s_mov_b32 s58, -2
	s_add_u32 s2, s24, 0x100
	s_addc_u32 s3, s25, 0
	s_add_i32 s59, 0, 0x10000
	v_add_u32_e32 v52, s59, v194
	ds_read_b128 v[40:43], v52
	ds_read_b128 v[44:47], v52 offset:1024
	ds_read_b128 v[48:51], v52 offset:2048
	ds_read_b128 v[52:55], v52 offset:3072
	s_cmp_eq_u32 s58, 40
	s_cselect_b32 s27, s1, s3
	s_cselect_b32 s26, s0, s2
	s_cselect_b32 s9, s23, s57
	s_cselect_b32 s8, s22, s56
	v_lshl_add_u64 v[190:191], s[24:25], 0, v[166:167]
	s_add_i32 m0, s37, 0xc000
	ds_read_b128 v[56:59], v195
	ds_read_b128 v[60:63], v195 offset:1024
	ds_read_b128 v[72:75], v195 offset:2048
	ds_read_b128 v[84:87], v195 offset:3072
	ds_read_b128 v[182:185], v195 offset:4096
	ds_read_b128 v[186:189], v195 offset:5120
	ds_read_b128 v[196:199], v195 offset:6144
	ds_read_b128 v[200:203], v195 offset:7168
	global_load_lds_dwordx4 v[190:191], off
	s_add_i32 m0, s37, 0xe000
	v_lshl_add_u64 v[190:191], s[24:25], 0, v[180:181]
	global_load_lds_dwordx4 v[190:191], off
	s_waitcnt lgkmcnt(8)
	s_barrier
	s_waitcnt lgkmcnt(0)
	v_mfma_f32_16x16x32_bf16 v[156:159], v[40:43], v[56:59], 0
	v_mfma_f32_16x16x32_bf16 v[152:155], v[48:51], v[56:59], 0
	v_mfma_f32_16x16x32_bf16 v[140:143], v[40:43], v[72:75], 0
	v_mfma_f32_16x16x32_bf16 v[136:139], v[48:51], v[72:75], 0
	v_mfma_f32_16x16x32_bf16 v[124:127], v[40:43], v[182:185], 0
	v_mfma_f32_16x16x32_bf16 v[120:123], v[48:51], v[182:185], 0
	v_mfma_f32_16x16x32_bf16 v[108:111], v[40:43], v[196:199], 0
	v_mfma_f32_16x16x32_bf16 v[104:107], v[48:51], v[196:199], 0
	v_mfma_f32_16x16x32_bf16 v[156:159], v[44:47], v[60:63], v[156:159]
	v_mfma_f32_16x16x32_bf16 v[152:155], v[52:55], v[60:63], v[152:155]
	v_mfma_f32_16x16x32_bf16 v[140:143], v[44:47], v[84:87], v[140:143]
	v_mfma_f32_16x16x32_bf16 v[136:139], v[52:55], v[84:87], v[136:139]
	v_mfma_f32_16x16x32_bf16 v[124:127], v[44:47], v[186:189], v[124:127]
	v_mfma_f32_16x16x32_bf16 v[120:123], v[52:55], v[186:189], v[120:123]
	v_mfma_f32_16x16x32_bf16 v[108:111], v[44:47], v[200:203], v[108:111]
	v_mfma_f32_16x16x32_bf16 v[104:107], v[52:55], v[200:203], v[104:107]
	s_barrier
	s_add_i32 s60, 0, 0x14000
	v_add_u32_e32 v190, s60, v194
	s_add_i32 s24, s59, s36
	ds_read_b128 v[204:207], v190
	ds_read_b128 v[208:211], v190 offset:1024
	ds_read_b128 v[212:215], v190 offset:2048
	ds_read_b128 v[216:219], v190 offset:3072
	v_lshl_add_u64 v[190:191], s[8:9], 0, v[168:169]
	s_mov_b32 m0, s24
	v_lshl_add_u64 v[240:241], s[8:9], 0, v[164:165]
	global_load_lds_dwordx4 v[190:191], off
	s_add_i32 m0, s24, 0x2000
	s_nop 0
	global_load_lds_dwordx4 v[240:241], off
	s_barrier
	s_waitcnt lgkmcnt(0)
	v_mfma_f32_16x16x32_bf16 v[148:151], v[204:207], v[56:59], 0
	v_mfma_f32_16x16x32_bf16 v[56:59], v[212:215], v[56:59], 0
	v_mfma_f32_16x16x32_bf16 v[148:151], v[208:211], v[60:63], v[148:151]
	v_mfma_f32_16x16x32_bf16 v[56:59], v[216:219], v[60:63], v[56:59]
	v_mfma_f32_16x16x32_bf16 v[60:63], v[204:207], v[72:75], 0
	v_mfma_f32_16x16x32_bf16 v[72:75], v[212:215], v[72:75], 0
	v_mfma_f32_16x16x32_bf16 v[112:115], v[212:215], v[182:185], 0
	v_mfma_f32_16x16x32_bf16 v[100:103], v[204:207], v[196:199], 0
	v_mfma_f32_16x16x32_bf16 v[96:99], v[212:215], v[196:199], 0
	v_mfma_f32_16x16x32_bf16 v[60:63], v[208:211], v[84:87], v[60:63]
	v_mfma_f32_16x16x32_bf16 v[72:75], v[216:219], v[84:87], v[72:75]
	v_mfma_f32_16x16x32_bf16 v[84:87], v[204:207], v[182:185], 0
	v_mfma_f32_16x16x32_bf16 v[112:115], v[216:219], v[186:189], v[112:115]
	v_mfma_f32_16x16x32_bf16 v[100:103], v[208:211], v[200:203], v[100:103]
	v_mfma_f32_16x16x32_bf16 v[96:99], v[216:219], v[200:203], v[96:99]
	v_mfma_f32_16x16x32_bf16 v[84:87], v[208:211], v[186:189], v[84:87]
	s_mov_b32 m0, s37
	v_lshl_add_u64 v[242:243], s[26:27], 0, v[160:161]
	s_barrier
	ds_read_b128 v[116:119], v195 offset:16384
	ds_read_b128 v[128:131], v195 offset:17408
	ds_read_b128 v[132:135], v195 offset:18432
	ds_read_b128 v[144:147], v195 offset:19456
	ds_read_b128 v[182:185], v195 offset:20480
	ds_read_b128 v[186:189], v195 offset:21504
	ds_read_b128 v[196:199], v195 offset:22528
	ds_read_b128 v[200:203], v195 offset:23552
	global_load_lds_dwordx4 v[242:243], off
	s_mov_b32 m0, s38
	v_lshl_add_u64 v[244:245], s[26:27], 0, v[162:163]
	global_load_lds_dwordx4 v[244:245], off
	s_barrier
	s_waitcnt lgkmcnt(0)
	v_mfma_f32_16x16x32_bf16 v[92:95], v[40:43], v[116:119], 0
	v_mfma_f32_16x16x32_bf16 v[88:91], v[48:51], v[116:119], 0
	v_mfma_f32_16x16x32_bf16 v[68:71], v[40:43], v[132:135], 0
	v_mfma_f32_16x16x32_bf16 v[64:67], v[48:51], v[132:135], 0
	v_mfma_f32_16x16x32_bf16 v[28:31], v[40:43], v[182:185], 0
	v_mfma_f32_16x16x32_bf16 v[24:27], v[48:51], v[182:185], 0
	v_mfma_f32_16x16x32_bf16 v[12:15], v[40:43], v[196:199], 0
	v_mfma_f32_16x16x32_bf16 v[8:11], v[48:51], v[196:199], 0
	v_mfma_f32_16x16x32_bf16 v[92:95], v[44:47], v[128:131], v[92:95]
	v_mfma_f32_16x16x32_bf16 v[88:91], v[52:55], v[128:131], v[88:91]
	v_mfma_f32_16x16x32_bf16 v[68:71], v[44:47], v[144:147], v[68:71]
	v_mfma_f32_16x16x32_bf16 v[64:67], v[52:55], v[144:147], v[64:67]
	v_mfma_f32_16x16x32_bf16 v[28:31], v[44:47], v[186:189], v[28:31]
	v_mfma_f32_16x16x32_bf16 v[24:27], v[52:55], v[186:189], v[24:27]
	v_mfma_f32_16x16x32_bf16 v[12:15], v[44:47], v[200:203], v[12:15]
	v_mfma_f32_16x16x32_bf16 v[8:11], v[52:55], v[200:203], v[8:11]
	s_barrier
	s_add_u32 s24, s8, 0xb0000
	s_addc_u32 s25, s9, 0
	s_add_i32 s59, s60, s36
	s_mov_b32 m0, s59
	v_lshl_add_u64 v[40:41], s[24:25], 0, v[168:169]
	global_load_lds_dwordx4 v[40:41], off
	s_add_i32 m0, s59, 0x2000
	v_lshl_add_u64 v[40:41], s[24:25], 0, v[164:165]
	global_load_lds_dwordx4 v[40:41], off
	s_waitcnt vmcnt(6)
	s_barrier
	v_mfma_f32_16x16x32_bf16 v[36:39], v[204:207], v[132:135], 0
	v_mfma_f32_16x16x32_bf16 v[32:35], v[212:215], v[132:135], 0
	v_mfma_f32_16x16x32_bf16 v[20:23], v[204:207], v[182:185], 0
	v_mfma_f32_16x16x32_bf16 v[16:19], v[212:215], v[182:185], 0
	v_mfma_f32_16x16x32_bf16 v[4:7], v[204:207], v[196:199], 0
	v_mfma_f32_16x16x32_bf16 v[0:3], v[212:215], v[196:199], 0
	v_mfma_f32_16x16x32_bf16 v[40:43], v[204:207], v[116:119], 0
	v_mfma_f32_16x16x32_bf16 v[44:47], v[212:215], v[116:119], 0
	v_mfma_f32_16x16x32_bf16 v[36:39], v[208:211], v[144:147], v[36:39]
	v_mfma_f32_16x16x32_bf16 v[32:35], v[216:219], v[144:147], v[32:35]
	v_mfma_f32_16x16x32_bf16 v[20:23], v[208:211], v[186:189], v[20:23]
	v_mfma_f32_16x16x32_bf16 v[16:19], v[216:219], v[186:189], v[16:19]
	v_mfma_f32_16x16x32_bf16 v[4:7], v[208:211], v[200:203], v[4:7]
	v_mfma_f32_16x16x32_bf16 v[0:3], v[216:219], v[200:203], v[0:3]
	v_mfma_f32_16x16x32_bf16 v[40:43], v[208:211], v[128:131], v[40:43]
	v_mfma_f32_16x16x32_bf16 v[44:47], v[216:219], v[128:131], v[44:47]
	s_add_i32 s59, 0, 0x18000
	v_add_u32_e32 v80, s59, v194
	s_barrier
	ds_read_b128 v[48:51], v80
	ds_read_b128 v[52:55], v80 offset:1024
	ds_read_b128 v[76:79], v80 offset:2048
	ds_read_b128 v[80:83], v80 offset:3072
	s_add_u32 s24, s26, 0xb0000
	s_addc_u32 s25, s27, 0
	s_mov_b32 m0, s39
	v_lshl_add_u64 v[132:133], s[24:25], 0, v[160:161]
	ds_read_b128 v[116:119], v195 offset:32768
	ds_read_b128 v[128:131], v195 offset:33792
	ds_read_b128 v[182:185], v195 offset:34816
	ds_read_b128 v[186:189], v195 offset:35840
	ds_read_b128 v[196:199], v195 offset:36864
	ds_read_b128 v[200:203], v195 offset:37888
	ds_read_b128 v[204:207], v195 offset:38912
	ds_read_b128 v[208:211], v195 offset:39936
	global_load_lds_dwordx4 v[132:133], off
	s_mov_b32 m0, s40
	v_lshl_add_u64 v[132:133], s[24:25], 0, v[162:163]
	global_load_lds_dwordx4 v[132:133], off
	s_waitcnt lgkmcnt(8)
	s_barrier
	s_waitcnt lgkmcnt(0)
	v_mfma_f32_16x16x32_bf16 v[132:135], v[48:51], v[116:119], v[156:159]
	v_mfma_f32_16x16x32_bf16 v[156:159], v[52:55], v[128:131], v[132:135]
	v_mfma_f32_16x16x32_bf16 v[132:135], v[76:79], v[116:119], v[152:155]
	v_mfma_f32_16x16x32_bf16 v[152:155], v[80:83], v[128:131], v[132:135]
	v_mfma_f32_16x16x32_bf16 v[132:135], v[48:51], v[182:185], v[140:143]
	v_mfma_f32_16x16x32_bf16 v[140:143], v[52:55], v[186:189], v[132:135]
	v_mfma_f32_16x16x32_bf16 v[132:135], v[76:79], v[182:185], v[136:139]
	v_mfma_f32_16x16x32_bf16 v[124:127], v[48:51], v[196:199], v[124:127]
	v_mfma_f32_16x16x32_bf16 v[120:123], v[76:79], v[196:199], v[120:123]
	v_mfma_f32_16x16x32_bf16 v[108:111], v[48:51], v[204:207], v[108:111]
	v_mfma_f32_16x16x32_bf16 v[104:107], v[76:79], v[204:207], v[104:107]
	v_mfma_f32_16x16x32_bf16 v[136:139], v[80:83], v[186:189], v[132:135]
	v_mfma_f32_16x16x32_bf16 v[124:127], v[52:55], v[200:203], v[124:127]
	v_mfma_f32_16x16x32_bf16 v[120:123], v[80:83], v[200:203], v[120:123]
	v_mfma_f32_16x16x32_bf16 v[108:111], v[52:55], v[208:211], v[108:111]
	v_mfma_f32_16x16x32_bf16 v[104:107], v[80:83], v[208:211], v[104:107]
	s_barrier
	s_add_i32 s24, 0, 0x1c000
	v_add_u32_e32 v132, s24, v194
	s_add_i32 s25, s59, s36
	ds_read_b128 v[212:215], v132
	ds_read_b128 v[216:219], v132 offset:1024
	ds_read_b128 v[220:223], v132 offset:2048
	ds_read_b128 v[236:239], v132 offset:3072
	s_mov_b32 m0, s25
	v_lshl_add_u64 v[132:133], v[190:191], 0, s[78:79]
	global_load_lds_dwordx4 v[132:133], off
	s_add_i32 m0, s25, 0x2000
	v_lshl_add_u64 v[132:133], v[240:241], 0, s[78:79]
	global_load_lds_dwordx4 v[132:133], off
	s_barrier
	s_waitcnt lgkmcnt(0)
	v_mfma_f32_16x16x32_bf16 v[56:59], v[220:223], v[116:119], v[56:59]
	v_mfma_f32_16x16x32_bf16 v[132:135], v[212:215], v[116:119], v[148:151]
	v_mfma_f32_16x16x32_bf16 v[144:147], v[236:239], v[128:131], v[56:59]
	v_mfma_f32_16x16x32_bf16 v[56:59], v[212:215], v[182:185], v[60:63]
	v_mfma_f32_16x16x32_bf16 v[148:151], v[216:219], v[128:131], v[132:135]
	v_mfma_f32_16x16x32_bf16 v[132:135], v[216:219], v[186:189], v[56:59]
	v_mfma_f32_16x16x32_bf16 v[56:59], v[220:223], v[182:185], v[72:75]
	v_mfma_f32_16x16x32_bf16 v[128:131], v[236:239], v[186:189], v[56:59]
	v_mfma_f32_16x16x32_bf16 v[56:59], v[212:215], v[196:199], v[84:87]
	v_mfma_f32_16x16x32_bf16 v[116:119], v[216:219], v[200:203], v[56:59]
	v_mfma_f32_16x16x32_bf16 v[56:59], v[220:223], v[196:199], v[112:115]
	v_mfma_f32_16x16x32_bf16 v[112:115], v[236:239], v[200:203], v[56:59]
	v_mfma_f32_16x16x32_bf16 v[56:59], v[212:215], v[204:207], v[100:103]
	v_mfma_f32_16x16x32_bf16 v[100:103], v[216:219], v[208:211], v[56:59]
	v_mfma_f32_16x16x32_bf16 v[56:59], v[220:223], v[204:207], v[96:99]
	v_mfma_f32_16x16x32_bf16 v[96:99], v[236:239], v[208:211], v[56:59]
	s_mov_b32 m0, s47
	v_lshl_add_u64 v[190:191], v[242:243], 0, s[78:79]
	s_barrier
	s_nop 2
	ds_read_b128 v[56:59], v195 offset:49152
	ds_read_b128 v[60:63], v195 offset:50176
	ds_read_b128 v[72:75], v195 offset:51200
	ds_read_b128 v[84:87], v195 offset:52224
	ds_read_b128 v[182:185], v195 offset:53248
	ds_read_b128 v[186:189], v195 offset:54272
	ds_read_b128 v[196:199], v195 offset:55296
	ds_read_b128 v[200:203], v195 offset:56320
	global_load_lds_dwordx4 v[190:191], off
	s_mov_b32 m0, s49
	v_lshl_add_u64 v[190:191], v[244:245], 0, s[78:79]
	global_load_lds_dwordx4 v[190:191], off
	s_barrier
	s_waitcnt lgkmcnt(0)
	v_mfma_f32_16x16x32_bf16 v[92:95], v[48:51], v[56:59], v[92:95]
	v_mfma_f32_16x16x32_bf16 v[88:91], v[76:79], v[56:59], v[88:91]
	v_mfma_f32_16x16x32_bf16 v[68:71], v[48:51], v[72:75], v[68:71]
	v_mfma_f32_16x16x32_bf16 v[64:67], v[76:79], v[72:75], v[64:67]
	v_mfma_f32_16x16x32_bf16 v[28:31], v[48:51], v[182:185], v[28:31]
	v_mfma_f32_16x16x32_bf16 v[24:27], v[76:79], v[182:185], v[24:27]
	v_mfma_f32_16x16x32_bf16 v[12:15], v[48:51], v[196:199], v[12:15]
	v_mfma_f32_16x16x32_bf16 v[8:11], v[76:79], v[196:199], v[8:11]
	v_mfma_f32_16x16x32_bf16 v[92:95], v[52:55], v[60:63], v[92:95]
	v_mfma_f32_16x16x32_bf16 v[88:91], v[80:83], v[60:63], v[88:91]
	v_mfma_f32_16x16x32_bf16 v[68:71], v[52:55], v[84:87], v[68:71]
	v_mfma_f32_16x16x32_bf16 v[64:67], v[80:83], v[84:87], v[64:67]
	v_mfma_f32_16x16x32_bf16 v[28:31], v[52:55], v[186:189], v[28:31]
	v_mfma_f32_16x16x32_bf16 v[24:27], v[80:83], v[186:189], v[24:27]
	v_mfma_f32_16x16x32_bf16 v[12:15], v[52:55], v[200:203], v[12:15]
	v_mfma_f32_16x16x32_bf16 v[8:11], v[80:83], v[200:203], v[8:11]
	s_barrier
	s_add_u32 s8, s8, 0xb0080
	s_addc_u32 s9, s9, 0
	s_add_i32 s24, s24, s36
	s_mov_b32 m0, s24
	v_lshl_add_u64 v[48:49], s[8:9], 0, v[168:169]
	global_load_lds_dwordx4 v[48:49], off
	s_add_i32 m0, s24, 0x2000
	v_lshl_add_u64 v[48:49], s[8:9], 0, v[164:165]
	global_load_lds_dwordx4 v[48:49], off
	s_waitcnt vmcnt(6)
	s_barrier
	v_mfma_f32_16x16x32_bf16 v[40:43], v[212:215], v[56:59], v[40:43]
	v_mfma_f32_16x16x32_bf16 v[80:83], v[216:219], v[60:63], v[40:43]
	v_mfma_f32_16x16x32_bf16 v[40:43], v[220:223], v[56:59], v[44:47]
	v_mfma_f32_16x16x32_bf16 v[36:39], v[212:215], v[72:75], v[36:39]
	v_mfma_f32_16x16x32_bf16 v[32:35], v[220:223], v[72:75], v[32:35]
	v_mfma_f32_16x16x32_bf16 v[20:23], v[212:215], v[182:185], v[20:23]
	v_mfma_f32_16x16x32_bf16 v[16:19], v[220:223], v[182:185], v[16:19]
	v_mfma_f32_16x16x32_bf16 v[4:7], v[212:215], v[196:199], v[4:7]
	v_mfma_f32_16x16x32_bf16 v[0:3], v[220:223], v[196:199], v[0:3]
	v_mfma_f32_16x16x32_bf16 v[76:79], v[236:239], v[60:63], v[40:43]
	v_mfma_f32_16x16x32_bf16 v[36:39], v[216:219], v[84:87], v[36:39]
	v_mfma_f32_16x16x32_bf16 v[32:35], v[236:239], v[84:87], v[32:35]
	v_mfma_f32_16x16x32_bf16 v[20:23], v[216:219], v[186:189], v[20:23]
	v_mfma_f32_16x16x32_bf16 v[16:19], v[236:239], v[186:189], v[16:19]
	v_mfma_f32_16x16x32_bf16 v[4:7], v[216:219], v[200:203], v[4:7]
	v_mfma_f32_16x16x32_bf16 v[0:3], v[236:239], v[200:203], v[0:3]
	s_add_i32 s58, s58, 2
	s_add_u32 s56, s56, 0x100
	s_addc_u32 s57, s57, 0
	s_cmp_gt_u32 s58, 41
	s_mov_b64 s[24:25], s[2:3]
	s_barrier
.LBB0_1049:
	s_add_u32 s2, s24, 0x100
	s_addc_u32 s3, s25, 0
	s_add_i32 s59, 0, 0x10000
	v_add_u32_e32 v52, s59, v194
	ds_read_b128 v[40:43], v52
	ds_read_b128 v[44:47], v52 offset:1024
	ds_read_b128 v[48:51], v52 offset:2048
	ds_read_b128 v[52:55], v52 offset:3072
	s_cmp_eq_u32 s58, 40
	s_cselect_b32 s27, s1, s3
	s_cselect_b32 s26, s0, s2
	s_cselect_b32 s9, s23, s57
	s_cselect_b32 s8, s22, s56
	v_lshl_add_u64 v[190:191], s[24:25], 0, v[166:167]
	s_add_i32 m0, s37, 0xc000
	ds_read_b128 v[56:59], v195
	ds_read_b128 v[60:63], v195 offset:1024
	ds_read_b128 v[72:75], v195 offset:2048
	ds_read_b128 v[84:87], v195 offset:3072
	ds_read_b128 v[182:185], v195 offset:4096
	ds_read_b128 v[186:189], v195 offset:5120
	ds_read_b128 v[196:199], v195 offset:6144
	ds_read_b128 v[200:203], v195 offset:7168
	global_load_lds_dwordx4 v[190:191], off
	s_add_i32 m0, s37, 0xe000
	v_lshl_add_u64 v[190:191], s[24:25], 0, v[180:181]
	global_load_lds_dwordx4 v[190:191], off
	s_waitcnt lgkmcnt(8)
	s_barrier
	s_waitcnt lgkmcnt(0)
	v_mfma_f32_16x16x32_bf16 v[156:159], v[40:43], v[56:59], v[156:159]
	v_mfma_f32_16x16x32_bf16 v[152:155], v[48:51], v[56:59], v[152:155]
	v_mfma_f32_16x16x32_bf16 v[140:143], v[40:43], v[72:75], v[140:143]
	v_mfma_f32_16x16x32_bf16 v[136:139], v[48:51], v[72:75], v[136:139]
	v_mfma_f32_16x16x32_bf16 v[124:127], v[40:43], v[182:185], v[124:127]
	v_mfma_f32_16x16x32_bf16 v[120:123], v[48:51], v[182:185], v[120:123]
	v_mfma_f32_16x16x32_bf16 v[108:111], v[40:43], v[196:199], v[108:111]
	v_mfma_f32_16x16x32_bf16 v[104:107], v[48:51], v[196:199], v[104:107]
	v_mfma_f32_16x16x32_bf16 v[156:159], v[44:47], v[60:63], v[156:159]
	v_mfma_f32_16x16x32_bf16 v[152:155], v[52:55], v[60:63], v[152:155]
	v_mfma_f32_16x16x32_bf16 v[140:143], v[44:47], v[84:87], v[140:143]
	v_mfma_f32_16x16x32_bf16 v[136:139], v[52:55], v[84:87], v[136:139]
	v_mfma_f32_16x16x32_bf16 v[124:127], v[44:47], v[186:189], v[124:127]
	v_mfma_f32_16x16x32_bf16 v[120:123], v[52:55], v[186:189], v[120:123]
	v_mfma_f32_16x16x32_bf16 v[108:111], v[44:47], v[200:203], v[108:111]
	v_mfma_f32_16x16x32_bf16 v[104:107], v[52:55], v[200:203], v[104:107]
	s_barrier
	s_add_i32 s60, 0, 0x14000
	v_add_u32_e32 v190, s60, v194
	s_add_i32 s24, s59, s36
	ds_read_b128 v[204:207], v190
	ds_read_b128 v[208:211], v190 offset:1024
	ds_read_b128 v[212:215], v190 offset:2048
	ds_read_b128 v[216:219], v190 offset:3072
	v_lshl_add_u64 v[190:191], s[8:9], 0, v[168:169]
	s_mov_b32 m0, s24
	v_lshl_add_u64 v[240:241], s[8:9], 0, v[164:165]
	global_load_lds_dwordx4 v[190:191], off
	s_add_i32 m0, s24, 0x2000
	s_nop 0
	global_load_lds_dwordx4 v[240:241], off
	s_barrier
	s_waitcnt lgkmcnt(0)
	v_mfma_f32_16x16x32_bf16 v[148:151], v[204:207], v[56:59], v[148:151]
	v_mfma_f32_16x16x32_bf16 v[56:59], v[212:215], v[56:59], v[144:147]
	v_mfma_f32_16x16x32_bf16 v[148:151], v[208:211], v[60:63], v[148:151]
	v_mfma_f32_16x16x32_bf16 v[56:59], v[216:219], v[60:63], v[56:59]
	v_mfma_f32_16x16x32_bf16 v[60:63], v[204:207], v[72:75], v[132:135]
	v_mfma_f32_16x16x32_bf16 v[72:75], v[212:215], v[72:75], v[128:131]
	v_mfma_f32_16x16x32_bf16 v[112:115], v[212:215], v[182:185], v[112:115]
	v_mfma_f32_16x16x32_bf16 v[100:103], v[204:207], v[196:199], v[100:103]
	v_mfma_f32_16x16x32_bf16 v[96:99], v[212:215], v[196:199], v[96:99]
	v_mfma_f32_16x16x32_bf16 v[60:63], v[208:211], v[84:87], v[60:63]
	v_mfma_f32_16x16x32_bf16 v[72:75], v[216:219], v[84:87], v[72:75]
	v_mfma_f32_16x16x32_bf16 v[84:87], v[204:207], v[182:185], v[116:119]
	v_mfma_f32_16x16x32_bf16 v[112:115], v[216:219], v[186:189], v[112:115]
	v_mfma_f32_16x16x32_bf16 v[100:103], v[208:211], v[200:203], v[100:103]
	v_mfma_f32_16x16x32_bf16 v[96:99], v[216:219], v[200:203], v[96:99]
	v_mfma_f32_16x16x32_bf16 v[84:87], v[208:211], v[186:189], v[84:87]
	s_mov_b32 m0, s37
	v_lshl_add_u64 v[242:243], s[26:27], 0, v[160:161]
	s_barrier
	ds_read_b128 v[116:119], v195 offset:16384
	ds_read_b128 v[128:131], v195 offset:17408
	ds_read_b128 v[132:135], v195 offset:18432
	ds_read_b128 v[144:147], v195 offset:19456
	ds_read_b128 v[182:185], v195 offset:20480
	ds_read_b128 v[186:189], v195 offset:21504
	ds_read_b128 v[196:199], v195 offset:22528
	ds_read_b128 v[200:203], v195 offset:23552
	global_load_lds_dwordx4 v[242:243], off
	s_mov_b32 m0, s38
	v_lshl_add_u64 v[244:245], s[26:27], 0, v[162:163]
	global_load_lds_dwordx4 v[244:245], off
	s_barrier
	s_waitcnt lgkmcnt(0)
	v_mfma_f32_16x16x32_bf16 v[92:95], v[40:43], v[116:119], v[92:95]
	v_mfma_f32_16x16x32_bf16 v[88:91], v[48:51], v[116:119], v[88:91]
	v_mfma_f32_16x16x32_bf16 v[68:71], v[40:43], v[132:135], v[68:71]
	v_mfma_f32_16x16x32_bf16 v[64:67], v[48:51], v[132:135], v[64:67]
	v_mfma_f32_16x16x32_bf16 v[28:31], v[40:43], v[182:185], v[28:31]
	v_mfma_f32_16x16x32_bf16 v[24:27], v[48:51], v[182:185], v[24:27]
	v_mfma_f32_16x16x32_bf16 v[12:15], v[40:43], v[196:199], v[12:15]
	v_mfma_f32_16x16x32_bf16 v[8:11], v[48:51], v[196:199], v[8:11]
	v_mfma_f32_16x16x32_bf16 v[92:95], v[44:47], v[128:131], v[92:95]
	v_mfma_f32_16x16x32_bf16 v[88:91], v[52:55], v[128:131], v[88:91]
	v_mfma_f32_16x16x32_bf16 v[68:71], v[44:47], v[144:147], v[68:71]
	v_mfma_f32_16x16x32_bf16 v[64:67], v[52:55], v[144:147], v[64:67]
	v_mfma_f32_16x16x32_bf16 v[28:31], v[44:47], v[186:189], v[28:31]
	v_mfma_f32_16x16x32_bf16 v[24:27], v[52:55], v[186:189], v[24:27]
	v_mfma_f32_16x16x32_bf16 v[12:15], v[44:47], v[200:203], v[12:15]
	v_mfma_f32_16x16x32_bf16 v[8:11], v[52:55], v[200:203], v[8:11]
	s_barrier
	s_add_u32 s24, s8, 0xb0000
	s_addc_u32 s25, s9, 0
	s_add_i32 s59, s60, s36
	s_mov_b32 m0, s59
	v_lshl_add_u64 v[40:41], s[24:25], 0, v[168:169]
	global_load_lds_dwordx4 v[40:41], off
	s_add_i32 m0, s59, 0x2000
	v_lshl_add_u64 v[40:41], s[24:25], 0, v[164:165]
	global_load_lds_dwordx4 v[40:41], off
	s_waitcnt vmcnt(6)
	s_barrier
	v_mfma_f32_16x16x32_bf16 v[36:39], v[204:207], v[132:135], v[36:39]
	v_mfma_f32_16x16x32_bf16 v[32:35], v[212:215], v[132:135], v[32:35]
	v_mfma_f32_16x16x32_bf16 v[20:23], v[204:207], v[182:185], v[20:23]
	v_mfma_f32_16x16x32_bf16 v[16:19], v[212:215], v[182:185], v[16:19]
	v_mfma_f32_16x16x32_bf16 v[4:7], v[204:207], v[196:199], v[4:7]
	v_mfma_f32_16x16x32_bf16 v[0:3], v[212:215], v[196:199], v[0:3]
	v_mfma_f32_16x16x32_bf16 v[40:43], v[204:207], v[116:119], v[80:83]
	v_mfma_f32_16x16x32_bf16 v[44:47], v[212:215], v[116:119], v[76:79]
	v_mfma_f32_16x16x32_bf16 v[36:39], v[208:211], v[144:147], v[36:39]
	v_mfma_f32_16x16x32_bf16 v[32:35], v[216:219], v[144:147], v[32:35]
	v_mfma_f32_16x16x32_bf16 v[20:23], v[208:211], v[186:189], v[20:23]
	v_mfma_f32_16x16x32_bf16 v[16:19], v[216:219], v[186:189], v[16:19]
	v_mfma_f32_16x16x32_bf16 v[4:7], v[208:211], v[200:203], v[4:7]
	v_mfma_f32_16x16x32_bf16 v[0:3], v[216:219], v[200:203], v[0:3]
	v_mfma_f32_16x16x32_bf16 v[40:43], v[208:211], v[128:131], v[40:43]
	v_mfma_f32_16x16x32_bf16 v[44:47], v[216:219], v[128:131], v[44:47]
	s_add_i32 s59, 0, 0x18000
	v_add_u32_e32 v80, s59, v194
	s_barrier
	ds_read_b128 v[48:51], v80
	ds_read_b128 v[52:55], v80 offset:1024
	ds_read_b128 v[76:79], v80 offset:2048
	ds_read_b128 v[80:83], v80 offset:3072
	s_add_u32 s24, s26, 0xb0000
	s_addc_u32 s25, s27, 0
	s_mov_b32 m0, s39
	v_lshl_add_u64 v[132:133], s[24:25], 0, v[160:161]
	ds_read_b128 v[116:119], v195 offset:32768
	ds_read_b128 v[128:131], v195 offset:33792
	ds_read_b128 v[182:185], v195 offset:34816
	ds_read_b128 v[186:189], v195 offset:35840
	ds_read_b128 v[196:199], v195 offset:36864
	ds_read_b128 v[200:203], v195 offset:37888
	ds_read_b128 v[204:207], v195 offset:38912
	ds_read_b128 v[208:211], v195 offset:39936
	global_load_lds_dwordx4 v[132:133], off
	s_mov_b32 m0, s40
	v_lshl_add_u64 v[132:133], s[24:25], 0, v[162:163]
	global_load_lds_dwordx4 v[132:133], off
	s_waitcnt lgkmcnt(8)
	s_barrier
	s_waitcnt lgkmcnt(0)
	v_mfma_f32_16x16x32_bf16 v[132:135], v[48:51], v[116:119], v[156:159]
	v_mfma_f32_16x16x32_bf16 v[156:159], v[52:55], v[128:131], v[132:135]
	v_mfma_f32_16x16x32_bf16 v[132:135], v[76:79], v[116:119], v[152:155]
	v_mfma_f32_16x16x32_bf16 v[152:155], v[80:83], v[128:131], v[132:135]
	v_mfma_f32_16x16x32_bf16 v[132:135], v[48:51], v[182:185], v[140:143]
	v_mfma_f32_16x16x32_bf16 v[140:143], v[52:55], v[186:189], v[132:135]
	v_mfma_f32_16x16x32_bf16 v[132:135], v[76:79], v[182:185], v[136:139]
	v_mfma_f32_16x16x32_bf16 v[124:127], v[48:51], v[196:199], v[124:127]
	v_mfma_f32_16x16x32_bf16 v[120:123], v[76:79], v[196:199], v[120:123]
	v_mfma_f32_16x16x32_bf16 v[108:111], v[48:51], v[204:207], v[108:111]
	v_mfma_f32_16x16x32_bf16 v[104:107], v[76:79], v[204:207], v[104:107]
	v_mfma_f32_16x16x32_bf16 v[136:139], v[80:83], v[186:189], v[132:135]
	v_mfma_f32_16x16x32_bf16 v[124:127], v[52:55], v[200:203], v[124:127]
	v_mfma_f32_16x16x32_bf16 v[120:123], v[80:83], v[200:203], v[120:123]
	v_mfma_f32_16x16x32_bf16 v[108:111], v[52:55], v[208:211], v[108:111]
	v_mfma_f32_16x16x32_bf16 v[104:107], v[80:83], v[208:211], v[104:107]
	s_barrier
	s_add_i32 s24, 0, 0x1c000
	v_add_u32_e32 v132, s24, v194
	s_add_i32 s25, s59, s36
	ds_read_b128 v[212:215], v132
	ds_read_b128 v[216:219], v132 offset:1024
	ds_read_b128 v[220:223], v132 offset:2048
	ds_read_b128 v[236:239], v132 offset:3072
	s_mov_b32 m0, s25
	v_lshl_add_u64 v[132:133], v[190:191], 0, s[78:79]
	global_load_lds_dwordx4 v[132:133], off
	s_add_i32 m0, s25, 0x2000
	v_lshl_add_u64 v[132:133], v[240:241], 0, s[78:79]
	global_load_lds_dwordx4 v[132:133], off
	s_barrier
	s_waitcnt lgkmcnt(0)
	v_mfma_f32_16x16x32_bf16 v[56:59], v[220:223], v[116:119], v[56:59]
	v_mfma_f32_16x16x32_bf16 v[132:135], v[212:215], v[116:119], v[148:151]
	v_mfma_f32_16x16x32_bf16 v[144:147], v[236:239], v[128:131], v[56:59]
	v_mfma_f32_16x16x32_bf16 v[56:59], v[212:215], v[182:185], v[60:63]
	v_mfma_f32_16x16x32_bf16 v[148:151], v[216:219], v[128:131], v[132:135]
	v_mfma_f32_16x16x32_bf16 v[132:135], v[216:219], v[186:189], v[56:59]
	v_mfma_f32_16x16x32_bf16 v[56:59], v[220:223], v[182:185], v[72:75]
	v_mfma_f32_16x16x32_bf16 v[128:131], v[236:239], v[186:189], v[56:59]
	v_mfma_f32_16x16x32_bf16 v[56:59], v[212:215], v[196:199], v[84:87]
	v_mfma_f32_16x16x32_bf16 v[116:119], v[216:219], v[200:203], v[56:59]
	v_mfma_f32_16x16x32_bf16 v[56:59], v[220:223], v[196:199], v[112:115]
	v_mfma_f32_16x16x32_bf16 v[112:115], v[236:239], v[200:203], v[56:59]
	v_mfma_f32_16x16x32_bf16 v[56:59], v[212:215], v[204:207], v[100:103]
	v_mfma_f32_16x16x32_bf16 v[100:103], v[216:219], v[208:211], v[56:59]
	v_mfma_f32_16x16x32_bf16 v[56:59], v[220:223], v[204:207], v[96:99]
	v_mfma_f32_16x16x32_bf16 v[96:99], v[236:239], v[208:211], v[56:59]
	s_mov_b32 m0, s47
	v_lshl_add_u64 v[190:191], v[242:243], 0, s[78:79]
	s_barrier
	s_nop 2
	ds_read_b128 v[56:59], v195 offset:49152
	ds_read_b128 v[60:63], v195 offset:50176
	ds_read_b128 v[72:75], v195 offset:51200
	ds_read_b128 v[84:87], v195 offset:52224
	ds_read_b128 v[182:185], v195 offset:53248
	ds_read_b128 v[186:189], v195 offset:54272
	ds_read_b128 v[196:199], v195 offset:55296
	ds_read_b128 v[200:203], v195 offset:56320
	global_load_lds_dwordx4 v[190:191], off
	s_mov_b32 m0, s49
	v_lshl_add_u64 v[190:191], v[244:245], 0, s[78:79]
	global_load_lds_dwordx4 v[190:191], off
	s_barrier
	s_waitcnt lgkmcnt(0)
	v_mfma_f32_16x16x32_bf16 v[92:95], v[48:51], v[56:59], v[92:95]
	v_mfma_f32_16x16x32_bf16 v[88:91], v[76:79], v[56:59], v[88:91]
	v_mfma_f32_16x16x32_bf16 v[68:71], v[48:51], v[72:75], v[68:71]
	v_mfma_f32_16x16x32_bf16 v[64:67], v[76:79], v[72:75], v[64:67]
	v_mfma_f32_16x16x32_bf16 v[28:31], v[48:51], v[182:185], v[28:31]
	v_mfma_f32_16x16x32_bf16 v[24:27], v[76:79], v[182:185], v[24:27]
	v_mfma_f32_16x16x32_bf16 v[12:15], v[48:51], v[196:199], v[12:15]
	v_mfma_f32_16x16x32_bf16 v[8:11], v[76:79], v[196:199], v[8:11]
	v_mfma_f32_16x16x32_bf16 v[92:95], v[52:55], v[60:63], v[92:95]
	v_mfma_f32_16x16x32_bf16 v[88:91], v[80:83], v[60:63], v[88:91]
	v_mfma_f32_16x16x32_bf16 v[68:71], v[52:55], v[84:87], v[68:71]
	v_mfma_f32_16x16x32_bf16 v[64:67], v[80:83], v[84:87], v[64:67]
	v_mfma_f32_16x16x32_bf16 v[28:31], v[52:55], v[186:189], v[28:31]
	v_mfma_f32_16x16x32_bf16 v[24:27], v[80:83], v[186:189], v[24:27]
	v_mfma_f32_16x16x32_bf16 v[12:15], v[52:55], v[200:203], v[12:15]
	v_mfma_f32_16x16x32_bf16 v[8:11], v[80:83], v[200:203], v[8:11]
	s_barrier
	s_add_u32 s8, s8, 0xb0080
	s_addc_u32 s9, s9, 0
	s_add_i32 s24, s24, s36
	s_mov_b32 m0, s24
	v_lshl_add_u64 v[48:49], s[8:9], 0, v[168:169]
	global_load_lds_dwordx4 v[48:49], off
	s_add_i32 m0, s24, 0x2000
	v_lshl_add_u64 v[48:49], s[8:9], 0, v[164:165]
	global_load_lds_dwordx4 v[48:49], off
	s_waitcnt vmcnt(6)
	s_barrier
	v_mfma_f32_16x16x32_bf16 v[40:43], v[212:215], v[56:59], v[40:43]
	v_mfma_f32_16x16x32_bf16 v[80:83], v[216:219], v[60:63], v[40:43]
	v_mfma_f32_16x16x32_bf16 v[40:43], v[220:223], v[56:59], v[44:47]
	v_mfma_f32_16x16x32_bf16 v[36:39], v[212:215], v[72:75], v[36:39]
	v_mfma_f32_16x16x32_bf16 v[32:35], v[220:223], v[72:75], v[32:35]
	v_mfma_f32_16x16x32_bf16 v[20:23], v[212:215], v[182:185], v[20:23]
	v_mfma_f32_16x16x32_bf16 v[16:19], v[220:223], v[182:185], v[16:19]
	v_mfma_f32_16x16x32_bf16 v[4:7], v[212:215], v[196:199], v[4:7]
	v_mfma_f32_16x16x32_bf16 v[0:3], v[220:223], v[196:199], v[0:3]
	v_mfma_f32_16x16x32_bf16 v[76:79], v[236:239], v[60:63], v[40:43]
	v_mfma_f32_16x16x32_bf16 v[36:39], v[216:219], v[84:87], v[36:39]
	v_mfma_f32_16x16x32_bf16 v[32:35], v[236:239], v[84:87], v[32:35]
	v_mfma_f32_16x16x32_bf16 v[20:23], v[216:219], v[186:189], v[20:23]
	v_mfma_f32_16x16x32_bf16 v[16:19], v[236:239], v[186:189], v[16:19]
	v_mfma_f32_16x16x32_bf16 v[4:7], v[216:219], v[200:203], v[4:7]
	v_mfma_f32_16x16x32_bf16 v[0:3], v[236:239], v[200:203], v[0:3]
	s_add_i32 s58, s58, 2
	s_add_u32 s56, s56, 0x100
	s_addc_u32 s57, s57, 0
	s_cmp_gt_u32 s58, 41
	s_mov_b64 s[24:25], s[2:3]
	s_barrier
	s_cbranch_scc0 .LBB0_1049
	s_lshl_b32 s2, s55, 8
	v_mov_b32_e32 v186, v193
	v_mov_b32_e32 v196, v192
	s_or_b32 s2, s2, s46
	v_mov_b32_e32 v52, 0
	v_lshl_add_u32 v182, v196, 3, s2
	s_add_i32 s2, s54, -16
	s_lshr_b32 s2, s2, 3
	s_add_i32 s2, s2, 1
	s_cmp_gt_i32 s54, 15
	s_cselect_b32 s8, s2, 0
	s_mul_i32 s96, s8, 0x1800
	s_lshl_b64 s[2:3], s[96:97], 2
	s_add_u32 s2, s41, s2
	v_ashrrev_i32_e32 v183, 31, v182
	s_addc_u32 s3, s42, s3
	v_lshlrev_b64 v[40:41], 2, v[182:183]
	v_lshl_add_u64 v[42:43], s[2:3], 0, v[40:41]
	global_load_dwordx4 v[72:75], v[42:43], off
	s_lshl_b32 s96, s8, 10
	s_lshl_b64 s[2:3], s[96:97], 2
	s_add_u32 s2, s43, s2
	s_addc_u32 s3, s44, s3
	v_lshl_add_u64 v[184:185], s[2:3], 0, v[40:41]
	s_and_b64 vcc, exec, s[4:5]
	v_mov_b32_e32 v60, 0
	v_mov_b32_e32 v61, v52
	v_mov_b32_e32 v62, 0
	v_mov_b32_e32 v63, 0
	s_cbranch_vccnz .LBB0_1052
	global_load_dwordx4 v[60:63], v[184:185], off
